# v36 + removed the 32 back-to-back s_setprio 0 / s_setprio 1 pairs between the two 16-MFMA groups of the GEMM K-loop phases
# speedup vs baseline: 1.0062x; 1.0004x over previous
; #define PG8_STAGE(bufoff, gbase, voff) do { _Pragma("unroll") for (int _i = 0; _i < 2; ++_i) \
;         __builtin_amdgcn_global_load_lds((const unsigned*)((const char*)(gbase) + (voff)[_i]), (LAS unsigned*)(lds + (bufoff) + ldsw + _i * 8192), 16, 0, 0); } while (0)
; #define PG8_LDA(dst, b, h) do { _Pragma("unroll") for (int m = 0; m < 4; ++m) _Pragma("unroll") for (int k = 0; k < 2; ++k) dst[m][k] = *(const LAS bf16x8*)(lds + PG8_SA(b, h) + aoff + m * 2048 + k * 1024); } while (0)
; #define PG8_LDB(dst, b, h) do { _Pragma("unroll") for (int n = 0; n < 2; ++n) _Pragma("unroll") for (int k = 0; k < 2; ++k) dst[n][k] = *(const LAS bf16x8*)(lds + PG8_SB(b, h) + boff + n * 2048 + k * 1024); } while (0)
; #define PG8_MMA(ai, bj, At, Bt) do { __builtin_amdgcn_s_setprio(1); _Pragma("unroll") for (int m = 0; m < 4; ++m) _Pragma("unroll") for (int n = 0; n < 2; ++n) _Pragma("unroll") for (int k = 0; k < 2; ++k) \
;         acc[ai][bj][m][n] = __builtin_amdgcn_mfma_f32_16x16x32_bf16(Bt[n][k], At[m][k], acc[ai][bj][m][n], 0, 0, 0); __builtin_amdgcn_s_setprio(0); } while (0)
; #define PG8_WAIT_V(n) asm volatile("s_waitcnt vmcnt(" #n ")" ::: "memory")
; #define PG8_WAIT_L(n) asm volatile("s_waitcnt lgkmcnt(" #n ")" ::: "memory")
; #define PG8_BAR __builtin_amdgcn_s_barrier()
; #define PG8_SCHED __builtin_amdgcn_sched_barrier(0)
; template <int MODE> DI void gemm_phase(LAS unsigned char* lds, const Gemm g, const StaticOrder& S, const Epi& E) {
;     ...
;         for (int t = 0; t < nt; t += 2) {
;             const bool last = (t == nt - 2);
;             const char* a1 = cA + (size_t)(t + 1) * kstep;
;             const char* a2 = last ? nA : cA + (size_t)(t + 2) * kstep; const char* b2 = last ? nB : cB + (size_t)(t + 2) * kstep;
;             const char* a3 = a2 + kstep; const char* b3 = b2 + kstep;
;             PG8_LDB(B0, 0, 0); PG8_LDB(B1, 0, 1); PG8_SCHED; PG8_LDA(At, 0, 0); PG8_STAGE(PG8_SA(1, 1), a1 + hstepA, voffA);
;             PG8_WAIT_V(8); PG8_WAIT_L(0); PG8_BAR; PG8_MMA(0, 0, At, B0); PG8_MMA(0, 1, At, B1); PG8_BAR; PG8_SCHED;
;             PG8_LDA(At, 0, 1); PG8_STAGE(PG8_SB(0, 0), b2, voffB); PG8_STAGE(PG8_SB(0, 1), b2 + hstepB, voffB); PG8_STAGE(PG8_SA(0, 0), a2, voffA);
;             PG8_WAIT_V(8); PG8_WAIT_L(0); PG8_BAR; PG8_MMA(1, 0, At, B0); PG8_MMA(1, 1, At, B1); PG8_BAR; PG8_SCHED;
.LBB0_206:
	ds_read_b128 v[128:131], v188
	ds_read_b128 v[132:135], v188 offset:1024
	ds_read_b128 v[136:139], v188 offset:2048
	ds_read_b128 v[140:143], v188 offset:3072
	ds_read_b128 v[144:147], v190
	ds_read_b128 v[148:151], v190 offset:1024
	ds_read_b128 v[152:155], v190 offset:2048
	ds_read_b128 v[156:159], v190 offset:3072
	s_add_u32 s24, s22, 0xfffc0080
	s_addc_u32 s25, s23, -1
	s_cmp_eq_u32 s48, 12
	s_cselect_b32 s27, s3, s25
	s_cselect_b32 s26, s5, s24
	s_cselect_b32 s25, s15, s47
	s_cselect_b32 s24, s21, s33
	v_lshl_add_u64 v[182:183], s[22:23], 0, v[170:171]
	s_add_i32 m0, s29, 0xc000
	ds_read_b128 v[178:181], v191
	ds_read_b128 v[202:205], v191 offset:1024
	ds_read_b128 v[206:209], v191 offset:2048
	ds_read_b128 v[210:213], v191 offset:3072
	ds_read_b128 v[214:217], v191 offset:4096
	ds_read_b128 v[218:221], v191 offset:5120
	ds_read_b128 v[222:225], v191 offset:6144
	ds_read_b128 v[226:229], v191 offset:7168
	global_load_lds_dwordx4 v[182:183], off
	v_lshl_add_u64 v[182:183], s[22:23], 0, v[172:173]
	s_add_i32 m0, s29, 0xe000
	s_nop 0
	global_load_lds_dwordx4 v[182:183], off
	s_waitcnt vmcnt(8)
	s_waitcnt lgkmcnt(0)
	s_barrier
	s_setprio 1
	s_waitcnt lgkmcnt(0)
	v_mfma_f32_16x16x32_bf16 v[124:127], v[128:131], v[178:181], v[124:127]
	v_mfma_f32_16x16x32_bf16 v[120:123], v[136:139], v[178:181], v[120:123]
	v_mfma_f32_16x16x32_bf16 v[108:111], v[128:131], v[206:209], v[108:111]
	v_mfma_f32_16x16x32_bf16 v[104:107], v[136:139], v[206:209], v[104:107]
	v_mfma_f32_16x16x32_bf16 v[92:95], v[128:131], v[214:217], v[92:95]
	v_mfma_f32_16x16x32_bf16 v[88:91], v[136:139], v[214:217], v[88:91]
	v_mfma_f32_16x16x32_bf16 v[76:79], v[128:131], v[222:225], v[76:79]
	v_mfma_f32_16x16x32_bf16 v[72:75], v[136:139], v[222:225], v[72:75]
	v_mfma_f32_16x16x32_bf16 v[124:127], v[132:135], v[202:205], v[124:127]
	v_mfma_f32_16x16x32_bf16 v[120:123], v[140:143], v[202:205], v[120:123]
	v_mfma_f32_16x16x32_bf16 v[108:111], v[132:135], v[210:213], v[108:111]
	v_mfma_f32_16x16x32_bf16 v[104:107], v[140:143], v[210:213], v[104:107]
	v_mfma_f32_16x16x32_bf16 v[92:95], v[132:135], v[218:221], v[92:95]
	v_mfma_f32_16x16x32_bf16 v[88:91], v[140:143], v[218:221], v[88:91]
	v_mfma_f32_16x16x32_bf16 v[76:79], v[132:135], v[226:229], v[76:79]
	v_mfma_f32_16x16x32_bf16 v[72:75], v[140:143], v[226:229], v[72:75]
	v_mfma_f32_16x16x32_bf16 v[116:119], v[144:147], v[178:181], v[116:119]
	v_mfma_f32_16x16x32_bf16 v[112:115], v[152:155], v[178:181], v[112:115]
	v_mfma_f32_16x16x32_bf16 v[100:103], v[144:147], v[206:209], v[100:103]
	v_mfma_f32_16x16x32_bf16 v[96:99], v[152:155], v[206:209], v[96:99]
	v_mfma_f32_16x16x32_bf16 v[84:87], v[144:147], v[214:217], v[84:87]
	v_mfma_f32_16x16x32_bf16 v[80:83], v[152:155], v[214:217], v[80:83]
	v_mfma_f32_16x16x32_bf16 v[68:71], v[144:147], v[222:225], v[68:71]
	v_mfma_f32_16x16x32_bf16 v[64:67], v[152:155], v[222:225], v[64:67]
	v_mfma_f32_16x16x32_bf16 v[116:119], v[148:151], v[202:205], v[116:119]
	v_mfma_f32_16x16x32_bf16 v[112:115], v[156:159], v[202:205], v[112:115]
	v_mfma_f32_16x16x32_bf16 v[100:103], v[148:151], v[210:213], v[100:103]
	v_mfma_f32_16x16x32_bf16 v[96:99], v[156:159], v[210:213], v[96:99]
	v_mfma_f32_16x16x32_bf16 v[84:87], v[148:151], v[218:221], v[84:87]
	v_mfma_f32_16x16x32_bf16 v[80:83], v[156:159], v[218:221], v[80:83]
	v_mfma_f32_16x16x32_bf16 v[68:71], v[148:151], v[226:229], v[68:71]
	v_mfma_f32_16x16x32_bf16 v[64:67], v[156:159], v[226:229], v[64:67]
	s_setprio 0
	s_barrier
	s_add_i32 s49, s41, s28
	v_lshl_add_u64 v[182:183], s[24:25], 0, v[162:163]
	s_mov_b32 m0, s49
	ds_read_b128 v[178:181], v191 offset:16384
	ds_read_b128 v[202:205], v191 offset:17408
	ds_read_b128 v[206:209], v191 offset:18432
	ds_read_b128 v[210:213], v191 offset:19456
	ds_read_b128 v[214:217], v191 offset:20480
	ds_read_b128 v[218:221], v191 offset:21504
	ds_read_b128 v[222:225], v191 offset:22528
	ds_read_b128 v[226:229], v191 offset:23552
	global_load_lds_dwordx4 v[182:183], off
	s_add_i32 m0, s49, 0x2000
	s_add_u32 s50, s24, 0x10000
	v_lshl_add_u64 v[230:231], s[24:25], 0, v[166:167]
	s_addc_u32 s51, s25, 0
	s_add_i32 s49, s42, s28
	global_load_lds_dwordx4 v[230:231], off
	v_lshl_add_u64 v[232:233], s[50:51], 0, v[162:163]
	s_mov_b32 m0, s49
	v_lshl_add_u64 v[234:235], s[26:27], 0, v[164:165]
	global_load_lds_dwordx4 v[232:233], off
	v_lshl_add_u64 v[232:233], s[50:51], 0, v[166:167]
	s_add_i32 m0, s49, 0x2000
	s_nop 0
	global_load_lds_dwordx4 v[232:233], off
	v_lshl_add_u64 v[232:233], s[26:27], 0, v[160:161]
	s_mov_b32 m0, s29
	s_nop 0
	global_load_lds_dwordx4 v[232:233], off
	s_mov_b32 m0, s30
	s_nop 0
	global_load_lds_dwordx4 v[234:235], off
	s_waitcnt vmcnt(8)
	s_waitcnt lgkmcnt(0)
	s_barrier
; #define PG8_STAGE(bufoff, gbase, voff) do { _Pragma("unroll") for (int _i = 0; _i < 2; ++_i) \
;         __builtin_amdgcn_global_load_lds((const unsigned*)((const char*)(gbase) + (voff)[_i]), (LAS unsigned*)(lds + (bufoff) + ldsw + _i * 8192), 16, 0, 0); } while (0)
; #define PG8_LDA(dst, b, h) do { _Pragma("unroll") for (int m = 0; m < 4; ++m) _Pragma("unroll") for (int k = 0; k < 2; ++k) dst[m][k] = *(const LAS bf16x8*)(lds + PG8_SA(b, h) + aoff + m * 2048 + k * 1024); } while (0)
; #define PG8_LDB(dst, b, h) do { _Pragma("unroll") for (int n = 0; n < 2; ++n) _Pragma("unroll") for (int k = 0; k < 2; ++k) dst[n][k] = *(const LAS bf16x8*)(lds + PG8_SB(b, h) + boff + n * 2048 + k * 1024); } while (0)
; #define PG8_MMA(ai, bj, At, Bt) do { __builtin_amdgcn_s_setprio(1); _Pragma("unroll") for (int m = 0; m < 4; ++m) _Pragma("unroll") for (int n = 0; n < 2; ++n) _Pragma("unroll") for (int k = 0; k < 2; ++k) \
;         acc[ai][bj][m][n] = __builtin_amdgcn_mfma_f32_16x16x32_bf16(Bt[n][k], At[m][k], acc[ai][bj][m][n], 0, 0, 0); __builtin_amdgcn_s_setprio(0); } while (0)
; #define PG8_WAIT_V(n) asm volatile("s_waitcnt vmcnt(" #n ")" ::: "memory")
; #define PG8_WAIT_L(n) asm volatile("s_waitcnt lgkmcnt(" #n ")" ::: "memory")
; #define PG8_BAR __builtin_amdgcn_s_barrier()
; #define PG8_SCHED __builtin_amdgcn_sched_barrier(0)
; template <int MODE> DI void gemm_phase(LAS unsigned char* lds, const Gemm g, const StaticOrder& S, const Epi& E) {
;     ...
;             PG8_WAIT_V(8); PG8_WAIT_L(0); PG8_BAR; PG8_MMA(1, 0, At, B0); PG8_MMA(1, 1, At, B1); PG8_BAR; PG8_SCHED;
;             PG8_LDB(B0, 1, 0); PG8_LDB(B1, 1, 1); PG8_SCHED; PG8_LDA(At, 1, 0); PG8_STAGE(PG8_SA(0, 1), a2 + hstepA, voffA);
;             PG8_WAIT_V(8); PG8_WAIT_L(0); PG8_BAR; PG8_MMA(0, 0, At, B0); PG8_MMA(0, 1, At, B1); PG8_BAR; PG8_SCHED;
;             PG8_LDA(At, 1, 1); PG8_STAGE(PG8_SB(1, 0), b3, voffB); PG8_STAGE(PG8_SB(1, 1), b3 + hstepB, voffB); PG8_STAGE(PG8_SA(1, 0), a3, voffA);
;             PG8_WAIT_V(8); PG8_WAIT_L(0); PG8_BAR; PG8_MMA(1, 0, At, B0); PG8_MMA(1, 1, At, B1); PG8_BAR; PG8_SCHED;
	s_setprio 1
	s_waitcnt lgkmcnt(0)
	v_mfma_f32_16x16x32_bf16 v[60:63], v[128:131], v[178:181], v[60:63]
	v_mfma_f32_16x16x32_bf16 v[56:59], v[136:139], v[178:181], v[56:59]
	v_mfma_f32_16x16x32_bf16 v[44:47], v[128:131], v[206:209], v[44:47]
	v_mfma_f32_16x16x32_bf16 v[40:43], v[136:139], v[206:209], v[40:43]
	v_mfma_f32_16x16x32_bf16 v[28:31], v[128:131], v[214:217], v[28:31]
	v_mfma_f32_16x16x32_bf16 v[24:27], v[136:139], v[214:217], v[24:27]
	v_mfma_f32_16x16x32_bf16 v[12:15], v[128:131], v[222:225], v[12:15]
	v_mfma_f32_16x16x32_bf16 v[8:11], v[136:139], v[222:225], v[8:11]
	v_mfma_f32_16x16x32_bf16 v[60:63], v[132:135], v[202:205], v[60:63]
	v_mfma_f32_16x16x32_bf16 v[56:59], v[140:143], v[202:205], v[56:59]
	v_mfma_f32_16x16x32_bf16 v[44:47], v[132:135], v[210:213], v[44:47]
	v_mfma_f32_16x16x32_bf16 v[40:43], v[140:143], v[210:213], v[40:43]
	v_mfma_f32_16x16x32_bf16 v[28:31], v[132:135], v[218:221], v[28:31]
	v_mfma_f32_16x16x32_bf16 v[24:27], v[140:143], v[218:221], v[24:27]
	v_mfma_f32_16x16x32_bf16 v[12:15], v[132:135], v[226:229], v[12:15]
	v_mfma_f32_16x16x32_bf16 v[8:11], v[140:143], v[226:229], v[8:11]
	v_mfma_f32_16x16x32_bf16 v[52:55], v[144:147], v[178:181], v[52:55]
	v_mfma_f32_16x16x32_bf16 v[48:51], v[152:155], v[178:181], v[48:51]
	v_mfma_f32_16x16x32_bf16 v[36:39], v[144:147], v[206:209], v[36:39]
	v_mfma_f32_16x16x32_bf16 v[32:35], v[152:155], v[206:209], v[32:35]
	v_mfma_f32_16x16x32_bf16 v[20:23], v[144:147], v[214:217], v[20:23]
	v_mfma_f32_16x16x32_bf16 v[16:19], v[152:155], v[214:217], v[16:19]
	v_mfma_f32_16x16x32_bf16 v[4:7], v[144:147], v[222:225], v[4:7]
	v_mfma_f32_16x16x32_bf16 v[0:3], v[152:155], v[222:225], v[0:3]
	v_mfma_f32_16x16x32_bf16 v[52:55], v[148:151], v[202:205], v[52:55]
	v_mfma_f32_16x16x32_bf16 v[48:51], v[156:159], v[202:205], v[48:51]
	v_mfma_f32_16x16x32_bf16 v[36:39], v[148:151], v[210:213], v[36:39]
	v_mfma_f32_16x16x32_bf16 v[32:35], v[156:159], v[210:213], v[32:35]
	v_mfma_f32_16x16x32_bf16 v[20:23], v[148:151], v[218:221], v[20:23]
	v_mfma_f32_16x16x32_bf16 v[16:19], v[156:159], v[218:221], v[16:19]
	v_mfma_f32_16x16x32_bf16 v[4:7], v[148:151], v[226:229], v[4:7]
	v_mfma_f32_16x16x32_bf16 v[0:3], v[156:159], v[226:229], v[0:3]
	s_setprio 0
	s_barrier
	s_add_i32 s49, 0, 0x18000
	s_add_i32 s50, 0, 0x1c000
	v_add_u32_e32 v140, s49, v186
	v_add_u32_e32 v156, s50, v186
	ds_read_b128 v[128:131], v140
	ds_read_b128 v[132:135], v140 offset:1024
	ds_read_b128 v[136:139], v140 offset:2048
	ds_read_b128 v[140:143], v140 offset:3072
	ds_read_b128 v[144:147], v156
	ds_read_b128 v[148:151], v156 offset:1024
	ds_read_b128 v[152:155], v156 offset:2048
	ds_read_b128 v[156:159], v156 offset:3072
	s_add_u32 s26, s26, 0x40000
	s_addc_u32 s27, s27, 0
	s_mov_b32 m0, s31
	v_lshl_add_u64 v[236:237], s[26:27], 0, v[160:161]
	ds_read_b128 v[178:181], v191 offset:32768
	ds_read_b128 v[202:205], v191 offset:33792
	ds_read_b128 v[206:209], v191 offset:34816
	ds_read_b128 v[210:213], v191 offset:35840
	ds_read_b128 v[214:217], v191 offset:36864
	ds_read_b128 v[218:221], v191 offset:37888
	ds_read_b128 v[222:225], v191 offset:38912
	ds_read_b128 v[226:229], v191 offset:39936
	global_load_lds_dwordx4 v[236:237], off
	v_lshl_add_u64 v[236:237], s[26:27], 0, v[164:165]
	s_mov_b32 m0, s34
	s_nop 0
	global_load_lds_dwordx4 v[236:237], off
	s_waitcnt vmcnt(8)
	s_waitcnt lgkmcnt(0)
	s_barrier
	s_setprio 1
	s_waitcnt lgkmcnt(0)
	v_mfma_f32_16x16x32_bf16 v[124:127], v[128:131], v[178:181], v[124:127]
	v_mfma_f32_16x16x32_bf16 v[120:123], v[136:139], v[178:181], v[120:123]
	v_mfma_f32_16x16x32_bf16 v[108:111], v[128:131], v[206:209], v[108:111]
	v_mfma_f32_16x16x32_bf16 v[104:107], v[136:139], v[206:209], v[104:107]
	v_mfma_f32_16x16x32_bf16 v[92:95], v[128:131], v[214:217], v[92:95]
	v_mfma_f32_16x16x32_bf16 v[88:91], v[136:139], v[214:217], v[88:91]
	v_mfma_f32_16x16x32_bf16 v[76:79], v[128:131], v[222:225], v[76:79]
	v_mfma_f32_16x16x32_bf16 v[72:75], v[136:139], v[222:225], v[72:75]
	v_mfma_f32_16x16x32_bf16 v[124:127], v[132:135], v[202:205], v[124:127]
	v_mfma_f32_16x16x32_bf16 v[120:123], v[140:143], v[202:205], v[120:123]
	v_mfma_f32_16x16x32_bf16 v[108:111], v[132:135], v[210:213], v[108:111]
	v_mfma_f32_16x16x32_bf16 v[104:107], v[140:143], v[210:213], v[104:107]
	v_mfma_f32_16x16x32_bf16 v[92:95], v[132:135], v[218:221], v[92:95]
	v_mfma_f32_16x16x32_bf16 v[88:91], v[140:143], v[218:221], v[88:91]
	v_mfma_f32_16x16x32_bf16 v[76:79], v[132:135], v[226:229], v[76:79]
	v_mfma_f32_16x16x32_bf16 v[72:75], v[140:143], v[226:229], v[72:75]
	v_mfma_f32_16x16x32_bf16 v[116:119], v[144:147], v[178:181], v[116:119]
	v_mfma_f32_16x16x32_bf16 v[112:115], v[152:155], v[178:181], v[112:115]
	v_mfma_f32_16x16x32_bf16 v[100:103], v[144:147], v[206:209], v[100:103]
	v_mfma_f32_16x16x32_bf16 v[96:99], v[152:155], v[206:209], v[96:99]
	v_mfma_f32_16x16x32_bf16 v[84:87], v[144:147], v[214:217], v[84:87]
	v_mfma_f32_16x16x32_bf16 v[80:83], v[152:155], v[214:217], v[80:83]
	v_mfma_f32_16x16x32_bf16 v[68:71], v[144:147], v[222:225], v[68:71]
	v_mfma_f32_16x16x32_bf16 v[64:67], v[152:155], v[222:225], v[64:67]
	v_mfma_f32_16x16x32_bf16 v[116:119], v[148:151], v[202:205], v[116:119]
	v_mfma_f32_16x16x32_bf16 v[112:115], v[156:159], v[202:205], v[112:115]
	v_mfma_f32_16x16x32_bf16 v[100:103], v[148:151], v[210:213], v[100:103]
	v_mfma_f32_16x16x32_bf16 v[96:99], v[156:159], v[210:213], v[96:99]
	v_mfma_f32_16x16x32_bf16 v[84:87], v[148:151], v[218:221], v[84:87]
	v_mfma_f32_16x16x32_bf16 v[80:83], v[156:159], v[218:221], v[80:83]
	v_mfma_f32_16x16x32_bf16 v[68:71], v[148:151], v[226:229], v[68:71]
	v_mfma_f32_16x16x32_bf16 v[64:67], v[156:159], v[226:229], v[64:67]
	s_setprio 0
	s_barrier
; #define PG8_STAGE(bufoff, gbase, voff) do { _Pragma("unroll") for (int _i = 0; _i < 2; ++_i) \
;         __builtin_amdgcn_global_load_lds((const unsigned*)((const char*)(gbase) + (voff)[_i]), (LAS unsigned*)(lds + (bufoff) + ldsw + _i * 8192), 16, 0, 0); } while (0)
; #define PG8_LDA(dst, b, h) do { _Pragma("unroll") for (int m = 0; m < 4; ++m) _Pragma("unroll") for (int k = 0; k < 2; ++k) dst[m][k] = *(const LAS bf16x8*)(lds + PG8_SA(b, h) + aoff + m * 2048 + k * 1024); } while (0)
; #define PG8_MMA(ai, bj, At, Bt) do { __builtin_amdgcn_s_setprio(1); _Pragma("unroll") for (int m = 0; m < 4; ++m) _Pragma("unroll") for (int n = 0; n < 2; ++n) _Pragma("unroll") for (int k = 0; k < 2; ++k) \
;         acc[ai][bj][m][n] = __builtin_amdgcn_mfma_f32_16x16x32_bf16(Bt[n][k], At[m][k], acc[ai][bj][m][n], 0, 0, 0); __builtin_amdgcn_s_setprio(0); } while (0)
; #define PG8_WAIT_V(n) asm volatile("s_waitcnt vmcnt(" #n ")" ::: "memory")
; #define PG8_WAIT_L(n) asm volatile("s_waitcnt lgkmcnt(" #n ")" ::: "memory")
; #define PG8_BAR __builtin_amdgcn_s_barrier()
; #define PG8_SCHED __builtin_amdgcn_sched_barrier(0)
; template <int MODE> DI void gemm_phase(LAS unsigned char* lds, const Gemm g, const StaticOrder& S, const Epi& E) {
;     ...
;             PG8_LDA(At, 1, 1); PG8_STAGE(PG8_SB(1, 0), b3, voffB); PG8_STAGE(PG8_SB(1, 1), b3 + hstepB, voffB); PG8_STAGE(PG8_SA(1, 0), a3, voffA);
;             PG8_WAIT_V(8); PG8_WAIT_L(0); PG8_BAR; PG8_MMA(1, 0, At, B0); PG8_MMA(1, 1, At, B1); PG8_BAR; PG8_SCHED;
;         }
;         if (wr == 0) PG8_BAR;
	s_add_i32 s26, s49, s28
	v_lshl_add_u64 v[182:183], v[182:183], 0, s[10:11]
	s_mov_b32 m0, s26
	ds_read_b128 v[178:181], v191 offset:49152
	ds_read_b128 v[202:205], v191 offset:50176
	ds_read_b128 v[206:209], v191 offset:51200
	ds_read_b128 v[210:213], v191 offset:52224
	ds_read_b128 v[214:217], v191 offset:53248
	ds_read_b128 v[218:221], v191 offset:54272
	ds_read_b128 v[222:225], v191 offset:55296
	ds_read_b128 v[226:229], v191 offset:56320
	global_load_lds_dwordx4 v[182:183], off
	s_add_i32 m0, s26, 0x2000
	s_add_u32 s24, s24, 0x10080
	v_lshl_add_u64 v[182:183], v[230:231], 0, s[10:11]
	s_addc_u32 s25, s25, 0
	s_add_i32 s26, s50, s28
	global_load_lds_dwordx4 v[182:183], off
	v_lshl_add_u64 v[182:183], s[24:25], 0, v[162:163]
	s_mov_b32 m0, s26
	s_nop 0
	global_load_lds_dwordx4 v[182:183], off
	v_lshl_add_u64 v[182:183], s[24:25], 0, v[166:167]
	s_add_i32 m0, s26, 0x2000
	s_nop 0
	global_load_lds_dwordx4 v[182:183], off
	v_lshl_add_u64 v[182:183], v[232:233], 0, s[10:11]
	s_mov_b32 m0, s38
	s_nop 0
	global_load_lds_dwordx4 v[182:183], off
	v_lshl_add_u64 v[182:183], v[234:235], 0, s[10:11]
	s_mov_b32 m0, s39
	s_nop 0
	global_load_lds_dwordx4 v[182:183], off
	s_waitcnt vmcnt(8)
	s_waitcnt lgkmcnt(0)
	s_barrier
	s_setprio 1
	s_waitcnt lgkmcnt(0)
	v_mfma_f32_16x16x32_bf16 v[60:63], v[128:131], v[178:181], v[60:63]
	v_mfma_f32_16x16x32_bf16 v[56:59], v[136:139], v[178:181], v[56:59]
	v_mfma_f32_16x16x32_bf16 v[44:47], v[128:131], v[206:209], v[44:47]
	v_mfma_f32_16x16x32_bf16 v[40:43], v[136:139], v[206:209], v[40:43]
	v_mfma_f32_16x16x32_bf16 v[28:31], v[128:131], v[214:217], v[28:31]
	v_mfma_f32_16x16x32_bf16 v[24:27], v[136:139], v[214:217], v[24:27]
	v_mfma_f32_16x16x32_bf16 v[12:15], v[128:131], v[222:225], v[12:15]
	v_mfma_f32_16x16x32_bf16 v[8:11], v[136:139], v[222:225], v[8:11]
	v_mfma_f32_16x16x32_bf16 v[60:63], v[132:135], v[202:205], v[60:63]
	v_mfma_f32_16x16x32_bf16 v[56:59], v[140:143], v[202:205], v[56:59]
	v_mfma_f32_16x16x32_bf16 v[44:47], v[132:135], v[210:213], v[44:47]
	v_mfma_f32_16x16x32_bf16 v[40:43], v[140:143], v[210:213], v[40:43]
	v_mfma_f32_16x16x32_bf16 v[28:31], v[132:135], v[218:221], v[28:31]
	v_mfma_f32_16x16x32_bf16 v[24:27], v[140:143], v[218:221], v[24:27]
	v_mfma_f32_16x16x32_bf16 v[12:15], v[132:135], v[226:229], v[12:15]
	v_mfma_f32_16x16x32_bf16 v[8:11], v[140:143], v[226:229], v[8:11]
	v_mfma_f32_16x16x32_bf16 v[52:55], v[144:147], v[178:181], v[52:55]
	v_mfma_f32_16x16x32_bf16 v[48:51], v[152:155], v[178:181], v[48:51]
	v_mfma_f32_16x16x32_bf16 v[36:39], v[144:147], v[206:209], v[36:39]
	v_mfma_f32_16x16x32_bf16 v[32:35], v[152:155], v[206:209], v[32:35]
	v_mfma_f32_16x16x32_bf16 v[20:23], v[144:147], v[214:217], v[20:23]
	v_mfma_f32_16x16x32_bf16 v[16:19], v[152:155], v[214:217], v[16:19]
	v_mfma_f32_16x16x32_bf16 v[4:7], v[144:147], v[222:225], v[4:7]
	v_mfma_f32_16x16x32_bf16 v[0:3], v[152:155], v[222:225], v[0:3]
	v_mfma_f32_16x16x32_bf16 v[52:55], v[148:151], v[202:205], v[52:55]
	v_mfma_f32_16x16x32_bf16 v[48:51], v[156:159], v[202:205], v[48:51]
	v_mfma_f32_16x16x32_bf16 v[36:39], v[148:151], v[210:213], v[36:39]
	v_mfma_f32_16x16x32_bf16 v[32:35], v[156:159], v[210:213], v[32:35]
	v_mfma_f32_16x16x32_bf16 v[20:23], v[148:151], v[218:221], v[20:23]
	v_mfma_f32_16x16x32_bf16 v[16:19], v[156:159], v[218:221], v[16:19]
	v_mfma_f32_16x16x32_bf16 v[4:7], v[148:151], v[226:229], v[4:7]
	v_mfma_f32_16x16x32_bf16 v[0:3], v[156:159], v[226:229], v[0:3]
	s_setprio 0
	s_barrier
	s_add_i32 s48, s48, 2
	s_add_u32 s22, s22, 0x100
	s_addc_u32 s23, s23, 0
	s_add_u32 s33, s33, 0x100
	s_addc_u32 s47, s47, 0
	s_cmp_gt_u32 s48, 13
	s_cbranch_scc0 .LBB0_206
	s_and_b64 vcc, exec, s[12:13]
	s_cbranch_vccz .LBB0_209
	s_barrier

; #define PG8_STAGE(bufoff, gbase, voff) do { _Pragma("unroll") for (int _i = 0; _i < 2; ++_i) \
;         __builtin_amdgcn_global_load_lds((const unsigned*)((const char*)(gbase) + (voff)[_i]), (LAS unsigned*)(lds + (bufoff) + ldsw + _i * 8192), 16, 0, 0); } while (0)
; #define PG8_LDA(dst, b, h) do { _Pragma("unroll") for (int m = 0; m < 4; ++m) _Pragma("unroll") for (int k = 0; k < 2; ++k) dst[m][k] = *(const LAS bf16x8*)(lds + PG8_SA(b, h) + aoff + m * 2048 + k * 1024); } while (0)
; #define PG8_LDB(dst, b, h) do { _Pragma("unroll") for (int n = 0; n < 2; ++n) _Pragma("unroll") for (int k = 0; k < 2; ++k) dst[n][k] = *(const LAS bf16x8*)(lds + PG8_SB(b, h) + boff + n * 2048 + k * 1024); } while (0)
; #define PG8_MMA(ai, bj, At, Bt) do { __builtin_amdgcn_s_setprio(1); _Pragma("unroll") for (int m = 0; m < 4; ++m) _Pragma("unroll") for (int n = 0; n < 2; ++n) _Pragma("unroll") for (int k = 0; k < 2; ++k) \
;         acc[ai][bj][m][n] = __builtin_amdgcn_mfma_f32_16x16x32_bf16(Bt[n][k], At[m][k], acc[ai][bj][m][n], 0, 0, 0); __builtin_amdgcn_s_setprio(0); } while (0)
; #define PG8_WAIT_V(n) asm volatile("s_waitcnt vmcnt(" #n ")" ::: "memory")
; #define PG8_WAIT_L(n) asm volatile("s_waitcnt lgkmcnt(" #n ")" ::: "memory")
; #define PG8_BAR __builtin_amdgcn_s_barrier()
; #define PG8_SCHED __builtin_amdgcn_sched_barrier(0)
; template <int MODE> DI void gemm_phase(LAS unsigned char* lds, const Gemm g, const StaticOrder& S, const Epi& E) {
;     ...
;         for (int t = 0; t < nt; t += 2) {
;             const bool last = (t == nt - 2);
;             const char* a1 = cA + (size_t)(t + 1) * kstep;
;             const char* a2 = last ? nA : cA + (size_t)(t + 2) * kstep; const char* b2 = last ? nB : cB + (size_t)(t + 2) * kstep;
;             const char* a3 = a2 + kstep; const char* b3 = b2 + kstep;
;             PG8_LDB(B0, 0, 0); PG8_LDB(B1, 0, 1); PG8_SCHED; PG8_LDA(At, 0, 0); PG8_STAGE(PG8_SA(1, 1), a1 + hstepA, voffA);
;             PG8_WAIT_V(8); PG8_WAIT_L(0); PG8_BAR; PG8_MMA(0, 0, At, B0); PG8_MMA(0, 1, At, B1); PG8_BAR; PG8_SCHED;
;             PG8_LDA(At, 0, 1); PG8_STAGE(PG8_SB(0, 0), b2, voffB); PG8_STAGE(PG8_SB(0, 1), b2 + hstepB, voffB); PG8_STAGE(PG8_SA(0, 0), a2, voffA);
;             PG8_WAIT_V(8); PG8_WAIT_L(0); PG8_BAR; PG8_MMA(1, 0, At, B0); PG8_MMA(1, 1, At, B1); PG8_BAR; PG8_SCHED;
.LBB0_499:
	ds_read_b128 v[128:131], v199
	ds_read_b128 v[132:135], v199 offset:1024
	ds_read_b128 v[154:157], v199 offset:2048
	ds_read_b128 v[158:161], v199 offset:3072
	ds_read_b128 v[162:165], v200
	ds_read_b128 v[166:169], v200 offset:1024
	ds_read_b128 v[170:173], v200 offset:2048
	ds_read_b128 v[174:177], v200 offset:3072
	s_add_u32 s36, s34, 0xfffe0080
	s_addc_u32 s37, s35, -1
	s_cmp_eq_u32 s60, 4
	s_cselect_b32 s39, s3, s37
	s_cselect_b32 s38, s9, s36
	s_cselect_b32 s37, s25, s59
	s_cselect_b32 s36, s27, s33
	v_lshl_add_u64 v[186:187], s[34:35], 0, v[146:147]
	s_add_i32 m0, s42, 0xc000
	ds_read_b128 v[178:181], v201
	ds_read_b128 v[182:185], v201 offset:1024
	ds_read_b128 v[190:193], v201 offset:2048
	ds_read_b128 v[204:207], v201 offset:3072
	ds_read_b128 v[208:211], v201 offset:4096
	ds_read_b128 v[212:215], v201 offset:5120
	ds_read_b128 v[216:219], v201 offset:6144
	ds_read_b128 v[220:223], v201 offset:7168
	global_load_lds_dwordx4 v[186:187], off
	v_lshl_add_u64 v[186:187], s[34:35], 0, v[148:149]
	s_add_i32 m0, s42, 0xe000
	s_nop 0
	global_load_lds_dwordx4 v[186:187], off
	s_waitcnt vmcnt(8)
	s_waitcnt lgkmcnt(0)
	s_barrier
	s_setprio 1
	s_waitcnt lgkmcnt(0)
	v_mfma_f32_16x16x32_bf16 v[48:51], v[128:131], v[178:181], v[48:51]
	v_mfma_f32_16x16x32_bf16 v[28:31], v[154:157], v[178:181], v[28:31]
	v_mfma_f32_16x16x32_bf16 v[68:71], v[128:131], v[190:193], v[68:71]
	v_mfma_f32_16x16x32_bf16 v[52:55], v[154:157], v[190:193], v[52:55]
	v_mfma_f32_16x16x32_bf16 v[84:87], v[128:131], v[208:211], v[84:87]
	v_mfma_f32_16x16x32_bf16 v[76:79], v[154:157], v[208:211], v[76:79]
	v_mfma_f32_16x16x32_bf16 v[96:99], v[128:131], v[216:219], v[96:99]
	v_mfma_f32_16x16x32_bf16 v[88:91], v[154:157], v[216:219], v[88:91]
	v_mfma_f32_16x16x32_bf16 v[48:51], v[132:135], v[182:185], v[48:51]
	v_mfma_f32_16x16x32_bf16 v[28:31], v[158:161], v[182:185], v[28:31]
	v_mfma_f32_16x16x32_bf16 v[68:71], v[132:135], v[204:207], v[68:71]
	v_mfma_f32_16x16x32_bf16 v[52:55], v[158:161], v[204:207], v[52:55]
	v_mfma_f32_16x16x32_bf16 v[84:87], v[132:135], v[212:215], v[84:87]
	v_mfma_f32_16x16x32_bf16 v[76:79], v[158:161], v[212:215], v[76:79]
	v_mfma_f32_16x16x32_bf16 v[96:99], v[132:135], v[220:223], v[96:99]
	v_mfma_f32_16x16x32_bf16 v[88:91], v[158:161], v[220:223], v[88:91]
	v_mfma_f32_16x16x32_bf16 v[32:35], v[162:165], v[178:181], v[32:35]
	v_mfma_f32_16x16x32_bf16 v[16:19], v[170:173], v[178:181], v[16:19]
	v_mfma_f32_16x16x32_bf16 v[60:63], v[162:165], v[190:193], v[60:63]
	v_mfma_f32_16x16x32_bf16 v[40:43], v[170:173], v[190:193], v[40:43]
	v_mfma_f32_16x16x32_bf16 v[24:27], v[162:165], v[208:211], v[24:27]
	v_mfma_f32_16x16x32_bf16 v[4:7], v[170:173], v[208:211], v[4:7]
	v_mfma_f32_16x16x32_bf16 v[64:67], v[162:165], v[216:219], v[64:67]
	v_mfma_f32_16x16x32_bf16 v[44:47], v[170:173], v[216:219], v[44:47]
	v_mfma_f32_16x16x32_bf16 v[32:35], v[166:169], v[182:185], v[32:35]
	v_mfma_f32_16x16x32_bf16 v[16:19], v[174:177], v[182:185], v[16:19]
	v_mfma_f32_16x16x32_bf16 v[60:63], v[166:169], v[204:207], v[60:63]
	v_mfma_f32_16x16x32_bf16 v[40:43], v[174:177], v[204:207], v[40:43]
	v_mfma_f32_16x16x32_bf16 v[24:27], v[166:169], v[212:215], v[24:27]
	v_mfma_f32_16x16x32_bf16 v[4:7], v[174:177], v[212:215], v[4:7]
	v_mfma_f32_16x16x32_bf16 v[64:67], v[166:169], v[220:223], v[64:67]
	v_mfma_f32_16x16x32_bf16 v[44:47], v[174:177], v[220:223], v[44:47]
	s_setprio 0
	s_barrier
	s_add_i32 s61, s55, s41
	v_lshl_add_u64 v[186:187], s[36:37], 0, v[138:139]
	s_mov_b32 m0, s61
	ds_read_b128 v[178:181], v201 offset:16384
	ds_read_b128 v[182:185], v201 offset:17408
	ds_read_b128 v[190:193], v201 offset:18432
	ds_read_b128 v[204:207], v201 offset:19456
	ds_read_b128 v[208:211], v201 offset:20480
	ds_read_b128 v[212:215], v201 offset:21504
	ds_read_b128 v[216:219], v201 offset:22528
	ds_read_b128 v[220:223], v201 offset:23552
	global_load_lds_dwordx4 v[186:187], off
	s_add_i32 m0, s61, 0x2000
	s_add_u32 s62, s36, 0x8000
	v_lshl_add_u64 v[188:189], s[36:37], 0, v[142:143]
	s_addc_u32 s63, s37, 0
	s_add_i32 s61, s56, s41
	global_load_lds_dwordx4 v[188:189], off
	v_lshl_add_u64 v[194:195], s[62:63], 0, v[138:139]
	s_mov_b32 m0, s61
	v_lshl_add_u64 v[224:225], s[38:39], 0, v[140:141]
	global_load_lds_dwordx4 v[194:195], off
	v_lshl_add_u64 v[194:195], s[62:63], 0, v[142:143]
	s_add_i32 m0, s61, 0x2000
	s_nop 0
	global_load_lds_dwordx4 v[194:195], off
	v_lshl_add_u64 v[194:195], s[38:39], 0, v[136:137]
	s_mov_b32 m0, s42
	s_nop 0
	global_load_lds_dwordx4 v[194:195], off
	s_mov_b32 m0, s43
	s_nop 0
	global_load_lds_dwordx4 v[224:225], off
	s_waitcnt vmcnt(8)
	s_waitcnt lgkmcnt(0)
	s_barrier
; #define PG8_STAGE(bufoff, gbase, voff) do { _Pragma("unroll") for (int _i = 0; _i < 2; ++_i) \
;         __builtin_amdgcn_global_load_lds((const unsigned*)((const char*)(gbase) + (voff)[_i]), (LAS unsigned*)(lds + (bufoff) + ldsw + _i * 8192), 16, 0, 0); } while (0)
; #define PG8_LDA(dst, b, h) do { _Pragma("unroll") for (int m = 0; m < 4; ++m) _Pragma("unroll") for (int k = 0; k < 2; ++k) dst[m][k] = *(const LAS bf16x8*)(lds + PG8_SA(b, h) + aoff + m * 2048 + k * 1024); } while (0)
; #define PG8_LDB(dst, b, h) do { _Pragma("unroll") for (int n = 0; n < 2; ++n) _Pragma("unroll") for (int k = 0; k < 2; ++k) dst[n][k] = *(const LAS bf16x8*)(lds + PG8_SB(b, h) + boff + n * 2048 + k * 1024); } while (0)
; #define PG8_MMA(ai, bj, At, Bt) do { __builtin_amdgcn_s_setprio(1); _Pragma("unroll") for (int m = 0; m < 4; ++m) _Pragma("unroll") for (int n = 0; n < 2; ++n) _Pragma("unroll") for (int k = 0; k < 2; ++k) \
;         acc[ai][bj][m][n] = __builtin_amdgcn_mfma_f32_16x16x32_bf16(Bt[n][k], At[m][k], acc[ai][bj][m][n], 0, 0, 0); __builtin_amdgcn_s_setprio(0); } while (0)
; #define PG8_WAIT_V(n) asm volatile("s_waitcnt vmcnt(" #n ")" ::: "memory")
; #define PG8_WAIT_L(n) asm volatile("s_waitcnt lgkmcnt(" #n ")" ::: "memory")
; #define PG8_BAR __builtin_amdgcn_s_barrier()
; #define PG8_SCHED __builtin_amdgcn_sched_barrier(0)
; template <int MODE> DI void gemm_phase(LAS unsigned char* lds, const Gemm g, const StaticOrder& S, const Epi& E) {
;     ...
;             PG8_WAIT_V(8); PG8_WAIT_L(0); PG8_BAR; PG8_MMA(1, 0, At, B0); PG8_MMA(1, 1, At, B1); PG8_BAR; PG8_SCHED;
;             PG8_LDB(B0, 1, 0); PG8_LDB(B1, 1, 1); PG8_SCHED; PG8_LDA(At, 1, 0); PG8_STAGE(PG8_SA(0, 1), a2 + hstepA, voffA);
;             PG8_WAIT_V(8); PG8_WAIT_L(0); PG8_BAR; PG8_MMA(0, 0, At, B0); PG8_MMA(0, 1, At, B1); PG8_BAR; PG8_SCHED;
;             PG8_LDA(At, 1, 1); PG8_STAGE(PG8_SB(1, 0), b3, voffB); PG8_STAGE(PG8_SB(1, 1), b3 + hstepB, voffB); PG8_STAGE(PG8_SA(1, 0), a3, voffA);
;             PG8_WAIT_V(8); PG8_WAIT_L(0); PG8_BAR; PG8_MMA(1, 0, At, B0); PG8_MMA(1, 1, At, B1); PG8_BAR; PG8_SCHED;
	s_setprio 1
	s_waitcnt lgkmcnt(0)
	v_mfma_f32_16x16x32_bf16 v[112:115], v[128:131], v[178:181], v[112:115]
	v_mfma_f32_16x16x32_bf16 v[104:107], v[154:157], v[178:181], v[104:107]
	v_mfma_f32_16x16x32_bf16 v[20:23], v[128:131], v[190:193], v[20:23]
	v_mfma_f32_16x16x32_bf16 v[0:3], v[154:157], v[190:193], v[0:3]
	v_mfma_f32_16x16x32_bf16 v[56:59], v[128:131], v[208:211], v[56:59]
	v_mfma_f32_16x16x32_bf16 v[36:39], v[154:157], v[208:211], v[36:39]
	v_mfma_f32_16x16x32_bf16 v[8:11], v[128:131], v[216:219], v[8:11]
	v_mfma_f32_16x16x32_bf16 v[12:15], v[154:157], v[216:219], v[12:15]
	v_mfma_f32_16x16x32_bf16 v[112:115], v[132:135], v[182:185], v[112:115]
	v_mfma_f32_16x16x32_bf16 v[104:107], v[158:161], v[182:185], v[104:107]
	v_mfma_f32_16x16x32_bf16 v[20:23], v[132:135], v[204:207], v[20:23]
	v_mfma_f32_16x16x32_bf16 v[0:3], v[158:161], v[204:207], v[0:3]
	v_mfma_f32_16x16x32_bf16 v[56:59], v[132:135], v[212:215], v[56:59]
	v_mfma_f32_16x16x32_bf16 v[36:39], v[158:161], v[212:215], v[36:39]
	v_mfma_f32_16x16x32_bf16 v[8:11], v[132:135], v[220:223], v[8:11]
	v_mfma_f32_16x16x32_bf16 v[12:15], v[158:161], v[220:223], v[12:15]
	v_mfma_f32_16x16x32_bf16 v[80:83], v[162:165], v[178:181], v[80:83]
	v_mfma_f32_16x16x32_bf16 v[72:75], v[170:173], v[178:181], v[72:75]
	v_mfma_f32_16x16x32_bf16 v[100:103], v[162:165], v[190:193], v[100:103]
	v_mfma_f32_16x16x32_bf16 v[92:95], v[170:173], v[190:193], v[92:95]
	v_mfma_f32_16x16x32_bf16 v[116:119], v[162:165], v[208:211], v[116:119]
	v_mfma_f32_16x16x32_bf16 v[108:111], v[170:173], v[208:211], v[108:111]
	v_mfma_f32_16x16x32_bf16 v[124:127], v[162:165], v[216:219], v[124:127]
	v_mfma_f32_16x16x32_bf16 v[120:123], v[170:173], v[216:219], v[120:123]
	v_mfma_f32_16x16x32_bf16 v[80:83], v[166:169], v[182:185], v[80:83]
	v_mfma_f32_16x16x32_bf16 v[72:75], v[174:177], v[182:185], v[72:75]
	v_mfma_f32_16x16x32_bf16 v[100:103], v[166:169], v[204:207], v[100:103]
	v_mfma_f32_16x16x32_bf16 v[92:95], v[174:177], v[204:207], v[92:95]
	v_mfma_f32_16x16x32_bf16 v[116:119], v[166:169], v[212:215], v[116:119]
	v_mfma_f32_16x16x32_bf16 v[108:111], v[174:177], v[212:215], v[108:111]
	v_mfma_f32_16x16x32_bf16 v[124:127], v[166:169], v[220:223], v[124:127]
	v_mfma_f32_16x16x32_bf16 v[120:123], v[174:177], v[220:223], v[120:123]
	s_setprio 0
	s_barrier
	s_add_i32 s61, 0, 0x18000
	v_add_u32_e32 v144, s61, v197
	s_add_i32 s62, 0, 0x1c000
	ds_read_b128 v[128:131], v144
	ds_read_b128 v[132:135], v144 offset:1024
	ds_read_b128 v[154:157], v144 offset:2048
	ds_read_b128 v[158:161], v144 offset:3072
	v_add_u32_e32 v144, s62, v197
	ds_read_b128 v[162:165], v144
	ds_read_b128 v[166:169], v144 offset:1024
	ds_read_b128 v[170:173], v144 offset:2048
	ds_read_b128 v[174:177], v144 offset:3072
	s_add_u32 s38, s38, 0x20000
	s_addc_u32 s39, s39, 0
	s_mov_b32 m0, s44
	v_lshl_add_u64 v[226:227], s[38:39], 0, v[136:137]
	ds_read_b128 v[178:181], v201 offset:32768
	ds_read_b128 v[182:185], v201 offset:33792
	ds_read_b128 v[190:193], v201 offset:34816
	ds_read_b128 v[204:207], v201 offset:35840
	ds_read_b128 v[208:211], v201 offset:36864
	ds_read_b128 v[212:215], v201 offset:37888
	ds_read_b128 v[216:219], v201 offset:38912
	ds_read_b128 v[220:223], v201 offset:39936
	global_load_lds_dwordx4 v[226:227], off
	v_lshl_add_u64 v[226:227], s[38:39], 0, v[140:141]
	s_mov_b32 m0, s45
	s_nop 0
	global_load_lds_dwordx4 v[226:227], off
	s_waitcnt vmcnt(8)
	s_waitcnt lgkmcnt(0)
	s_barrier
	s_setprio 1
	s_waitcnt lgkmcnt(0)
	v_mfma_f32_16x16x32_bf16 v[48:51], v[128:131], v[178:181], v[48:51]
	v_mfma_f32_16x16x32_bf16 v[28:31], v[154:157], v[178:181], v[28:31]
	v_mfma_f32_16x16x32_bf16 v[68:71], v[128:131], v[190:193], v[68:71]
	v_mfma_f32_16x16x32_bf16 v[52:55], v[154:157], v[190:193], v[52:55]
	v_mfma_f32_16x16x32_bf16 v[84:87], v[128:131], v[208:211], v[84:87]
	v_mfma_f32_16x16x32_bf16 v[76:79], v[154:157], v[208:211], v[76:79]
	v_mfma_f32_16x16x32_bf16 v[96:99], v[128:131], v[216:219], v[96:99]
	v_mfma_f32_16x16x32_bf16 v[88:91], v[154:157], v[216:219], v[88:91]
	v_mfma_f32_16x16x32_bf16 v[48:51], v[132:135], v[182:185], v[48:51]
	v_mfma_f32_16x16x32_bf16 v[28:31], v[158:161], v[182:185], v[28:31]
	v_mfma_f32_16x16x32_bf16 v[68:71], v[132:135], v[204:207], v[68:71]
	v_mfma_f32_16x16x32_bf16 v[52:55], v[158:161], v[204:207], v[52:55]
	v_mfma_f32_16x16x32_bf16 v[84:87], v[132:135], v[212:215], v[84:87]
	v_mfma_f32_16x16x32_bf16 v[76:79], v[158:161], v[212:215], v[76:79]
	v_mfma_f32_16x16x32_bf16 v[96:99], v[132:135], v[220:223], v[96:99]
	v_mfma_f32_16x16x32_bf16 v[88:91], v[158:161], v[220:223], v[88:91]
	v_mfma_f32_16x16x32_bf16 v[32:35], v[162:165], v[178:181], v[32:35]
	v_mfma_f32_16x16x32_bf16 v[16:19], v[170:173], v[178:181], v[16:19]
	v_mfma_f32_16x16x32_bf16 v[60:63], v[162:165], v[190:193], v[60:63]
	v_mfma_f32_16x16x32_bf16 v[40:43], v[170:173], v[190:193], v[40:43]
	v_mfma_f32_16x16x32_bf16 v[24:27], v[162:165], v[208:211], v[24:27]
	v_mfma_f32_16x16x32_bf16 v[4:7], v[170:173], v[208:211], v[4:7]
	v_mfma_f32_16x16x32_bf16 v[64:67], v[162:165], v[216:219], v[64:67]
	v_mfma_f32_16x16x32_bf16 v[44:47], v[170:173], v[216:219], v[44:47]
	v_mfma_f32_16x16x32_bf16 v[32:35], v[166:169], v[182:185], v[32:35]
	v_mfma_f32_16x16x32_bf16 v[16:19], v[174:177], v[182:185], v[16:19]
	v_mfma_f32_16x16x32_bf16 v[60:63], v[166:169], v[204:207], v[60:63]
	v_mfma_f32_16x16x32_bf16 v[40:43], v[174:177], v[204:207], v[40:43]
	v_mfma_f32_16x16x32_bf16 v[24:27], v[166:169], v[212:215], v[24:27]
	v_mfma_f32_16x16x32_bf16 v[4:7], v[174:177], v[212:215], v[4:7]
	v_mfma_f32_16x16x32_bf16 v[64:67], v[166:169], v[220:223], v[64:67]
	v_mfma_f32_16x16x32_bf16 v[44:47], v[174:177], v[220:223], v[44:47]
	s_setprio 0
	s_barrier
; #define PG8_STAGE(bufoff, gbase, voff) do { _Pragma("unroll") for (int _i = 0; _i < 2; ++_i) \
;         __builtin_amdgcn_global_load_lds((const unsigned*)((const char*)(gbase) + (voff)[_i]), (LAS unsigned*)(lds + (bufoff) + ldsw + _i * 8192), 16, 0, 0); } while (0)
; #define PG8_LDA(dst, b, h) do { _Pragma("unroll") for (int m = 0; m < 4; ++m) _Pragma("unroll") for (int k = 0; k < 2; ++k) dst[m][k] = *(const LAS bf16x8*)(lds + PG8_SA(b, h) + aoff + m * 2048 + k * 1024); } while (0)
; #define PG8_MMA(ai, bj, At, Bt) do { __builtin_amdgcn_s_setprio(1); _Pragma("unroll") for (int m = 0; m < 4; ++m) _Pragma("unroll") for (int n = 0; n < 2; ++n) _Pragma("unroll") for (int k = 0; k < 2; ++k) \
;         acc[ai][bj][m][n] = __builtin_amdgcn_mfma_f32_16x16x32_bf16(Bt[n][k], At[m][k], acc[ai][bj][m][n], 0, 0, 0); __builtin_amdgcn_s_setprio(0); } while (0)
; #define PG8_WAIT_V(n) asm volatile("s_waitcnt vmcnt(" #n ")" ::: "memory")
; #define PG8_WAIT_L(n) asm volatile("s_waitcnt lgkmcnt(" #n ")" ::: "memory")
; #define PG8_BAR __builtin_amdgcn_s_barrier()
; #define PG8_SCHED __builtin_amdgcn_sched_barrier(0)
; template <int MODE> DI void gemm_phase(LAS unsigned char* lds, const Gemm g, const StaticOrder& S, const Epi& E) {
;     ...
;             PG8_LDA(At, 1, 1); PG8_STAGE(PG8_SB(1, 0), b3, voffB); PG8_STAGE(PG8_SB(1, 1), b3 + hstepB, voffB); PG8_STAGE(PG8_SA(1, 0), a3, voffA);
;             PG8_WAIT_V(8); PG8_WAIT_L(0); PG8_BAR; PG8_MMA(1, 0, At, B0); PG8_MMA(1, 1, At, B1); PG8_BAR; PG8_SCHED;
;         }
;         if (wr == 0) PG8_BAR;
	s_add_i32 s38, s61, s41
	v_lshl_add_u64 v[186:187], v[186:187], 0, s[12:13]
	s_mov_b32 m0, s38
	ds_read_b128 v[178:181], v201 offset:49152
	ds_read_b128 v[182:185], v201 offset:50176
	ds_read_b128 v[190:193], v201 offset:51200
	ds_read_b128 v[204:207], v201 offset:52224
	ds_read_b128 v[208:211], v201 offset:53248
	ds_read_b128 v[212:215], v201 offset:54272
	ds_read_b128 v[216:219], v201 offset:55296
	ds_read_b128 v[220:223], v201 offset:56320
	global_load_lds_dwordx4 v[186:187], off
	s_add_i32 m0, s38, 0x2000
	s_add_u32 s36, s36, 0x8080
	v_lshl_add_u64 v[186:187], v[188:189], 0, s[12:13]
	s_addc_u32 s37, s37, 0
	s_add_i32 s38, s62, s41
	global_load_lds_dwordx4 v[186:187], off
	v_lshl_add_u64 v[186:187], s[36:37], 0, v[138:139]
	s_mov_b32 m0, s38
	s_nop 0
	global_load_lds_dwordx4 v[186:187], off
	v_lshl_add_u64 v[186:187], s[36:37], 0, v[142:143]
	s_add_i32 m0, s38, 0x2000
	s_nop 0
	global_load_lds_dwordx4 v[186:187], off
	v_lshl_add_u64 v[186:187], v[194:195], 0, s[12:13]
	s_mov_b32 m0, s53
	s_nop 0
	global_load_lds_dwordx4 v[186:187], off
	v_lshl_add_u64 v[186:187], v[224:225], 0, s[12:13]
	s_mov_b32 m0, s54
	s_nop 0
	global_load_lds_dwordx4 v[186:187], off
	s_waitcnt vmcnt(8)
	s_waitcnt lgkmcnt(0)
	s_barrier
	s_setprio 1
	s_waitcnt lgkmcnt(0)
	v_mfma_f32_16x16x32_bf16 v[112:115], v[128:131], v[178:181], v[112:115]
	v_mfma_f32_16x16x32_bf16 v[104:107], v[154:157], v[178:181], v[104:107]
	v_mfma_f32_16x16x32_bf16 v[20:23], v[128:131], v[190:193], v[20:23]
	v_mfma_f32_16x16x32_bf16 v[0:3], v[154:157], v[190:193], v[0:3]
	v_mfma_f32_16x16x32_bf16 v[56:59], v[128:131], v[208:211], v[56:59]
	v_mfma_f32_16x16x32_bf16 v[36:39], v[154:157], v[208:211], v[36:39]
	v_mfma_f32_16x16x32_bf16 v[8:11], v[128:131], v[216:219], v[8:11]
	v_mfma_f32_16x16x32_bf16 v[12:15], v[154:157], v[216:219], v[12:15]
	v_mfma_f32_16x16x32_bf16 v[112:115], v[132:135], v[182:185], v[112:115]
	v_mfma_f32_16x16x32_bf16 v[104:107], v[158:161], v[182:185], v[104:107]
	v_mfma_f32_16x16x32_bf16 v[20:23], v[132:135], v[204:207], v[20:23]
	v_mfma_f32_16x16x32_bf16 v[0:3], v[158:161], v[204:207], v[0:3]
	v_mfma_f32_16x16x32_bf16 v[56:59], v[132:135], v[212:215], v[56:59]
	v_mfma_f32_16x16x32_bf16 v[36:39], v[158:161], v[212:215], v[36:39]
	v_mfma_f32_16x16x32_bf16 v[8:11], v[132:135], v[220:223], v[8:11]
	v_mfma_f32_16x16x32_bf16 v[12:15], v[158:161], v[220:223], v[12:15]
	v_mfma_f32_16x16x32_bf16 v[80:83], v[162:165], v[178:181], v[80:83]
	v_mfma_f32_16x16x32_bf16 v[72:75], v[170:173], v[178:181], v[72:75]
	v_mfma_f32_16x16x32_bf16 v[100:103], v[162:165], v[190:193], v[100:103]
	v_mfma_f32_16x16x32_bf16 v[92:95], v[170:173], v[190:193], v[92:95]
	v_mfma_f32_16x16x32_bf16 v[116:119], v[162:165], v[208:211], v[116:119]
	v_mfma_f32_16x16x32_bf16 v[108:111], v[170:173], v[208:211], v[108:111]
	v_mfma_f32_16x16x32_bf16 v[124:127], v[162:165], v[216:219], v[124:127]
	v_mfma_f32_16x16x32_bf16 v[120:123], v[170:173], v[216:219], v[120:123]
	v_mfma_f32_16x16x32_bf16 v[80:83], v[166:169], v[182:185], v[80:83]
	v_mfma_f32_16x16x32_bf16 v[72:75], v[174:177], v[182:185], v[72:75]
	v_mfma_f32_16x16x32_bf16 v[100:103], v[166:169], v[204:207], v[100:103]
	v_mfma_f32_16x16x32_bf16 v[92:95], v[174:177], v[204:207], v[92:95]
	v_mfma_f32_16x16x32_bf16 v[116:119], v[166:169], v[212:215], v[116:119]
	v_mfma_f32_16x16x32_bf16 v[108:111], v[174:177], v[212:215], v[108:111]
	v_mfma_f32_16x16x32_bf16 v[124:127], v[166:169], v[220:223], v[124:127]
	v_mfma_f32_16x16x32_bf16 v[120:123], v[174:177], v[220:223], v[120:123]
	s_setprio 0
	s_barrier
	s_add_i32 s60, s60, 2
	s_add_u32 s34, s34, 0x100
	s_addc_u32 s35, s35, 0
	s_add_u32 s33, s33, 0x100
	s_addc_u32 s59, s59, 0
	s_cmp_gt_u32 s60, 5
	s_cbranch_scc0 .LBB0_499
	s_and_b64 vcc, exec, s[14:15]
	s_cbranch_vccz .LBB0_502
	s_barrier

; #define PG8_STAGE(bufoff, gbase, voff) do { _Pragma("unroll") for (int _i = 0; _i < 2; ++_i) \
;         __builtin_amdgcn_global_load_lds((const unsigned*)((const char*)(gbase) + (voff)[_i]), (LAS unsigned*)(lds + (bufoff) + ldsw + _i * 8192), 16, 0, 0); } while (0)
; #define PG8_LDA(dst, b, h) do { _Pragma("unroll") for (int m = 0; m < 4; ++m) _Pragma("unroll") for (int k = 0; k < 2; ++k) dst[m][k] = *(const LAS bf16x8*)(lds + PG8_SA(b, h) + aoff + m * 2048 + k * 1024); } while (0)
; #define PG8_LDB(dst, b, h) do { _Pragma("unroll") for (int n = 0; n < 2; ++n) _Pragma("unroll") for (int k = 0; k < 2; ++k) dst[n][k] = *(const LAS bf16x8*)(lds + PG8_SB(b, h) + boff + n * 2048 + k * 1024); } while (0)
; #define PG8_MMA(ai, bj, At, Bt) do { __builtin_amdgcn_s_setprio(1); _Pragma("unroll") for (int m = 0; m < 4; ++m) _Pragma("unroll") for (int n = 0; n < 2; ++n) _Pragma("unroll") for (int k = 0; k < 2; ++k) \
;         acc[ai][bj][m][n] = __builtin_amdgcn_mfma_f32_16x16x32_bf16(Bt[n][k], At[m][k], acc[ai][bj][m][n], 0, 0, 0); __builtin_amdgcn_s_setprio(0); } while (0)
; #define PG8_WAIT_V(n) asm volatile("s_waitcnt vmcnt(" #n ")" ::: "memory")
; #define PG8_WAIT_L(n) asm volatile("s_waitcnt lgkmcnt(" #n ")" ::: "memory")
; #define PG8_BAR __builtin_amdgcn_s_barrier()
; #define PG8_SCHED __builtin_amdgcn_sched_barrier(0)
; template <int MODE> DI void gemm_phase(LAS unsigned char* lds, const Gemm g, const StaticOrder& S, const Epi& E) {
;     ...
;         for (int t = 0; t < nt; t += 2) {
;             const bool last = (t == nt - 2);
;             const char* a1 = cA + (size_t)(t + 1) * kstep;
;             const char* a2 = last ? nA : cA + (size_t)(t + 2) * kstep; const char* b2 = last ? nB : cB + (size_t)(t + 2) * kstep;
;             const char* a3 = a2 + kstep; const char* b3 = b2 + kstep;
;             PG8_LDB(B0, 0, 0); PG8_LDB(B1, 0, 1); PG8_SCHED; PG8_LDA(At, 0, 0); PG8_STAGE(PG8_SA(1, 1), a1 + hstepA, voffA);
;             PG8_WAIT_V(8); PG8_WAIT_L(0); PG8_BAR; PG8_MMA(0, 0, At, B0); PG8_MMA(0, 1, At, B1); PG8_BAR; PG8_SCHED;
;             PG8_LDA(At, 0, 1); PG8_STAGE(PG8_SB(0, 0), b2, voffB); PG8_STAGE(PG8_SB(0, 1), b2 + hstepB, voffB); PG8_STAGE(PG8_SA(0, 0), a2, voffA);
;             PG8_WAIT_V(8); PG8_WAIT_L(0); PG8_BAR; PG8_MMA(1, 0, At, B0); PG8_MMA(1, 1, At, B1); PG8_BAR; PG8_SCHED;
.LBB0_590:
	ds_read_b128 v[144:147], v151
	ds_read_b128 v[154:157], v151 offset:1024
	ds_read_b128 v[158:161], v151 offset:2048
	ds_read_b128 v[162:165], v151 offset:3072
	ds_read_b128 v[166:169], v152
	ds_read_b128 v[170:173], v152 offset:1024
	ds_read_b128 v[174:177], v152 offset:2048
	ds_read_b128 v[178:181], v152 offset:3072
	s_add_u32 s20, s18, 0xfffc0080
	s_addc_u32 s21, s19, -1
	s_cmp_eq_u32 s43, 12
	s_cselect_b32 s23, s11, s21
	s_cselect_b32 s22, s39, s20
	s_cselect_b32 s21, s9, s42
	s_cselect_b32 s20, s40, s41
	v_lshl_add_u64 v[186:187], s[18:19], 0, v[136:137]
	s_add_i32 m0, s17, 0xc000
	ds_read_b128 v[182:185], v153
	ds_read_b128 v[190:193], v153 offset:1024
	ds_read_b128 v[194:197], v153 offset:2048
	ds_read_b128 v[198:201], v153 offset:3072
	ds_read_b128 v[202:205], v153 offset:4096
	ds_read_b128 v[206:209], v153 offset:5120
	ds_read_b128 v[210:213], v153 offset:6144
	ds_read_b128 v[214:217], v153 offset:7168
	global_load_lds_dwordx4 v[186:187], off
	v_lshl_add_u64 v[186:187], s[18:19], 0, v[138:139]
	s_add_i32 m0, s17, 0xe000
	s_nop 0
	global_load_lds_dwordx4 v[186:187], off
	s_waitcnt vmcnt(8)
	s_waitcnt lgkmcnt(0)
	s_barrier
	s_setprio 1
	s_waitcnt lgkmcnt(0)
	v_mfma_f32_16x16x32_bf16 v[124:127], v[144:147], v[182:185], v[124:127]
	v_mfma_f32_16x16x32_bf16 v[116:119], v[158:161], v[182:185], v[116:119]
	v_mfma_f32_16x16x32_bf16 v[108:111], v[144:147], v[194:197], v[108:111]
	v_mfma_f32_16x16x32_bf16 v[100:103], v[158:161], v[194:197], v[100:103]
	v_mfma_f32_16x16x32_bf16 v[92:95], v[144:147], v[202:205], v[92:95]
	v_mfma_f32_16x16x32_bf16 v[84:87], v[158:161], v[202:205], v[84:87]
	v_mfma_f32_16x16x32_bf16 v[76:79], v[144:147], v[210:213], v[76:79]
	v_mfma_f32_16x16x32_bf16 v[68:71], v[158:161], v[210:213], v[68:71]
	v_mfma_f32_16x16x32_bf16 v[124:127], v[154:157], v[190:193], v[124:127]
	v_mfma_f32_16x16x32_bf16 v[116:119], v[162:165], v[190:193], v[116:119]
	v_mfma_f32_16x16x32_bf16 v[108:111], v[154:157], v[198:201], v[108:111]
	v_mfma_f32_16x16x32_bf16 v[100:103], v[162:165], v[198:201], v[100:103]
	v_mfma_f32_16x16x32_bf16 v[92:95], v[154:157], v[206:209], v[92:95]
	v_mfma_f32_16x16x32_bf16 v[84:87], v[162:165], v[206:209], v[84:87]
	v_mfma_f32_16x16x32_bf16 v[76:79], v[154:157], v[214:217], v[76:79]
	v_mfma_f32_16x16x32_bf16 v[68:71], v[162:165], v[214:217], v[68:71]
	v_mfma_f32_16x16x32_bf16 v[120:123], v[166:169], v[182:185], v[120:123]
	v_mfma_f32_16x16x32_bf16 v[112:115], v[174:177], v[182:185], v[112:115]
	v_mfma_f32_16x16x32_bf16 v[104:107], v[166:169], v[194:197], v[104:107]
	v_mfma_f32_16x16x32_bf16 v[96:99], v[174:177], v[194:197], v[96:99]
	v_mfma_f32_16x16x32_bf16 v[88:91], v[166:169], v[202:205], v[88:91]
	v_mfma_f32_16x16x32_bf16 v[80:83], v[174:177], v[202:205], v[80:83]
	v_mfma_f32_16x16x32_bf16 v[72:75], v[166:169], v[210:213], v[72:75]
	v_mfma_f32_16x16x32_bf16 v[64:67], v[174:177], v[210:213], v[64:67]
	v_mfma_f32_16x16x32_bf16 v[120:123], v[170:173], v[190:193], v[120:123]
	v_mfma_f32_16x16x32_bf16 v[112:115], v[178:181], v[190:193], v[112:115]
	v_mfma_f32_16x16x32_bf16 v[104:107], v[170:173], v[198:201], v[104:107]
	v_mfma_f32_16x16x32_bf16 v[96:99], v[178:181], v[198:201], v[96:99]
	v_mfma_f32_16x16x32_bf16 v[88:91], v[170:173], v[206:209], v[88:91]
	v_mfma_f32_16x16x32_bf16 v[80:83], v[178:181], v[206:209], v[80:83]
	v_mfma_f32_16x16x32_bf16 v[72:75], v[170:173], v[214:217], v[72:75]
	v_mfma_f32_16x16x32_bf16 v[64:67], v[178:181], v[214:217], v[64:67]
	s_setprio 0
	s_barrier
	s_add_i32 s44, s35, s26
	v_lshl_add_u64 v[186:187], s[20:21], 0, v[132:133]
	s_mov_b32 m0, s44
	ds_read_b128 v[182:185], v153 offset:16384
	ds_read_b128 v[190:193], v153 offset:17408
	ds_read_b128 v[194:197], v153 offset:18432
	ds_read_b128 v[198:201], v153 offset:19456
	ds_read_b128 v[202:205], v153 offset:20480
	ds_read_b128 v[206:209], v153 offset:21504
	ds_read_b128 v[210:213], v153 offset:22528
	ds_read_b128 v[214:217], v153 offset:23552
	global_load_lds_dwordx4 v[186:187], off
	s_add_i32 m0, s44, 0x2000
	s_add_u32 s44, s20, 0x10000
	v_lshl_add_u64 v[188:189], s[20:21], 0, v[128:129]
	s_addc_u32 s45, s21, 0
	s_add_i32 s46, s36, s26
	global_load_lds_dwordx4 v[188:189], off
	v_lshl_add_u64 v[218:219], s[44:45], 0, v[132:133]
	s_mov_b32 m0, s46
	v_lshl_add_u64 v[220:221], s[22:23], 0, v[130:131]
	global_load_lds_dwordx4 v[218:219], off
	v_lshl_add_u64 v[218:219], s[44:45], 0, v[128:129]
	s_add_i32 m0, s46, 0x2000
	s_nop 0
	global_load_lds_dwordx4 v[218:219], off
	v_lshl_add_u64 v[218:219], s[22:23], 0, v[134:135]
	s_mov_b32 m0, s17
	s_nop 0
	global_load_lds_dwordx4 v[218:219], off
	s_mov_b32 m0, s28
	s_nop 0
	global_load_lds_dwordx4 v[220:221], off
	s_waitcnt vmcnt(8)
	s_waitcnt lgkmcnt(0)
	s_barrier
; #define PG8_STAGE(bufoff, gbase, voff) do { _Pragma("unroll") for (int _i = 0; _i < 2; ++_i) \
;         __builtin_amdgcn_global_load_lds((const unsigned*)((const char*)(gbase) + (voff)[_i]), (LAS unsigned*)(lds + (bufoff) + ldsw + _i * 8192), 16, 0, 0); } while (0)
; #define PG8_LDA(dst, b, h) do { _Pragma("unroll") for (int m = 0; m < 4; ++m) _Pragma("unroll") for (int k = 0; k < 2; ++k) dst[m][k] = *(const LAS bf16x8*)(lds + PG8_SA(b, h) + aoff + m * 2048 + k * 1024); } while (0)
; #define PG8_LDB(dst, b, h) do { _Pragma("unroll") for (int n = 0; n < 2; ++n) _Pragma("unroll") for (int k = 0; k < 2; ++k) dst[n][k] = *(const LAS bf16x8*)(lds + PG8_SB(b, h) + boff + n * 2048 + k * 1024); } while (0)
; #define PG8_MMA(ai, bj, At, Bt) do { __builtin_amdgcn_s_setprio(1); _Pragma("unroll") for (int m = 0; m < 4; ++m) _Pragma("unroll") for (int n = 0; n < 2; ++n) _Pragma("unroll") for (int k = 0; k < 2; ++k) \
;         acc[ai][bj][m][n] = __builtin_amdgcn_mfma_f32_16x16x32_bf16(Bt[n][k], At[m][k], acc[ai][bj][m][n], 0, 0, 0); __builtin_amdgcn_s_setprio(0); } while (0)
; #define PG8_WAIT_V(n) asm volatile("s_waitcnt vmcnt(" #n ")" ::: "memory")
; #define PG8_WAIT_L(n) asm volatile("s_waitcnt lgkmcnt(" #n ")" ::: "memory")
; #define PG8_BAR __builtin_amdgcn_s_barrier()
; #define PG8_SCHED __builtin_amdgcn_sched_barrier(0)
; template <int MODE> DI void gemm_phase(LAS unsigned char* lds, const Gemm g, const StaticOrder& S, const Epi& E) {
;     ...
;             PG8_WAIT_V(8); PG8_WAIT_L(0); PG8_BAR; PG8_MMA(1, 0, At, B0); PG8_MMA(1, 1, At, B1); PG8_BAR; PG8_SCHED;
;             PG8_LDB(B0, 1, 0); PG8_LDB(B1, 1, 1); PG8_SCHED; PG8_LDA(At, 1, 0); PG8_STAGE(PG8_SA(0, 1), a2 + hstepA, voffA);
;             PG8_WAIT_V(8); PG8_WAIT_L(0); PG8_BAR; PG8_MMA(0, 0, At, B0); PG8_MMA(0, 1, At, B1); PG8_BAR; PG8_SCHED;
;             PG8_LDA(At, 1, 1); PG8_STAGE(PG8_SB(1, 0), b3, voffB); PG8_STAGE(PG8_SB(1, 1), b3 + hstepB, voffB); PG8_STAGE(PG8_SA(1, 0), a3, voffA);
;             PG8_WAIT_V(8); PG8_WAIT_L(0); PG8_BAR; PG8_MMA(1, 0, At, B0); PG8_MMA(1, 1, At, B1); PG8_BAR; PG8_SCHED;
	s_setprio 1
	s_waitcnt lgkmcnt(0)
	v_mfma_f32_16x16x32_bf16 v[60:63], v[144:147], v[182:185], v[60:63]
	v_mfma_f32_16x16x32_bf16 v[52:55], v[158:161], v[182:185], v[52:55]
	v_mfma_f32_16x16x32_bf16 v[44:47], v[144:147], v[194:197], v[44:47]
	v_mfma_f32_16x16x32_bf16 v[36:39], v[158:161], v[194:197], v[36:39]
	v_mfma_f32_16x16x32_bf16 v[28:31], v[144:147], v[202:205], v[28:31]
	v_mfma_f32_16x16x32_bf16 v[20:23], v[158:161], v[202:205], v[20:23]
	v_mfma_f32_16x16x32_bf16 v[12:15], v[144:147], v[210:213], v[12:15]
	v_mfma_f32_16x16x32_bf16 v[4:7], v[158:161], v[210:213], v[4:7]
	v_mfma_f32_16x16x32_bf16 v[60:63], v[154:157], v[190:193], v[60:63]
	v_mfma_f32_16x16x32_bf16 v[52:55], v[162:165], v[190:193], v[52:55]
	v_mfma_f32_16x16x32_bf16 v[44:47], v[154:157], v[198:201], v[44:47]
	v_mfma_f32_16x16x32_bf16 v[36:39], v[162:165], v[198:201], v[36:39]
	v_mfma_f32_16x16x32_bf16 v[28:31], v[154:157], v[206:209], v[28:31]
	v_mfma_f32_16x16x32_bf16 v[20:23], v[162:165], v[206:209], v[20:23]
	v_mfma_f32_16x16x32_bf16 v[12:15], v[154:157], v[214:217], v[12:15]
	v_mfma_f32_16x16x32_bf16 v[4:7], v[162:165], v[214:217], v[4:7]
	v_mfma_f32_16x16x32_bf16 v[56:59], v[166:169], v[182:185], v[56:59]
	v_mfma_f32_16x16x32_bf16 v[48:51], v[174:177], v[182:185], v[48:51]
	v_mfma_f32_16x16x32_bf16 v[40:43], v[166:169], v[194:197], v[40:43]
	v_mfma_f32_16x16x32_bf16 v[32:35], v[174:177], v[194:197], v[32:35]
	v_mfma_f32_16x16x32_bf16 v[24:27], v[166:169], v[202:205], v[24:27]
	v_mfma_f32_16x16x32_bf16 v[16:19], v[174:177], v[202:205], v[16:19]
	v_mfma_f32_16x16x32_bf16 v[8:11], v[166:169], v[210:213], v[8:11]
	v_mfma_f32_16x16x32_bf16 v[0:3], v[174:177], v[210:213], v[0:3]
	v_mfma_f32_16x16x32_bf16 v[56:59], v[170:173], v[190:193], v[56:59]
	v_mfma_f32_16x16x32_bf16 v[48:51], v[178:181], v[190:193], v[48:51]
	v_mfma_f32_16x16x32_bf16 v[40:43], v[170:173], v[198:201], v[40:43]
	v_mfma_f32_16x16x32_bf16 v[32:35], v[178:181], v[198:201], v[32:35]
	v_mfma_f32_16x16x32_bf16 v[24:27], v[170:173], v[206:209], v[24:27]
	v_mfma_f32_16x16x32_bf16 v[16:19], v[178:181], v[206:209], v[16:19]
	v_mfma_f32_16x16x32_bf16 v[8:11], v[170:173], v[214:217], v[8:11]
	v_mfma_f32_16x16x32_bf16 v[0:3], v[178:181], v[214:217], v[0:3]
	s_setprio 0
	s_barrier
	s_add_i32 s44, 0, 0x18000
	s_add_i32 s45, 0, 0x1c000
	v_add_u32_e32 v162, s44, v149
	v_add_u32_e32 v178, s45, v149
	ds_read_b128 v[144:147], v162
	ds_read_b128 v[154:157], v162 offset:1024
	ds_read_b128 v[158:161], v162 offset:2048
	ds_read_b128 v[162:165], v162 offset:3072
	ds_read_b128 v[166:169], v178
	ds_read_b128 v[170:173], v178 offset:1024
	ds_read_b128 v[174:177], v178 offset:2048
	ds_read_b128 v[178:181], v178 offset:3072
	s_add_u32 s22, s22, 0x40000
	s_addc_u32 s23, s23, 0
	s_mov_b32 m0, s29
	v_lshl_add_u64 v[222:223], s[22:23], 0, v[134:135]
	ds_read_b128 v[182:185], v153 offset:32768
	ds_read_b128 v[190:193], v153 offset:33792
	ds_read_b128 v[194:197], v153 offset:34816
	ds_read_b128 v[198:201], v153 offset:35840
	ds_read_b128 v[202:205], v153 offset:36864
	ds_read_b128 v[206:209], v153 offset:37888
	ds_read_b128 v[210:213], v153 offset:38912
	ds_read_b128 v[214:217], v153 offset:39936
	global_load_lds_dwordx4 v[222:223], off
	v_lshl_add_u64 v[222:223], s[22:23], 0, v[130:131]
	s_mov_b32 m0, s30
	s_nop 0
	global_load_lds_dwordx4 v[222:223], off
	s_waitcnt vmcnt(8)
	s_waitcnt lgkmcnt(0)
	s_barrier
	s_setprio 1
	s_waitcnt lgkmcnt(0)
	v_mfma_f32_16x16x32_bf16 v[124:127], v[144:147], v[182:185], v[124:127]
	v_mfma_f32_16x16x32_bf16 v[116:119], v[158:161], v[182:185], v[116:119]
	v_mfma_f32_16x16x32_bf16 v[108:111], v[144:147], v[194:197], v[108:111]
	v_mfma_f32_16x16x32_bf16 v[100:103], v[158:161], v[194:197], v[100:103]
	v_mfma_f32_16x16x32_bf16 v[92:95], v[144:147], v[202:205], v[92:95]
	v_mfma_f32_16x16x32_bf16 v[84:87], v[158:161], v[202:205], v[84:87]
	v_mfma_f32_16x16x32_bf16 v[76:79], v[144:147], v[210:213], v[76:79]
	v_mfma_f32_16x16x32_bf16 v[68:71], v[158:161], v[210:213], v[68:71]
	v_mfma_f32_16x16x32_bf16 v[124:127], v[154:157], v[190:193], v[124:127]
	v_mfma_f32_16x16x32_bf16 v[116:119], v[162:165], v[190:193], v[116:119]
	v_mfma_f32_16x16x32_bf16 v[108:111], v[154:157], v[198:201], v[108:111]
	v_mfma_f32_16x16x32_bf16 v[100:103], v[162:165], v[198:201], v[100:103]
	v_mfma_f32_16x16x32_bf16 v[92:95], v[154:157], v[206:209], v[92:95]
	v_mfma_f32_16x16x32_bf16 v[84:87], v[162:165], v[206:209], v[84:87]
	v_mfma_f32_16x16x32_bf16 v[76:79], v[154:157], v[214:217], v[76:79]
	v_mfma_f32_16x16x32_bf16 v[68:71], v[162:165], v[214:217], v[68:71]
	v_mfma_f32_16x16x32_bf16 v[120:123], v[166:169], v[182:185], v[120:123]
	v_mfma_f32_16x16x32_bf16 v[112:115], v[174:177], v[182:185], v[112:115]
	v_mfma_f32_16x16x32_bf16 v[104:107], v[166:169], v[194:197], v[104:107]
	v_mfma_f32_16x16x32_bf16 v[96:99], v[174:177], v[194:197], v[96:99]
	v_mfma_f32_16x16x32_bf16 v[88:91], v[166:169], v[202:205], v[88:91]
	v_mfma_f32_16x16x32_bf16 v[80:83], v[174:177], v[202:205], v[80:83]
	v_mfma_f32_16x16x32_bf16 v[72:75], v[166:169], v[210:213], v[72:75]
	v_mfma_f32_16x16x32_bf16 v[64:67], v[174:177], v[210:213], v[64:67]
	v_mfma_f32_16x16x32_bf16 v[120:123], v[170:173], v[190:193], v[120:123]
	v_mfma_f32_16x16x32_bf16 v[112:115], v[178:181], v[190:193], v[112:115]
	v_mfma_f32_16x16x32_bf16 v[104:107], v[170:173], v[198:201], v[104:107]
	v_mfma_f32_16x16x32_bf16 v[96:99], v[178:181], v[198:201], v[96:99]
	v_mfma_f32_16x16x32_bf16 v[88:91], v[170:173], v[206:209], v[88:91]
	v_mfma_f32_16x16x32_bf16 v[80:83], v[178:181], v[206:209], v[80:83]
	v_mfma_f32_16x16x32_bf16 v[72:75], v[170:173], v[214:217], v[72:75]
	v_mfma_f32_16x16x32_bf16 v[64:67], v[178:181], v[214:217], v[64:67]
	s_setprio 0
	s_barrier
; #define PG8_STAGE(bufoff, gbase, voff) do { _Pragma("unroll") for (int _i = 0; _i < 2; ++_i) \
;         __builtin_amdgcn_global_load_lds((const unsigned*)((const char*)(gbase) + (voff)[_i]), (LAS unsigned*)(lds + (bufoff) + ldsw + _i * 8192), 16, 0, 0); } while (0)
; #define PG8_LDA(dst, b, h) do { _Pragma("unroll") for (int m = 0; m < 4; ++m) _Pragma("unroll") for (int k = 0; k < 2; ++k) dst[m][k] = *(const LAS bf16x8*)(lds + PG8_SA(b, h) + aoff + m * 2048 + k * 1024); } while (0)
; #define PG8_MMA(ai, bj, At, Bt) do { __builtin_amdgcn_s_setprio(1); _Pragma("unroll") for (int m = 0; m < 4; ++m) _Pragma("unroll") for (int n = 0; n < 2; ++n) _Pragma("unroll") for (int k = 0; k < 2; ++k) \
;         acc[ai][bj][m][n] = __builtin_amdgcn_mfma_f32_16x16x32_bf16(Bt[n][k], At[m][k], acc[ai][bj][m][n], 0, 0, 0); __builtin_amdgcn_s_setprio(0); } while (0)
; #define PG8_WAIT_V(n) asm volatile("s_waitcnt vmcnt(" #n ")" ::: "memory")
; #define PG8_WAIT_L(n) asm volatile("s_waitcnt lgkmcnt(" #n ")" ::: "memory")
; #define PG8_BAR __builtin_amdgcn_s_barrier()
; #define PG8_SCHED __builtin_amdgcn_sched_barrier(0)
; template <int MODE> DI void gemm_phase(LAS unsigned char* lds, const Gemm g, const StaticOrder& S, const Epi& E) {
;     ...
;             PG8_LDA(At, 1, 1); PG8_STAGE(PG8_SB(1, 0), b3, voffB); PG8_STAGE(PG8_SB(1, 1), b3 + hstepB, voffB); PG8_STAGE(PG8_SA(1, 0), a3, voffA);
;             PG8_WAIT_V(8); PG8_WAIT_L(0); PG8_BAR; PG8_MMA(1, 0, At, B0); PG8_MMA(1, 1, At, B1); PG8_BAR; PG8_SCHED;
;         }
;         if (wr == 0) PG8_BAR;
	s_add_i32 s22, s44, s26
	v_lshl_add_u64 v[186:187], v[186:187], 0, s[2:3]
	s_mov_b32 m0, s22
	ds_read_b128 v[182:185], v153 offset:49152
	ds_read_b128 v[190:193], v153 offset:50176
	ds_read_b128 v[194:197], v153 offset:51200
	ds_read_b128 v[198:201], v153 offset:52224
	ds_read_b128 v[202:205], v153 offset:53248
	ds_read_b128 v[206:209], v153 offset:54272
	ds_read_b128 v[210:213], v153 offset:55296
	ds_read_b128 v[214:217], v153 offset:56320
	global_load_lds_dwordx4 v[186:187], off
	s_add_i32 m0, s22, 0x2000
	s_add_u32 s20, s20, 0x10080
	v_lshl_add_u64 v[186:187], v[188:189], 0, s[2:3]
	s_addc_u32 s21, s21, 0
	s_add_i32 s22, s45, s26
	global_load_lds_dwordx4 v[186:187], off
	v_lshl_add_u64 v[186:187], s[20:21], 0, v[132:133]
	s_mov_b32 m0, s22
	s_nop 0
	global_load_lds_dwordx4 v[186:187], off
	v_lshl_add_u64 v[186:187], s[20:21], 0, v[128:129]
	s_add_i32 m0, s22, 0x2000
	s_nop 0
	global_load_lds_dwordx4 v[186:187], off
	v_lshl_add_u64 v[186:187], v[218:219], 0, s[2:3]
	s_mov_b32 m0, s33
	s_nop 0
	global_load_lds_dwordx4 v[186:187], off
	v_lshl_add_u64 v[186:187], v[220:221], 0, s[2:3]
	s_mov_b32 m0, s34
	s_nop 0
	global_load_lds_dwordx4 v[186:187], off
	s_waitcnt vmcnt(8)
	s_waitcnt lgkmcnt(0)
	s_barrier
	s_setprio 1
	s_waitcnt lgkmcnt(0)
	v_mfma_f32_16x16x32_bf16 v[60:63], v[144:147], v[182:185], v[60:63]
	v_mfma_f32_16x16x32_bf16 v[52:55], v[158:161], v[182:185], v[52:55]
	v_mfma_f32_16x16x32_bf16 v[44:47], v[144:147], v[194:197], v[44:47]
	v_mfma_f32_16x16x32_bf16 v[36:39], v[158:161], v[194:197], v[36:39]
	v_mfma_f32_16x16x32_bf16 v[28:31], v[144:147], v[202:205], v[28:31]
	v_mfma_f32_16x16x32_bf16 v[20:23], v[158:161], v[202:205], v[20:23]
	v_mfma_f32_16x16x32_bf16 v[12:15], v[144:147], v[210:213], v[12:15]
	v_mfma_f32_16x16x32_bf16 v[4:7], v[158:161], v[210:213], v[4:7]
	v_mfma_f32_16x16x32_bf16 v[60:63], v[154:157], v[190:193], v[60:63]
	v_mfma_f32_16x16x32_bf16 v[52:55], v[162:165], v[190:193], v[52:55]
	v_mfma_f32_16x16x32_bf16 v[44:47], v[154:157], v[198:201], v[44:47]
	v_mfma_f32_16x16x32_bf16 v[36:39], v[162:165], v[198:201], v[36:39]
	v_mfma_f32_16x16x32_bf16 v[28:31], v[154:157], v[206:209], v[28:31]
	v_mfma_f32_16x16x32_bf16 v[20:23], v[162:165], v[206:209], v[20:23]
	v_mfma_f32_16x16x32_bf16 v[12:15], v[154:157], v[214:217], v[12:15]
	v_mfma_f32_16x16x32_bf16 v[4:7], v[162:165], v[214:217], v[4:7]
	v_mfma_f32_16x16x32_bf16 v[56:59], v[166:169], v[182:185], v[56:59]
	v_mfma_f32_16x16x32_bf16 v[48:51], v[174:177], v[182:185], v[48:51]
	v_mfma_f32_16x16x32_bf16 v[40:43], v[166:169], v[194:197], v[40:43]
	v_mfma_f32_16x16x32_bf16 v[32:35], v[174:177], v[194:197], v[32:35]
	v_mfma_f32_16x16x32_bf16 v[24:27], v[166:169], v[202:205], v[24:27]
	v_mfma_f32_16x16x32_bf16 v[16:19], v[174:177], v[202:205], v[16:19]
	v_mfma_f32_16x16x32_bf16 v[8:11], v[166:169], v[210:213], v[8:11]
	v_mfma_f32_16x16x32_bf16 v[0:3], v[174:177], v[210:213], v[0:3]
	v_mfma_f32_16x16x32_bf16 v[56:59], v[170:173], v[190:193], v[56:59]
	v_mfma_f32_16x16x32_bf16 v[48:51], v[178:181], v[190:193], v[48:51]
	v_mfma_f32_16x16x32_bf16 v[40:43], v[170:173], v[198:201], v[40:43]
	v_mfma_f32_16x16x32_bf16 v[32:35], v[178:181], v[198:201], v[32:35]
	v_mfma_f32_16x16x32_bf16 v[24:27], v[170:173], v[206:209], v[24:27]
	v_mfma_f32_16x16x32_bf16 v[16:19], v[178:181], v[206:209], v[16:19]
	v_mfma_f32_16x16x32_bf16 v[8:11], v[170:173], v[214:217], v[8:11]
	v_mfma_f32_16x16x32_bf16 v[0:3], v[178:181], v[214:217], v[0:3]
	s_setprio 0
	s_barrier
	s_add_i32 s43, s43, 2
	s_add_u32 s18, s18, 0x100
	s_addc_u32 s19, s19, 0
	s_add_u32 s41, s41, 0x100
	s_addc_u32 s42, s42, 0
	s_cmp_gt_u32 s43, 13
	s_cbranch_scc0 .LBB0_590
	s_and_b64 vcc, exec, s[6:7]
	s_cbranch_vccz .LBB0_593
	s_barrier

; #define PG8_STAGE(bufoff, gbase, voff) do { _Pragma("unroll") for (int _i = 0; _i < 2; ++_i) \
;         __builtin_amdgcn_global_load_lds((const unsigned*)((const char*)(gbase) + (voff)[_i]), (LAS unsigned*)(lds + (bufoff) + ldsw + _i * 8192), 16, 0, 0); } while (0)
; #define PG8_LDA(dst, b, h) do { _Pragma("unroll") for (int m = 0; m < 4; ++m) _Pragma("unroll") for (int k = 0; k < 2; ++k) dst[m][k] = *(const LAS bf16x8*)(lds + PG8_SA(b, h) + aoff + m * 2048 + k * 1024); } while (0)
; #define PG8_LDB(dst, b, h) do { _Pragma("unroll") for (int n = 0; n < 2; ++n) _Pragma("unroll") for (int k = 0; k < 2; ++k) dst[n][k] = *(const LAS bf16x8*)(lds + PG8_SB(b, h) + boff + n * 2048 + k * 1024); } while (0)
; #define PG8_MMA(ai, bj, At, Bt) do { __builtin_amdgcn_s_setprio(1); _Pragma("unroll") for (int m = 0; m < 4; ++m) _Pragma("unroll") for (int n = 0; n < 2; ++n) _Pragma("unroll") for (int k = 0; k < 2; ++k) \
;         acc[ai][bj][m][n] = __builtin_amdgcn_mfma_f32_16x16x32_bf16(Bt[n][k], At[m][k], acc[ai][bj][m][n], 0, 0, 0); __builtin_amdgcn_s_setprio(0); } while (0)
; #define PG8_WAIT_V(n) asm volatile("s_waitcnt vmcnt(" #n ")" ::: "memory")
; #define PG8_WAIT_L(n) asm volatile("s_waitcnt lgkmcnt(" #n ")" ::: "memory")
; #define PG8_BAR __builtin_amdgcn_s_barrier()
; #define PG8_SCHED __builtin_amdgcn_sched_barrier(0)
; template <int MODE> DI void gemm_phase(LAS unsigned char* lds, const Gemm g, const StaticOrder& S, const Epi& E) {
;     ...
;         for (int t = 0; t < nt; t += 2) {
;             const bool last = (t == nt - 2);
;             const char* a1 = cA + (size_t)(t + 1) * kstep;
;             const char* a2 = last ? nA : cA + (size_t)(t + 2) * kstep; const char* b2 = last ? nB : cB + (size_t)(t + 2) * kstep;
;             const char* a3 = a2 + kstep; const char* b3 = b2 + kstep;
;             PG8_LDB(B0, 0, 0); PG8_LDB(B1, 0, 1); PG8_SCHED; PG8_LDA(At, 0, 0); PG8_STAGE(PG8_SA(1, 1), a1 + hstepA, voffA);
;             PG8_WAIT_V(8); PG8_WAIT_L(0); PG8_BAR; PG8_MMA(0, 0, At, B0); PG8_MMA(0, 1, At, B1); PG8_BAR; PG8_SCHED;
;             PG8_LDA(At, 0, 1); PG8_STAGE(PG8_SB(0, 0), b2, voffB); PG8_STAGE(PG8_SB(0, 1), b2 + hstepB, voffB); PG8_STAGE(PG8_SA(0, 0), a2, voffA);
;             PG8_WAIT_V(8); PG8_WAIT_L(0); PG8_BAR; PG8_MMA(1, 0, At, B0); PG8_MMA(1, 1, At, B1); PG8_BAR; PG8_SCHED;
.LBB0_665:
	ds_read_b128 v[128:131], v197
	ds_read_b128 v[132:135], v197 offset:1024
	ds_read_b128 v[154:157], v197 offset:2048
	ds_read_b128 v[158:161], v197 offset:3072
	ds_read_b128 v[162:165], v198
	ds_read_b128 v[166:169], v198 offset:1024
	ds_read_b128 v[170:173], v198 offset:2048
	ds_read_b128 v[174:177], v198 offset:3072
	s_add_u32 s8, s10, 0x100
	s_addc_u32 s9, s11, 0
	s_cmp_eq_u32 s58, 40
	s_cselect_b32 s15, s35, s9
	s_cselect_b32 s14, s34, s8
	s_cselect_b32 s13, s37, s39
	s_cselect_b32 s12, s36, s38
	v_lshl_add_u64 v[186:187], s[10:11], 0, v[146:147]
	s_add_i32 m0, s31, 0xc000
	ds_read_b128 v[178:181], v199
	ds_read_b128 v[182:185], v199 offset:1024
	ds_read_b128 v[202:205], v199 offset:2048
	ds_read_b128 v[206:209], v199 offset:3072
	ds_read_b128 v[210:213], v199 offset:4096
	ds_read_b128 v[214:217], v199 offset:5120
	ds_read_b128 v[218:221], v199 offset:6144
	ds_read_b128 v[222:225], v199 offset:7168
	global_load_lds_dwordx4 v[186:187], off
	v_lshl_add_u64 v[186:187], s[10:11], 0, v[148:149]
	s_add_i32 m0, s31, 0xe000
	s_nop 0
	global_load_lds_dwordx4 v[186:187], off
	s_waitcnt vmcnt(8)
	s_waitcnt lgkmcnt(0)
	s_barrier
	s_setprio 1
	s_waitcnt lgkmcnt(0)
	v_mfma_f32_16x16x32_bf16 v[48:51], v[128:131], v[178:181], v[48:51]
	v_mfma_f32_16x16x32_bf16 v[28:31], v[154:157], v[178:181], v[28:31]
	v_mfma_f32_16x16x32_bf16 v[68:71], v[128:131], v[202:205], v[68:71]
	v_mfma_f32_16x16x32_bf16 v[52:55], v[154:157], v[202:205], v[52:55]
	v_mfma_f32_16x16x32_bf16 v[84:87], v[128:131], v[210:213], v[84:87]
	v_mfma_f32_16x16x32_bf16 v[76:79], v[154:157], v[210:213], v[76:79]
	v_mfma_f32_16x16x32_bf16 v[96:99], v[128:131], v[218:221], v[96:99]
	v_mfma_f32_16x16x32_bf16 v[88:91], v[154:157], v[218:221], v[88:91]
	v_mfma_f32_16x16x32_bf16 v[48:51], v[132:135], v[182:185], v[48:51]
	v_mfma_f32_16x16x32_bf16 v[28:31], v[158:161], v[182:185], v[28:31]
	v_mfma_f32_16x16x32_bf16 v[68:71], v[132:135], v[206:209], v[68:71]
	v_mfma_f32_16x16x32_bf16 v[52:55], v[158:161], v[206:209], v[52:55]
	v_mfma_f32_16x16x32_bf16 v[84:87], v[132:135], v[214:217], v[84:87]
	v_mfma_f32_16x16x32_bf16 v[76:79], v[158:161], v[214:217], v[76:79]
	v_mfma_f32_16x16x32_bf16 v[96:99], v[132:135], v[222:225], v[96:99]
	v_mfma_f32_16x16x32_bf16 v[88:91], v[158:161], v[222:225], v[88:91]
	v_mfma_f32_16x16x32_bf16 v[32:35], v[162:165], v[178:181], v[32:35]
	v_mfma_f32_16x16x32_bf16 v[16:19], v[170:173], v[178:181], v[16:19]
	v_mfma_f32_16x16x32_bf16 v[60:63], v[162:165], v[202:205], v[60:63]
	v_mfma_f32_16x16x32_bf16 v[40:43], v[170:173], v[202:205], v[40:43]
	v_mfma_f32_16x16x32_bf16 v[24:27], v[162:165], v[210:213], v[24:27]
	v_mfma_f32_16x16x32_bf16 v[4:7], v[170:173], v[210:213], v[4:7]
	v_mfma_f32_16x16x32_bf16 v[64:67], v[162:165], v[218:221], v[64:67]
	v_mfma_f32_16x16x32_bf16 v[44:47], v[170:173], v[218:221], v[44:47]
	v_mfma_f32_16x16x32_bf16 v[32:35], v[166:169], v[182:185], v[32:35]
	v_mfma_f32_16x16x32_bf16 v[16:19], v[174:177], v[182:185], v[16:19]
	v_mfma_f32_16x16x32_bf16 v[60:63], v[166:169], v[206:209], v[60:63]
	v_mfma_f32_16x16x32_bf16 v[40:43], v[174:177], v[206:209], v[40:43]
	v_mfma_f32_16x16x32_bf16 v[24:27], v[166:169], v[214:217], v[24:27]
	v_mfma_f32_16x16x32_bf16 v[4:7], v[174:177], v[214:217], v[4:7]
	v_mfma_f32_16x16x32_bf16 v[64:67], v[166:169], v[222:225], v[64:67]
	v_mfma_f32_16x16x32_bf16 v[44:47], v[174:177], v[222:225], v[44:47]
	s_setprio 0
	s_barrier
	s_add_i32 s10, s52, s29
	v_lshl_add_u64 v[186:187], s[12:13], 0, v[138:139]
	s_mov_b32 m0, s10
	ds_read_b128 v[178:181], v199 offset:16384
	ds_read_b128 v[182:185], v199 offset:17408
	ds_read_b128 v[202:205], v199 offset:18432
	ds_read_b128 v[206:209], v199 offset:19456
	ds_read_b128 v[210:213], v199 offset:20480
	ds_read_b128 v[214:217], v199 offset:21504
	ds_read_b128 v[218:221], v199 offset:22528
	ds_read_b128 v[222:225], v199 offset:23552
	global_load_lds_dwordx4 v[186:187], off
	s_add_i32 m0, s10, 0x2000
	s_add_u32 s10, s12, 0x2c000
	v_lshl_add_u64 v[188:189], s[12:13], 0, v[142:143]
	s_addc_u32 s11, s13, 0
	s_add_i32 s59, s53, s29
	global_load_lds_dwordx4 v[188:189], off
	v_lshl_add_u64 v[194:195], s[10:11], 0, v[138:139]
	s_mov_b32 m0, s59
	v_lshl_add_u64 v[226:227], s[14:15], 0, v[140:141]
	global_load_lds_dwordx4 v[194:195], off
	v_lshl_add_u64 v[194:195], s[10:11], 0, v[142:143]
	s_add_i32 m0, s59, 0x2000
	s_nop 0
	global_load_lds_dwordx4 v[194:195], off
	v_lshl_add_u64 v[194:195], s[14:15], 0, v[136:137]
	s_mov_b32 m0, s31
	s_nop 0
	global_load_lds_dwordx4 v[194:195], off
	s_mov_b32 m0, s33
	s_nop 0
	global_load_lds_dwordx4 v[226:227], off
	s_waitcnt vmcnt(8)
	s_waitcnt lgkmcnt(0)
	s_barrier
; #define PG8_STAGE(bufoff, gbase, voff) do { _Pragma("unroll") for (int _i = 0; _i < 2; ++_i) \
;         __builtin_amdgcn_global_load_lds((const unsigned*)((const char*)(gbase) + (voff)[_i]), (LAS unsigned*)(lds + (bufoff) + ldsw + _i * 8192), 16, 0, 0); } while (0)
; #define PG8_LDA(dst, b, h) do { _Pragma("unroll") for (int m = 0; m < 4; ++m) _Pragma("unroll") for (int k = 0; k < 2; ++k) dst[m][k] = *(const LAS bf16x8*)(lds + PG8_SA(b, h) + aoff + m * 2048 + k * 1024); } while (0)
; #define PG8_LDB(dst, b, h) do { _Pragma("unroll") for (int n = 0; n < 2; ++n) _Pragma("unroll") for (int k = 0; k < 2; ++k) dst[n][k] = *(const LAS bf16x8*)(lds + PG8_SB(b, h) + boff + n * 2048 + k * 1024); } while (0)
; #define PG8_MMA(ai, bj, At, Bt) do { __builtin_amdgcn_s_setprio(1); _Pragma("unroll") for (int m = 0; m < 4; ++m) _Pragma("unroll") for (int n = 0; n < 2; ++n) _Pragma("unroll") for (int k = 0; k < 2; ++k) \
;         acc[ai][bj][m][n] = __builtin_amdgcn_mfma_f32_16x16x32_bf16(Bt[n][k], At[m][k], acc[ai][bj][m][n], 0, 0, 0); __builtin_amdgcn_s_setprio(0); } while (0)
; #define PG8_WAIT_V(n) asm volatile("s_waitcnt vmcnt(" #n ")" ::: "memory")
; #define PG8_WAIT_L(n) asm volatile("s_waitcnt lgkmcnt(" #n ")" ::: "memory")
; #define PG8_BAR __builtin_amdgcn_s_barrier()
; #define PG8_SCHED __builtin_amdgcn_sched_barrier(0)
; template <int MODE> DI void gemm_phase(LAS unsigned char* lds, const Gemm g, const StaticOrder& S, const Epi& E) {
;     ...
;             PG8_WAIT_V(8); PG8_WAIT_L(0); PG8_BAR; PG8_MMA(1, 0, At, B0); PG8_MMA(1, 1, At, B1); PG8_BAR; PG8_SCHED;
;             PG8_LDB(B0, 1, 0); PG8_LDB(B1, 1, 1); PG8_SCHED; PG8_LDA(At, 1, 0); PG8_STAGE(PG8_SA(0, 1), a2 + hstepA, voffA);
;             PG8_WAIT_V(8); PG8_WAIT_L(0); PG8_BAR; PG8_MMA(0, 0, At, B0); PG8_MMA(0, 1, At, B1); PG8_BAR; PG8_SCHED;
;             PG8_LDA(At, 1, 1); PG8_STAGE(PG8_SB(1, 0), b3, voffB); PG8_STAGE(PG8_SB(1, 1), b3 + hstepB, voffB); PG8_STAGE(PG8_SA(1, 0), a3, voffA);
;             PG8_WAIT_V(8); PG8_WAIT_L(0); PG8_BAR; PG8_MMA(1, 0, At, B0); PG8_MMA(1, 1, At, B1); PG8_BAR; PG8_SCHED;
	s_setprio 1
	s_waitcnt lgkmcnt(0)
	v_mfma_f32_16x16x32_bf16 v[112:115], v[128:131], v[178:181], v[112:115]
	v_mfma_f32_16x16x32_bf16 v[104:107], v[154:157], v[178:181], v[104:107]
	v_mfma_f32_16x16x32_bf16 v[20:23], v[128:131], v[202:205], v[20:23]
	v_mfma_f32_16x16x32_bf16 v[0:3], v[154:157], v[202:205], v[0:3]
	v_mfma_f32_16x16x32_bf16 v[56:59], v[128:131], v[210:213], v[56:59]
	v_mfma_f32_16x16x32_bf16 v[36:39], v[154:157], v[210:213], v[36:39]
	v_mfma_f32_16x16x32_bf16 v[8:11], v[128:131], v[218:221], v[8:11]
	v_mfma_f32_16x16x32_bf16 v[12:15], v[154:157], v[218:221], v[12:15]
	v_mfma_f32_16x16x32_bf16 v[112:115], v[132:135], v[182:185], v[112:115]
	v_mfma_f32_16x16x32_bf16 v[104:107], v[158:161], v[182:185], v[104:107]
	v_mfma_f32_16x16x32_bf16 v[20:23], v[132:135], v[206:209], v[20:23]
	v_mfma_f32_16x16x32_bf16 v[0:3], v[158:161], v[206:209], v[0:3]
	v_mfma_f32_16x16x32_bf16 v[56:59], v[132:135], v[214:217], v[56:59]
	v_mfma_f32_16x16x32_bf16 v[36:39], v[158:161], v[214:217], v[36:39]
	v_mfma_f32_16x16x32_bf16 v[8:11], v[132:135], v[222:225], v[8:11]
	v_mfma_f32_16x16x32_bf16 v[12:15], v[158:161], v[222:225], v[12:15]
	v_mfma_f32_16x16x32_bf16 v[80:83], v[162:165], v[178:181], v[80:83]
	v_mfma_f32_16x16x32_bf16 v[72:75], v[170:173], v[178:181], v[72:75]
	v_mfma_f32_16x16x32_bf16 v[100:103], v[162:165], v[202:205], v[100:103]
	v_mfma_f32_16x16x32_bf16 v[92:95], v[170:173], v[202:205], v[92:95]
	v_mfma_f32_16x16x32_bf16 v[116:119], v[162:165], v[210:213], v[116:119]
	v_mfma_f32_16x16x32_bf16 v[108:111], v[170:173], v[210:213], v[108:111]
	v_mfma_f32_16x16x32_bf16 v[124:127], v[162:165], v[218:221], v[124:127]
	v_mfma_f32_16x16x32_bf16 v[120:123], v[170:173], v[218:221], v[120:123]
	v_mfma_f32_16x16x32_bf16 v[80:83], v[166:169], v[182:185], v[80:83]
	v_mfma_f32_16x16x32_bf16 v[72:75], v[174:177], v[182:185], v[72:75]
	v_mfma_f32_16x16x32_bf16 v[100:103], v[166:169], v[206:209], v[100:103]
	v_mfma_f32_16x16x32_bf16 v[92:95], v[174:177], v[206:209], v[92:95]
	v_mfma_f32_16x16x32_bf16 v[116:119], v[166:169], v[214:217], v[116:119]
	v_mfma_f32_16x16x32_bf16 v[108:111], v[174:177], v[214:217], v[108:111]
	v_mfma_f32_16x16x32_bf16 v[124:127], v[166:169], v[222:225], v[124:127]
	v_mfma_f32_16x16x32_bf16 v[120:123], v[174:177], v[222:225], v[120:123]
	s_setprio 0
	s_barrier
	s_add_i32 s59, 0, 0x18000
	v_add_u32_e32 v144, s59, v193
	s_add_i32 s60, 0, 0x1c000
	ds_read_b128 v[128:131], v144
	ds_read_b128 v[132:135], v144 offset:1024
	ds_read_b128 v[154:157], v144 offset:2048
	ds_read_b128 v[158:161], v144 offset:3072
	v_add_u32_e32 v144, s60, v193
	ds_read_b128 v[162:165], v144
	ds_read_b128 v[166:169], v144 offset:1024
	ds_read_b128 v[170:173], v144 offset:2048
	ds_read_b128 v[174:177], v144 offset:3072
	s_add_u32 s10, s14, 0xb0000
	s_addc_u32 s11, s15, 0
	s_mov_b32 m0, s40
	v_lshl_add_u64 v[228:229], s[10:11], 0, v[136:137]
	ds_read_b128 v[178:181], v199 offset:32768
	ds_read_b128 v[182:185], v199 offset:33792
	ds_read_b128 v[202:205], v199 offset:34816
	ds_read_b128 v[206:209], v199 offset:35840
	ds_read_b128 v[210:213], v199 offset:36864
	ds_read_b128 v[214:217], v199 offset:37888
	ds_read_b128 v[218:221], v199 offset:38912
	ds_read_b128 v[222:225], v199 offset:39936
	global_load_lds_dwordx4 v[228:229], off
	v_lshl_add_u64 v[228:229], s[10:11], 0, v[140:141]
	s_mov_b32 m0, s41
	s_nop 0
	global_load_lds_dwordx4 v[228:229], off
	s_waitcnt vmcnt(8)
	s_waitcnt lgkmcnt(0)
	s_barrier
	s_setprio 1
	s_waitcnt lgkmcnt(0)
	v_mfma_f32_16x16x32_bf16 v[48:51], v[128:131], v[178:181], v[48:51]
	v_mfma_f32_16x16x32_bf16 v[28:31], v[154:157], v[178:181], v[28:31]
	v_mfma_f32_16x16x32_bf16 v[68:71], v[128:131], v[202:205], v[68:71]
	v_mfma_f32_16x16x32_bf16 v[52:55], v[154:157], v[202:205], v[52:55]
	v_mfma_f32_16x16x32_bf16 v[84:87], v[128:131], v[210:213], v[84:87]
	v_mfma_f32_16x16x32_bf16 v[76:79], v[154:157], v[210:213], v[76:79]
	v_mfma_f32_16x16x32_bf16 v[96:99], v[128:131], v[218:221], v[96:99]
	v_mfma_f32_16x16x32_bf16 v[88:91], v[154:157], v[218:221], v[88:91]
	v_mfma_f32_16x16x32_bf16 v[48:51], v[132:135], v[182:185], v[48:51]
	v_mfma_f32_16x16x32_bf16 v[28:31], v[158:161], v[182:185], v[28:31]
	v_mfma_f32_16x16x32_bf16 v[68:71], v[132:135], v[206:209], v[68:71]
	v_mfma_f32_16x16x32_bf16 v[52:55], v[158:161], v[206:209], v[52:55]
	v_mfma_f32_16x16x32_bf16 v[84:87], v[132:135], v[214:217], v[84:87]
	v_mfma_f32_16x16x32_bf16 v[76:79], v[158:161], v[214:217], v[76:79]
	v_mfma_f32_16x16x32_bf16 v[96:99], v[132:135], v[222:225], v[96:99]
	v_mfma_f32_16x16x32_bf16 v[88:91], v[158:161], v[222:225], v[88:91]
	v_mfma_f32_16x16x32_bf16 v[32:35], v[162:165], v[178:181], v[32:35]
	v_mfma_f32_16x16x32_bf16 v[16:19], v[170:173], v[178:181], v[16:19]
	v_mfma_f32_16x16x32_bf16 v[60:63], v[162:165], v[202:205], v[60:63]
	v_mfma_f32_16x16x32_bf16 v[40:43], v[170:173], v[202:205], v[40:43]
	v_mfma_f32_16x16x32_bf16 v[24:27], v[162:165], v[210:213], v[24:27]
	v_mfma_f32_16x16x32_bf16 v[4:7], v[170:173], v[210:213], v[4:7]
	v_mfma_f32_16x16x32_bf16 v[64:67], v[162:165], v[218:221], v[64:67]
	v_mfma_f32_16x16x32_bf16 v[44:47], v[170:173], v[218:221], v[44:47]
	v_mfma_f32_16x16x32_bf16 v[32:35], v[166:169], v[182:185], v[32:35]
	v_mfma_f32_16x16x32_bf16 v[16:19], v[174:177], v[182:185], v[16:19]
	v_mfma_f32_16x16x32_bf16 v[60:63], v[166:169], v[206:209], v[60:63]
	v_mfma_f32_16x16x32_bf16 v[40:43], v[174:177], v[206:209], v[40:43]
	v_mfma_f32_16x16x32_bf16 v[24:27], v[166:169], v[214:217], v[24:27]
	v_mfma_f32_16x16x32_bf16 v[4:7], v[174:177], v[214:217], v[4:7]
	v_mfma_f32_16x16x32_bf16 v[64:67], v[166:169], v[222:225], v[64:67]
	v_mfma_f32_16x16x32_bf16 v[44:47], v[174:177], v[222:225], v[44:47]
	s_setprio 0
	s_barrier
; #define PG8_STAGE(bufoff, gbase, voff) do { _Pragma("unroll") for (int _i = 0; _i < 2; ++_i) \
;         __builtin_amdgcn_global_load_lds((const unsigned*)((const char*)(gbase) + (voff)[_i]), (LAS unsigned*)(lds + (bufoff) + ldsw + _i * 8192), 16, 0, 0); } while (0)
; #define PG8_LDA(dst, b, h) do { _Pragma("unroll") for (int m = 0; m < 4; ++m) _Pragma("unroll") for (int k = 0; k < 2; ++k) dst[m][k] = *(const LAS bf16x8*)(lds + PG8_SA(b, h) + aoff + m * 2048 + k * 1024); } while (0)
; #define PG8_MMA(ai, bj, At, Bt) do { __builtin_amdgcn_s_setprio(1); _Pragma("unroll") for (int m = 0; m < 4; ++m) _Pragma("unroll") for (int n = 0; n < 2; ++n) _Pragma("unroll") for (int k = 0; k < 2; ++k) \
;         acc[ai][bj][m][n] = __builtin_amdgcn_mfma_f32_16x16x32_bf16(Bt[n][k], At[m][k], acc[ai][bj][m][n], 0, 0, 0); __builtin_amdgcn_s_setprio(0); } while (0)
; #define PG8_WAIT_V(n) asm volatile("s_waitcnt vmcnt(" #n ")" ::: "memory")
; #define PG8_WAIT_L(n) asm volatile("s_waitcnt lgkmcnt(" #n ")" ::: "memory")
; #define PG8_BAR __builtin_amdgcn_s_barrier()
; #define PG8_SCHED __builtin_amdgcn_sched_barrier(0)
; template <int MODE> DI void gemm_phase(LAS unsigned char* lds, const Gemm g, const StaticOrder& S, const Epi& E) {
;     ...
;             PG8_LDA(At, 1, 1); PG8_STAGE(PG8_SB(1, 0), b3, voffB); PG8_STAGE(PG8_SB(1, 1), b3 + hstepB, voffB); PG8_STAGE(PG8_SA(1, 0), a3, voffA);
;             PG8_WAIT_V(8); PG8_WAIT_L(0); PG8_BAR; PG8_MMA(1, 0, At, B0); PG8_MMA(1, 1, At, B1); PG8_BAR; PG8_SCHED;
;         }
;         if (wr == 0) PG8_BAR;
	s_add_i32 s10, s59, s29
	v_lshl_add_u64 v[186:187], v[186:187], 0, s[18:19]
	s_mov_b32 m0, s10
	ds_read_b128 v[178:181], v199 offset:49152
	ds_read_b128 v[182:185], v199 offset:50176
	ds_read_b128 v[202:205], v199 offset:51200
	ds_read_b128 v[206:209], v199 offset:52224
	ds_read_b128 v[210:213], v199 offset:53248
	ds_read_b128 v[214:217], v199 offset:54272
	ds_read_b128 v[218:221], v199 offset:55296
	ds_read_b128 v[222:225], v199 offset:56320
	global_load_lds_dwordx4 v[186:187], off
	s_add_i32 m0, s10, 0x2000
	s_add_u32 s10, s12, 0x2c080
	v_lshl_add_u64 v[186:187], v[188:189], 0, s[18:19]
	s_addc_u32 s11, s13, 0
	s_add_i32 s12, s60, s29
	global_load_lds_dwordx4 v[186:187], off
	v_lshl_add_u64 v[186:187], s[10:11], 0, v[138:139]
	s_mov_b32 m0, s12
	s_nop 0
	global_load_lds_dwordx4 v[186:187], off
	v_lshl_add_u64 v[186:187], s[10:11], 0, v[142:143]
	s_add_i32 m0, s12, 0x2000
	s_nop 0
	global_load_lds_dwordx4 v[186:187], off
	v_lshl_add_u64 v[186:187], v[194:195], 0, s[18:19]
	s_mov_b32 m0, s49
	s_nop 0
	global_load_lds_dwordx4 v[186:187], off
	v_lshl_add_u64 v[186:187], v[226:227], 0, s[18:19]
	s_mov_b32 m0, s50
	s_nop 0
	global_load_lds_dwordx4 v[186:187], off
	s_waitcnt vmcnt(8)
	s_waitcnt lgkmcnt(0)
	s_barrier
	s_setprio 1
	s_waitcnt lgkmcnt(0)
	v_mfma_f32_16x16x32_bf16 v[112:115], v[128:131], v[178:181], v[112:115]
	v_mfma_f32_16x16x32_bf16 v[104:107], v[154:157], v[178:181], v[104:107]
	v_mfma_f32_16x16x32_bf16 v[20:23], v[128:131], v[202:205], v[20:23]
	v_mfma_f32_16x16x32_bf16 v[0:3], v[154:157], v[202:205], v[0:3]
	v_mfma_f32_16x16x32_bf16 v[56:59], v[128:131], v[210:213], v[56:59]
	v_mfma_f32_16x16x32_bf16 v[36:39], v[154:157], v[210:213], v[36:39]
	v_mfma_f32_16x16x32_bf16 v[8:11], v[128:131], v[218:221], v[8:11]
	v_mfma_f32_16x16x32_bf16 v[12:15], v[154:157], v[218:221], v[12:15]
	v_mfma_f32_16x16x32_bf16 v[112:115], v[132:135], v[182:185], v[112:115]
	v_mfma_f32_16x16x32_bf16 v[104:107], v[158:161], v[182:185], v[104:107]
	v_mfma_f32_16x16x32_bf16 v[20:23], v[132:135], v[206:209], v[20:23]
	v_mfma_f32_16x16x32_bf16 v[0:3], v[158:161], v[206:209], v[0:3]
	v_mfma_f32_16x16x32_bf16 v[56:59], v[132:135], v[214:217], v[56:59]
	v_mfma_f32_16x16x32_bf16 v[36:39], v[158:161], v[214:217], v[36:39]
	v_mfma_f32_16x16x32_bf16 v[8:11], v[132:135], v[222:225], v[8:11]
	v_mfma_f32_16x16x32_bf16 v[12:15], v[158:161], v[222:225], v[12:15]
	v_mfma_f32_16x16x32_bf16 v[80:83], v[162:165], v[178:181], v[80:83]
	v_mfma_f32_16x16x32_bf16 v[72:75], v[170:173], v[178:181], v[72:75]
	v_mfma_f32_16x16x32_bf16 v[100:103], v[162:165], v[202:205], v[100:103]
	v_mfma_f32_16x16x32_bf16 v[92:95], v[170:173], v[202:205], v[92:95]
	v_mfma_f32_16x16x32_bf16 v[116:119], v[162:165], v[210:213], v[116:119]
	v_mfma_f32_16x16x32_bf16 v[108:111], v[170:173], v[210:213], v[108:111]
	v_mfma_f32_16x16x32_bf16 v[124:127], v[162:165], v[218:221], v[124:127]
	v_mfma_f32_16x16x32_bf16 v[120:123], v[170:173], v[218:221], v[120:123]
	v_mfma_f32_16x16x32_bf16 v[80:83], v[166:169], v[182:185], v[80:83]
	v_mfma_f32_16x16x32_bf16 v[72:75], v[174:177], v[182:185], v[72:75]
	v_mfma_f32_16x16x32_bf16 v[100:103], v[166:169], v[206:209], v[100:103]
	v_mfma_f32_16x16x32_bf16 v[92:95], v[174:177], v[206:209], v[92:95]
	v_mfma_f32_16x16x32_bf16 v[116:119], v[166:169], v[214:217], v[116:119]
	v_mfma_f32_16x16x32_bf16 v[108:111], v[174:177], v[214:217], v[108:111]
	v_mfma_f32_16x16x32_bf16 v[124:127], v[166:169], v[222:225], v[124:127]
	v_mfma_f32_16x16x32_bf16 v[120:123], v[174:177], v[222:225], v[120:123]
	s_setprio 0
	s_barrier
	s_add_i32 s58, s58, 2
	s_add_u32 s38, s38, 0x100
	s_addc_u32 s39, s39, 0
	s_cmp_gt_u32 s58, 41
	s_mov_b64 s[10:11], s[8:9]
	s_cbranch_scc0 .LBB0_665
	s_and_b64 vcc, exec, s[20:21]
	s_cbranch_vccz .LBB0_668
	s_barrier

; #define PG8_STAGE(bufoff, gbase, voff) do { _Pragma("unroll") for (int _i = 0; _i < 2; ++_i) \
;         __builtin_amdgcn_global_load_lds((const unsigned*)((const char*)(gbase) + (voff)[_i]), (LAS unsigned*)(lds + (bufoff) + ldsw + _i * 8192), 16, 0, 0); } while (0)
; #define PG8_LDA(dst, b, h) do { _Pragma("unroll") for (int m = 0; m < 4; ++m) _Pragma("unroll") for (int k = 0; k < 2; ++k) dst[m][k] = *(const LAS bf16x8*)(lds + PG8_SA(b, h) + aoff + m * 2048 + k * 1024); } while (0)
; #define PG8_LDB(dst, b, h) do { _Pragma("unroll") for (int n = 0; n < 2; ++n) _Pragma("unroll") for (int k = 0; k < 2; ++k) dst[n][k] = *(const LAS bf16x8*)(lds + PG8_SB(b, h) + boff + n * 2048 + k * 1024); } while (0)
; #define PG8_MMA(ai, bj, At, Bt) do { __builtin_amdgcn_s_setprio(1); _Pragma("unroll") for (int m = 0; m < 4; ++m) _Pragma("unroll") for (int n = 0; n < 2; ++n) _Pragma("unroll") for (int k = 0; k < 2; ++k) \
;         acc[ai][bj][m][n] = __builtin_amdgcn_mfma_f32_16x16x32_bf16(Bt[n][k], At[m][k], acc[ai][bj][m][n], 0, 0, 0); __builtin_amdgcn_s_setprio(0); } while (0)
; #define PG8_WAIT_V(n) asm volatile("s_waitcnt vmcnt(" #n ")" ::: "memory")
; #define PG8_WAIT_L(n) asm volatile("s_waitcnt lgkmcnt(" #n ")" ::: "memory")
; #define PG8_BAR __builtin_amdgcn_s_barrier()
; #define PG8_SCHED __builtin_amdgcn_sched_barrier(0)
; template <int MODE> DI void gemm_phase(LAS unsigned char* lds, const Gemm g, const StaticOrder& S, const Epi& E) {
;     ...
;         for (int t = 0; t < nt; t += 2) {
;             const bool last = (t == nt - 2);
;             const char* a1 = cA + (size_t)(t + 1) * kstep;
;             const char* a2 = last ? nA : cA + (size_t)(t + 2) * kstep; const char* b2 = last ? nB : cB + (size_t)(t + 2) * kstep;
;             const char* a3 = a2 + kstep; const char* b3 = b2 + kstep;
;             PG8_LDB(B0, 0, 0); PG8_LDB(B1, 0, 1); PG8_SCHED; PG8_LDA(At, 0, 0); PG8_STAGE(PG8_SA(1, 1), a1 + hstepA, voffA);
;             PG8_WAIT_V(8); PG8_WAIT_L(0); PG8_BAR; PG8_MMA(0, 0, At, B0); PG8_MMA(0, 1, At, B1); PG8_BAR; PG8_SCHED;
;             PG8_LDA(At, 0, 1); PG8_STAGE(PG8_SB(0, 0), b2, voffB); PG8_STAGE(PG8_SB(0, 1), b2 + hstepB, voffB); PG8_STAGE(PG8_SA(0, 0), a2, voffA);
;             PG8_WAIT_V(8); PG8_WAIT_L(0); PG8_BAR; PG8_MMA(1, 0, At, B0); PG8_MMA(1, 1, At, B1); PG8_BAR; PG8_SCHED;
.LBB0_756:
	ds_read_b128 v[166:169], v161
	ds_read_b128 v[170:173], v161 offset:1024
	ds_read_b128 v[174:177], v161 offset:2048
	ds_read_b128 v[178:181], v161 offset:3072
	ds_read_b128 v[182:185], v162
	ds_read_b128 v[190:193], v162 offset:1024
	ds_read_b128 v[194:197], v162 offset:2048
	ds_read_b128 v[198:201], v162 offset:3072
	s_add_u32 s22, s20, 0xfffc0080
	s_addc_u32 s23, s21, -1
	s_cmp_eq_u32 s44, 12
	s_cselect_b32 s25, s13, s23
	s_cselect_b32 s24, s40, s22
	s_cselect_b32 s23, s11, s43
	s_cselect_b32 s22, s41, s42
	v_lshl_add_u64 v[156:157], s[20:21], 0, v[146:147]
	s_add_i32 m0, s19, 0xc000
	ds_read_b128 v[202:205], v163
	ds_read_b128 v[206:209], v163 offset:1024
	ds_read_b128 v[210:213], v163 offset:2048
	ds_read_b128 v[214:217], v163 offset:3072
	ds_read_b128 v[218:221], v163 offset:4096
	ds_read_b128 v[222:225], v163 offset:5120
	ds_read_b128 v[226:229], v163 offset:6144
	ds_read_b128 v[230:233], v163 offset:7168
	global_load_lds_dwordx4 v[156:157], off
	v_lshl_add_u64 v[156:157], s[20:21], 0, v[148:149]
	s_add_i32 m0, s19, 0xe000
	s_nop 0
	global_load_lds_dwordx4 v[156:157], off
	s_waitcnt vmcnt(8)
	s_waitcnt lgkmcnt(0)
	s_barrier
	s_setprio 1
	s_waitcnt lgkmcnt(0)
	v_mfma_f32_16x16x32_bf16 v[124:127], v[166:169], v[202:205], v[124:127]
	v_mfma_f32_16x16x32_bf16 v[120:123], v[174:177], v[202:205], v[120:123]
	v_mfma_f32_16x16x32_bf16 v[116:119], v[166:169], v[210:213], v[116:119]
	v_mfma_f32_16x16x32_bf16 v[108:111], v[174:177], v[210:213], v[108:111]
	v_mfma_f32_16x16x32_bf16 v[100:103], v[166:169], v[218:221], v[100:103]
	v_mfma_f32_16x16x32_bf16 v[92:95], v[174:177], v[218:221], v[92:95]
	v_mfma_f32_16x16x32_bf16 v[84:87], v[166:169], v[226:229], v[84:87]
	v_mfma_f32_16x16x32_bf16 v[76:79], v[174:177], v[226:229], v[76:79]
	v_mfma_f32_16x16x32_bf16 v[124:127], v[170:173], v[206:209], v[124:127]
	v_mfma_f32_16x16x32_bf16 v[120:123], v[178:181], v[206:209], v[120:123]
	v_mfma_f32_16x16x32_bf16 v[116:119], v[170:173], v[214:217], v[116:119]
	v_mfma_f32_16x16x32_bf16 v[108:111], v[178:181], v[214:217], v[108:111]
	v_mfma_f32_16x16x32_bf16 v[100:103], v[170:173], v[222:225], v[100:103]
	v_mfma_f32_16x16x32_bf16 v[92:95], v[178:181], v[222:225], v[92:95]
	v_mfma_f32_16x16x32_bf16 v[84:87], v[170:173], v[230:233], v[84:87]
	v_mfma_f32_16x16x32_bf16 v[76:79], v[178:181], v[230:233], v[76:79]
	v_mfma_f32_16x16x32_bf16 v[112:115], v[182:185], v[202:205], v[112:115]
	v_mfma_f32_16x16x32_bf16 v[104:107], v[194:197], v[202:205], v[104:107]
	v_mfma_f32_16x16x32_bf16 v[96:99], v[182:185], v[210:213], v[96:99]
	v_mfma_f32_16x16x32_bf16 v[88:91], v[194:197], v[210:213], v[88:91]
	v_mfma_f32_16x16x32_bf16 v[80:83], v[182:185], v[218:221], v[80:83]
	v_mfma_f32_16x16x32_bf16 v[72:75], v[194:197], v[218:221], v[72:75]
	v_mfma_f32_16x16x32_bf16 v[68:71], v[182:185], v[226:229], v[68:71]
	v_mfma_f32_16x16x32_bf16 v[64:67], v[194:197], v[226:229], v[64:67]
	v_mfma_f32_16x16x32_bf16 v[112:115], v[190:193], v[206:209], v[112:115]
	v_mfma_f32_16x16x32_bf16 v[104:107], v[198:201], v[206:209], v[104:107]
	v_mfma_f32_16x16x32_bf16 v[96:99], v[190:193], v[214:217], v[96:99]
	v_mfma_f32_16x16x32_bf16 v[88:91], v[198:201], v[214:217], v[88:91]
	v_mfma_f32_16x16x32_bf16 v[80:83], v[190:193], v[222:225], v[80:83]
	v_mfma_f32_16x16x32_bf16 v[72:75], v[198:201], v[222:225], v[72:75]
	v_mfma_f32_16x16x32_bf16 v[68:71], v[190:193], v[230:233], v[68:71]
	v_mfma_f32_16x16x32_bf16 v[64:67], v[198:201], v[230:233], v[64:67]
	s_setprio 0
	s_barrier
	s_add_i32 s45, s35, s26
	v_lshl_add_u64 v[156:157], s[22:23], 0, v[132:133]
	s_mov_b32 m0, s45
	ds_read_b128 v[202:205], v163 offset:16384
	ds_read_b128 v[206:209], v163 offset:17408
	ds_read_b128 v[210:213], v163 offset:18432
	ds_read_b128 v[214:217], v163 offset:19456
	ds_read_b128 v[218:221], v163 offset:20480
	ds_read_b128 v[222:225], v163 offset:21504
	ds_read_b128 v[226:229], v163 offset:22528
	ds_read_b128 v[230:233], v163 offset:23552
	global_load_lds_dwordx4 v[156:157], off
	s_add_i32 m0, s45, 0x2000
	s_add_u32 s46, s22, 0x10000
	v_lshl_add_u64 v[186:187], s[22:23], 0, v[128:129]
	s_addc_u32 s47, s23, 0
	s_add_i32 s45, s36, s26
	global_load_lds_dwordx4 v[186:187], off
	v_lshl_add_u64 v[188:189], s[46:47], 0, v[132:133]
	s_mov_b32 m0, s45
	v_lshl_add_u64 v[234:235], s[24:25], 0, v[130:131]
	global_load_lds_dwordx4 v[188:189], off
	v_lshl_add_u64 v[188:189], s[46:47], 0, v[128:129]
	s_add_i32 m0, s45, 0x2000
	s_nop 0
	global_load_lds_dwordx4 v[188:189], off
	v_lshl_add_u64 v[188:189], s[24:25], 0, v[134:135]
	s_mov_b32 m0, s19
	s_nop 0
	global_load_lds_dwordx4 v[188:189], off
	s_mov_b32 m0, s28
	s_nop 0
	global_load_lds_dwordx4 v[234:235], off
	s_waitcnt vmcnt(8)
	s_waitcnt lgkmcnt(0)
	s_barrier
; #define PG8_STAGE(bufoff, gbase, voff) do { _Pragma("unroll") for (int _i = 0; _i < 2; ++_i) \
;         __builtin_amdgcn_global_load_lds((const unsigned*)((const char*)(gbase) + (voff)[_i]), (LAS unsigned*)(lds + (bufoff) + ldsw + _i * 8192), 16, 0, 0); } while (0)
; #define PG8_LDA(dst, b, h) do { _Pragma("unroll") for (int m = 0; m < 4; ++m) _Pragma("unroll") for (int k = 0; k < 2; ++k) dst[m][k] = *(const LAS bf16x8*)(lds + PG8_SA(b, h) + aoff + m * 2048 + k * 1024); } while (0)
; #define PG8_LDB(dst, b, h) do { _Pragma("unroll") for (int n = 0; n < 2; ++n) _Pragma("unroll") for (int k = 0; k < 2; ++k) dst[n][k] = *(const LAS bf16x8*)(lds + PG8_SB(b, h) + boff + n * 2048 + k * 1024); } while (0)
; #define PG8_MMA(ai, bj, At, Bt) do { __builtin_amdgcn_s_setprio(1); _Pragma("unroll") for (int m = 0; m < 4; ++m) _Pragma("unroll") for (int n = 0; n < 2; ++n) _Pragma("unroll") for (int k = 0; k < 2; ++k) \
;         acc[ai][bj][m][n] = __builtin_amdgcn_mfma_f32_16x16x32_bf16(Bt[n][k], At[m][k], acc[ai][bj][m][n], 0, 0, 0); __builtin_amdgcn_s_setprio(0); } while (0)
; #define PG8_WAIT_V(n) asm volatile("s_waitcnt vmcnt(" #n ")" ::: "memory")
; #define PG8_WAIT_L(n) asm volatile("s_waitcnt lgkmcnt(" #n ")" ::: "memory")
; #define PG8_BAR __builtin_amdgcn_s_barrier()
; #define PG8_SCHED __builtin_amdgcn_sched_barrier(0)
; template <int MODE> DI void gemm_phase(LAS unsigned char* lds, const Gemm g, const StaticOrder& S, const Epi& E) {
;     ...
;             PG8_WAIT_V(8); PG8_WAIT_L(0); PG8_BAR; PG8_MMA(1, 0, At, B0); PG8_MMA(1, 1, At, B1); PG8_BAR; PG8_SCHED;
;             PG8_LDB(B0, 1, 0); PG8_LDB(B1, 1, 1); PG8_SCHED; PG8_LDA(At, 1, 0); PG8_STAGE(PG8_SA(0, 1), a2 + hstepA, voffA);
;             PG8_WAIT_V(8); PG8_WAIT_L(0); PG8_BAR; PG8_MMA(0, 0, At, B0); PG8_MMA(0, 1, At, B1); PG8_BAR; PG8_SCHED;
;             PG8_LDA(At, 1, 1); PG8_STAGE(PG8_SB(1, 0), b3, voffB); PG8_STAGE(PG8_SB(1, 1), b3 + hstepB, voffB); PG8_STAGE(PG8_SA(1, 0), a3, voffA);
;             PG8_WAIT_V(8); PG8_WAIT_L(0); PG8_BAR; PG8_MMA(1, 0, At, B0); PG8_MMA(1, 1, At, B1); PG8_BAR; PG8_SCHED;
	s_setprio 1
	s_waitcnt lgkmcnt(0)
	v_mfma_f32_16x16x32_bf16 v[60:63], v[166:169], v[202:205], v[60:63]
	v_mfma_f32_16x16x32_bf16 v[56:59], v[174:177], v[202:205], v[56:59]
	v_mfma_f32_16x16x32_bf16 v[52:55], v[166:169], v[210:213], v[52:55]
	v_mfma_f32_16x16x32_bf16 v[44:47], v[174:177], v[210:213], v[44:47]
	v_mfma_f32_16x16x32_bf16 v[36:39], v[166:169], v[218:221], v[36:39]
	v_mfma_f32_16x16x32_bf16 v[28:31], v[174:177], v[218:221], v[28:31]
	v_mfma_f32_16x16x32_bf16 v[20:23], v[166:169], v[226:229], v[20:23]
	v_mfma_f32_16x16x32_bf16 v[12:15], v[174:177], v[226:229], v[12:15]
	v_mfma_f32_16x16x32_bf16 v[60:63], v[170:173], v[206:209], v[60:63]
	v_mfma_f32_16x16x32_bf16 v[56:59], v[178:181], v[206:209], v[56:59]
	v_mfma_f32_16x16x32_bf16 v[52:55], v[170:173], v[214:217], v[52:55]
	v_mfma_f32_16x16x32_bf16 v[44:47], v[178:181], v[214:217], v[44:47]
	v_mfma_f32_16x16x32_bf16 v[36:39], v[170:173], v[222:225], v[36:39]
	v_mfma_f32_16x16x32_bf16 v[28:31], v[178:181], v[222:225], v[28:31]
	v_mfma_f32_16x16x32_bf16 v[20:23], v[170:173], v[230:233], v[20:23]
	v_mfma_f32_16x16x32_bf16 v[12:15], v[178:181], v[230:233], v[12:15]
	v_mfma_f32_16x16x32_bf16 v[48:51], v[182:185], v[202:205], v[48:51]
	v_mfma_f32_16x16x32_bf16 v[40:43], v[194:197], v[202:205], v[40:43]
	v_mfma_f32_16x16x32_bf16 v[32:35], v[182:185], v[210:213], v[32:35]
	v_mfma_f32_16x16x32_bf16 v[24:27], v[194:197], v[210:213], v[24:27]
	v_mfma_f32_16x16x32_bf16 v[16:19], v[182:185], v[218:221], v[16:19]
	v_mfma_f32_16x16x32_bf16 v[8:11], v[194:197], v[218:221], v[8:11]
	v_mfma_f32_16x16x32_bf16 v[4:7], v[182:185], v[226:229], v[4:7]
	v_mfma_f32_16x16x32_bf16 v[0:3], v[194:197], v[226:229], v[0:3]
	v_mfma_f32_16x16x32_bf16 v[48:51], v[190:193], v[206:209], v[48:51]
	v_mfma_f32_16x16x32_bf16 v[40:43], v[198:201], v[206:209], v[40:43]
	v_mfma_f32_16x16x32_bf16 v[32:35], v[190:193], v[214:217], v[32:35]
	v_mfma_f32_16x16x32_bf16 v[24:27], v[198:201], v[214:217], v[24:27]
	v_mfma_f32_16x16x32_bf16 v[16:19], v[190:193], v[222:225], v[16:19]
	v_mfma_f32_16x16x32_bf16 v[8:11], v[198:201], v[222:225], v[8:11]
	v_mfma_f32_16x16x32_bf16 v[4:7], v[190:193], v[230:233], v[4:7]
	v_mfma_f32_16x16x32_bf16 v[0:3], v[198:201], v[230:233], v[0:3]
	s_setprio 0
	s_barrier
	s_add_i32 s45, 0, 0x18000
	v_add_u32_e32 v154, s45, v159
	s_add_i32 s46, 0, 0x1c000
	ds_read_b128 v[166:169], v154
	ds_read_b128 v[170:173], v154 offset:1024
	ds_read_b128 v[174:177], v154 offset:2048
	ds_read_b128 v[178:181], v154 offset:3072
	v_add_u32_e32 v154, s46, v159
	ds_read_b128 v[182:185], v154
	ds_read_b128 v[190:193], v154 offset:1024
	ds_read_b128 v[194:197], v154 offset:2048
	ds_read_b128 v[198:201], v154 offset:3072
	s_add_u32 s24, s24, 0x40000
	s_addc_u32 s25, s25, 0
	s_mov_b32 m0, s29
	v_lshl_add_u64 v[236:237], s[24:25], 0, v[134:135]
	ds_read_b128 v[202:205], v163 offset:32768
	ds_read_b128 v[206:209], v163 offset:33792
	ds_read_b128 v[210:213], v163 offset:34816
	ds_read_b128 v[214:217], v163 offset:35840
	ds_read_b128 v[218:221], v163 offset:36864
	ds_read_b128 v[222:225], v163 offset:37888
	ds_read_b128 v[226:229], v163 offset:38912
	ds_read_b128 v[230:233], v163 offset:39936
	global_load_lds_dwordx4 v[236:237], off
	v_lshl_add_u64 v[236:237], s[24:25], 0, v[130:131]
	s_mov_b32 m0, s30
	s_nop 0
	global_load_lds_dwordx4 v[236:237], off
	s_waitcnt vmcnt(8)
	s_waitcnt lgkmcnt(0)
	s_barrier
	s_setprio 1
	s_waitcnt lgkmcnt(0)
	v_mfma_f32_16x16x32_bf16 v[124:127], v[166:169], v[202:205], v[124:127]
	v_mfma_f32_16x16x32_bf16 v[120:123], v[174:177], v[202:205], v[120:123]
	v_mfma_f32_16x16x32_bf16 v[116:119], v[166:169], v[210:213], v[116:119]
	v_mfma_f32_16x16x32_bf16 v[108:111], v[174:177], v[210:213], v[108:111]
	v_mfma_f32_16x16x32_bf16 v[100:103], v[166:169], v[218:221], v[100:103]
	v_mfma_f32_16x16x32_bf16 v[92:95], v[174:177], v[218:221], v[92:95]
	v_mfma_f32_16x16x32_bf16 v[84:87], v[166:169], v[226:229], v[84:87]
	v_mfma_f32_16x16x32_bf16 v[76:79], v[174:177], v[226:229], v[76:79]
	v_mfma_f32_16x16x32_bf16 v[124:127], v[170:173], v[206:209], v[124:127]
	v_mfma_f32_16x16x32_bf16 v[120:123], v[178:181], v[206:209], v[120:123]
	v_mfma_f32_16x16x32_bf16 v[116:119], v[170:173], v[214:217], v[116:119]
	v_mfma_f32_16x16x32_bf16 v[108:111], v[178:181], v[214:217], v[108:111]
	v_mfma_f32_16x16x32_bf16 v[100:103], v[170:173], v[222:225], v[100:103]
	v_mfma_f32_16x16x32_bf16 v[92:95], v[178:181], v[222:225], v[92:95]
	v_mfma_f32_16x16x32_bf16 v[84:87], v[170:173], v[230:233], v[84:87]
	v_mfma_f32_16x16x32_bf16 v[76:79], v[178:181], v[230:233], v[76:79]
	v_mfma_f32_16x16x32_bf16 v[112:115], v[182:185], v[202:205], v[112:115]
	v_mfma_f32_16x16x32_bf16 v[104:107], v[194:197], v[202:205], v[104:107]
	v_mfma_f32_16x16x32_bf16 v[96:99], v[182:185], v[210:213], v[96:99]
	v_mfma_f32_16x16x32_bf16 v[88:91], v[194:197], v[210:213], v[88:91]
	v_mfma_f32_16x16x32_bf16 v[80:83], v[182:185], v[218:221], v[80:83]
	v_mfma_f32_16x16x32_bf16 v[72:75], v[194:197], v[218:221], v[72:75]
	v_mfma_f32_16x16x32_bf16 v[68:71], v[182:185], v[226:229], v[68:71]
	v_mfma_f32_16x16x32_bf16 v[64:67], v[194:197], v[226:229], v[64:67]
	v_mfma_f32_16x16x32_bf16 v[112:115], v[190:193], v[206:209], v[112:115]
	v_mfma_f32_16x16x32_bf16 v[104:107], v[198:201], v[206:209], v[104:107]
	v_mfma_f32_16x16x32_bf16 v[96:99], v[190:193], v[214:217], v[96:99]
	v_mfma_f32_16x16x32_bf16 v[88:91], v[198:201], v[214:217], v[88:91]
	v_mfma_f32_16x16x32_bf16 v[80:83], v[190:193], v[222:225], v[80:83]
	v_mfma_f32_16x16x32_bf16 v[72:75], v[198:201], v[222:225], v[72:75]
	v_mfma_f32_16x16x32_bf16 v[68:71], v[190:193], v[230:233], v[68:71]
	v_mfma_f32_16x16x32_bf16 v[64:67], v[198:201], v[230:233], v[64:67]
	s_setprio 0
	s_barrier
; #define PG8_STAGE(bufoff, gbase, voff) do { _Pragma("unroll") for (int _i = 0; _i < 2; ++_i) \
;         __builtin_amdgcn_global_load_lds((const unsigned*)((const char*)(gbase) + (voff)[_i]), (LAS unsigned*)(lds + (bufoff) + ldsw + _i * 8192), 16, 0, 0); } while (0)
; #define PG8_LDA(dst, b, h) do { _Pragma("unroll") for (int m = 0; m < 4; ++m) _Pragma("unroll") for (int k = 0; k < 2; ++k) dst[m][k] = *(const LAS bf16x8*)(lds + PG8_SA(b, h) + aoff + m * 2048 + k * 1024); } while (0)
; #define PG8_MMA(ai, bj, At, Bt) do { __builtin_amdgcn_s_setprio(1); _Pragma("unroll") for (int m = 0; m < 4; ++m) _Pragma("unroll") for (int n = 0; n < 2; ++n) _Pragma("unroll") for (int k = 0; k < 2; ++k) \
;         acc[ai][bj][m][n] = __builtin_amdgcn_mfma_f32_16x16x32_bf16(Bt[n][k], At[m][k], acc[ai][bj][m][n], 0, 0, 0); __builtin_amdgcn_s_setprio(0); } while (0)
; #define PG8_WAIT_V(n) asm volatile("s_waitcnt vmcnt(" #n ")" ::: "memory")
; #define PG8_WAIT_L(n) asm volatile("s_waitcnt lgkmcnt(" #n ")" ::: "memory")
; #define PG8_BAR __builtin_amdgcn_s_barrier()
; #define PG8_SCHED __builtin_amdgcn_sched_barrier(0)
; template <int MODE> DI void gemm_phase(LAS unsigned char* lds, const Gemm g, const StaticOrder& S, const Epi& E) {
;     ...
;             PG8_LDA(At, 1, 1); PG8_STAGE(PG8_SB(1, 0), b3, voffB); PG8_STAGE(PG8_SB(1, 1), b3 + hstepB, voffB); PG8_STAGE(PG8_SA(1, 0), a3, voffA);
;             PG8_WAIT_V(8); PG8_WAIT_L(0); PG8_BAR; PG8_MMA(1, 0, At, B0); PG8_MMA(1, 1, At, B1); PG8_BAR; PG8_SCHED;
;         }
;         if (wr == 0) PG8_BAR;
	s_add_i32 s24, s45, s26
	v_lshl_add_u64 v[156:157], v[156:157], 0, s[6:7]
	s_mov_b32 m0, s24
	ds_read_b128 v[202:205], v163 offset:49152
	ds_read_b128 v[206:209], v163 offset:50176
	ds_read_b128 v[210:213], v163 offset:51200
	ds_read_b128 v[214:217], v163 offset:52224
	ds_read_b128 v[218:221], v163 offset:53248
	ds_read_b128 v[222:225], v163 offset:54272
	ds_read_b128 v[226:229], v163 offset:55296
	ds_read_b128 v[230:233], v163 offset:56320
	global_load_lds_dwordx4 v[156:157], off
	s_add_i32 m0, s24, 0x2000
	s_add_u32 s22, s22, 0x10080
	v_lshl_add_u64 v[156:157], v[186:187], 0, s[6:7]
	s_addc_u32 s23, s23, 0
	s_add_i32 s24, s46, s26
	global_load_lds_dwordx4 v[156:157], off
	v_lshl_add_u64 v[156:157], s[22:23], 0, v[132:133]
	s_mov_b32 m0, s24
	s_nop 0
	global_load_lds_dwordx4 v[156:157], off
	v_lshl_add_u64 v[156:157], s[22:23], 0, v[128:129]
	s_add_i32 m0, s24, 0x2000
	s_nop 0
	global_load_lds_dwordx4 v[156:157], off
	v_lshl_add_u64 v[156:157], v[188:189], 0, s[6:7]
	s_mov_b32 m0, s31
	s_nop 0
	global_load_lds_dwordx4 v[156:157], off
	v_lshl_add_u64 v[156:157], v[234:235], 0, s[6:7]
	s_mov_b32 m0, s33
	s_nop 0
	global_load_lds_dwordx4 v[156:157], off
	s_waitcnt vmcnt(8)
	s_waitcnt lgkmcnt(0)
	s_barrier
	s_setprio 1
	s_waitcnt lgkmcnt(0)
	v_mfma_f32_16x16x32_bf16 v[60:63], v[166:169], v[202:205], v[60:63]
	v_mfma_f32_16x16x32_bf16 v[56:59], v[174:177], v[202:205], v[56:59]
	v_mfma_f32_16x16x32_bf16 v[52:55], v[166:169], v[210:213], v[52:55]
	v_mfma_f32_16x16x32_bf16 v[44:47], v[174:177], v[210:213], v[44:47]
	v_mfma_f32_16x16x32_bf16 v[36:39], v[166:169], v[218:221], v[36:39]
	v_mfma_f32_16x16x32_bf16 v[28:31], v[174:177], v[218:221], v[28:31]
	v_mfma_f32_16x16x32_bf16 v[20:23], v[166:169], v[226:229], v[20:23]
	v_mfma_f32_16x16x32_bf16 v[12:15], v[174:177], v[226:229], v[12:15]
	v_mfma_f32_16x16x32_bf16 v[60:63], v[170:173], v[206:209], v[60:63]
	v_mfma_f32_16x16x32_bf16 v[56:59], v[178:181], v[206:209], v[56:59]
	v_mfma_f32_16x16x32_bf16 v[52:55], v[170:173], v[214:217], v[52:55]
	v_mfma_f32_16x16x32_bf16 v[44:47], v[178:181], v[214:217], v[44:47]
	v_mfma_f32_16x16x32_bf16 v[36:39], v[170:173], v[222:225], v[36:39]
	v_mfma_f32_16x16x32_bf16 v[28:31], v[178:181], v[222:225], v[28:31]
	v_mfma_f32_16x16x32_bf16 v[20:23], v[170:173], v[230:233], v[20:23]
	v_mfma_f32_16x16x32_bf16 v[12:15], v[178:181], v[230:233], v[12:15]
	v_mfma_f32_16x16x32_bf16 v[48:51], v[182:185], v[202:205], v[48:51]
	v_mfma_f32_16x16x32_bf16 v[40:43], v[194:197], v[202:205], v[40:43]
	v_mfma_f32_16x16x32_bf16 v[32:35], v[182:185], v[210:213], v[32:35]
	v_mfma_f32_16x16x32_bf16 v[24:27], v[194:197], v[210:213], v[24:27]
	v_mfma_f32_16x16x32_bf16 v[16:19], v[182:185], v[218:221], v[16:19]
	v_mfma_f32_16x16x32_bf16 v[8:11], v[194:197], v[218:221], v[8:11]
	v_mfma_f32_16x16x32_bf16 v[4:7], v[182:185], v[226:229], v[4:7]
	v_mfma_f32_16x16x32_bf16 v[0:3], v[194:197], v[226:229], v[0:3]
	v_mfma_f32_16x16x32_bf16 v[48:51], v[190:193], v[206:209], v[48:51]
	v_mfma_f32_16x16x32_bf16 v[40:43], v[198:201], v[206:209], v[40:43]
	v_mfma_f32_16x16x32_bf16 v[32:35], v[190:193], v[214:217], v[32:35]
	v_mfma_f32_16x16x32_bf16 v[24:27], v[198:201], v[214:217], v[24:27]
	v_mfma_f32_16x16x32_bf16 v[16:19], v[190:193], v[222:225], v[16:19]
	v_mfma_f32_16x16x32_bf16 v[8:11], v[198:201], v[222:225], v[8:11]
	v_mfma_f32_16x16x32_bf16 v[4:7], v[190:193], v[230:233], v[4:7]
	v_mfma_f32_16x16x32_bf16 v[0:3], v[198:201], v[230:233], v[0:3]
	s_setprio 0
	s_barrier
	s_add_i32 s44, s44, 2
	s_add_u32 s20, s20, 0x100
	s_addc_u32 s21, s21, 0
	s_add_u32 s42, s42, 0x100
	s_addc_u32 s43, s43, 0
	s_cmp_gt_u32 s44, 13
	s_cbranch_scc0 .LBB0_756
	s_and_b64 vcc, exec, s[8:9]
	s_cbranch_vccz .LBB0_759
	s_barrier

; #define PG8_STAGE(bufoff, gbase, voff) do { _Pragma("unroll") for (int _i = 0; _i < 2; ++_i) \
;         __builtin_amdgcn_global_load_lds((const unsigned*)((const char*)(gbase) + (voff)[_i]), (LAS unsigned*)(lds + (bufoff) + ldsw + _i * 8192), 16, 0, 0); } while (0)
; #define PG8_LDA(dst, b, h) do { _Pragma("unroll") for (int m = 0; m < 4; ++m) _Pragma("unroll") for (int k = 0; k < 2; ++k) dst[m][k] = *(const LAS bf16x8*)(lds + PG8_SA(b, h) + aoff + m * 2048 + k * 1024); } while (0)
; #define PG8_LDB(dst, b, h) do { _Pragma("unroll") for (int n = 0; n < 2; ++n) _Pragma("unroll") for (int k = 0; k < 2; ++k) dst[n][k] = *(const LAS bf16x8*)(lds + PG8_SB(b, h) + boff + n * 2048 + k * 1024); } while (0)
; #define PG8_MMA(ai, bj, At, Bt) do { __builtin_amdgcn_s_setprio(1); _Pragma("unroll") for (int m = 0; m < 4; ++m) _Pragma("unroll") for (int n = 0; n < 2; ++n) _Pragma("unroll") for (int k = 0; k < 2; ++k) \
;         acc[ai][bj][m][n] = __builtin_amdgcn_mfma_f32_16x16x32_bf16(Bt[n][k], At[m][k], acc[ai][bj][m][n], 0, 0, 0); __builtin_amdgcn_s_setprio(0); } while (0)
; #define PG8_WAIT_V(n) asm volatile("s_waitcnt vmcnt(" #n ")" ::: "memory")
; #define PG8_WAIT_L(n) asm volatile("s_waitcnt lgkmcnt(" #n ")" ::: "memory")
; #define PG8_BAR __builtin_amdgcn_s_barrier()
; #define PG8_SCHED __builtin_amdgcn_sched_barrier(0)
; template <int MODE> DI void gemm_phase(LAS unsigned char* lds, const Gemm g, const StaticOrder& S, const Epi& E) {
;     ...
;         for (int t = 0; t < nt; t += 2) {
;             const bool last = (t == nt - 2);
;             const char* a1 = cA + (size_t)(t + 1) * kstep;
;             const char* a2 = last ? nA : cA + (size_t)(t + 2) * kstep; const char* b2 = last ? nB : cB + (size_t)(t + 2) * kstep;
;             const char* a3 = a2 + kstep; const char* b3 = b2 + kstep;
;             PG8_LDB(B0, 0, 0); PG8_LDB(B1, 0, 1); PG8_SCHED; PG8_LDA(At, 0, 0); PG8_STAGE(PG8_SA(1, 1), a1 + hstepA, voffA);
;             PG8_WAIT_V(8); PG8_WAIT_L(0); PG8_BAR; PG8_MMA(0, 0, At, B0); PG8_MMA(0, 1, At, B1); PG8_BAR; PG8_SCHED;
;             PG8_LDA(At, 0, 1); PG8_STAGE(PG8_SB(0, 0), b2, voffB); PG8_STAGE(PG8_SB(0, 1), b2 + hstepB, voffB); PG8_STAGE(PG8_SA(0, 0), a2, voffA);
;             PG8_WAIT_V(8); PG8_WAIT_L(0); PG8_BAR; PG8_MMA(1, 0, At, B0); PG8_MMA(1, 1, At, B1); PG8_BAR; PG8_SCHED;
.LBB0_996:
	ds_read_b128 v[128:131], v197
	ds_read_b128 v[132:135], v197 offset:1024
	ds_read_b128 v[154:157], v197 offset:2048
	ds_read_b128 v[158:161], v197 offset:3072
	ds_read_b128 v[162:165], v198
	ds_read_b128 v[166:169], v198 offset:1024
	ds_read_b128 v[170:173], v198 offset:2048
	ds_read_b128 v[174:177], v198 offset:3072
	s_add_u32 s14, s12, 0xfffc0080
	s_addc_u32 s15, s13, -1
	s_cmp_eq_u32 s60, 12
	s_cselect_b32 s17, s9, s15
	s_cselect_b32 s16, s11, s14
	s_cselect_b32 s15, s35, s43
	s_cselect_b32 s14, s37, s42
	v_lshl_add_u64 v[186:187], s[12:13], 0, v[146:147]
	s_add_i32 m0, s31, 0xc000
	ds_read_b128 v[178:181], v199
	ds_read_b128 v[182:185], v199 offset:1024
	ds_read_b128 v[202:205], v199 offset:2048
	ds_read_b128 v[206:209], v199 offset:3072
	ds_read_b128 v[210:213], v199 offset:4096
	ds_read_b128 v[214:217], v199 offset:5120
	ds_read_b128 v[218:221], v199 offset:6144
	ds_read_b128 v[222:225], v199 offset:7168
	global_load_lds_dwordx4 v[186:187], off
	v_lshl_add_u64 v[186:187], s[12:13], 0, v[148:149]
	s_add_i32 m0, s31, 0xe000
	s_nop 0
	global_load_lds_dwordx4 v[186:187], off
	s_waitcnt vmcnt(8)
	s_waitcnt lgkmcnt(0)
	s_barrier
	s_setprio 1
	s_waitcnt lgkmcnt(0)
	v_mfma_f32_16x16x32_bf16 v[36:39], v[128:131], v[178:181], v[36:39]
	v_mfma_f32_16x16x32_bf16 v[20:23], v[154:157], v[178:181], v[20:23]
	v_mfma_f32_16x16x32_bf16 v[60:63], v[128:131], v[202:205], v[60:63]
	v_mfma_f32_16x16x32_bf16 v[44:47], v[154:157], v[202:205], v[44:47]
	v_mfma_f32_16x16x32_bf16 v[80:83], v[128:131], v[210:213], v[80:83]
	v_mfma_f32_16x16x32_bf16 v[72:75], v[154:157], v[210:213], v[72:75]
	v_mfma_f32_16x16x32_bf16 v[96:99], v[128:131], v[218:221], v[96:99]
	v_mfma_f32_16x16x32_bf16 v[88:91], v[154:157], v[218:221], v[88:91]
	v_mfma_f32_16x16x32_bf16 v[36:39], v[132:135], v[182:185], v[36:39]
	v_mfma_f32_16x16x32_bf16 v[20:23], v[158:161], v[182:185], v[20:23]
	v_mfma_f32_16x16x32_bf16 v[60:63], v[132:135], v[206:209], v[60:63]
	v_mfma_f32_16x16x32_bf16 v[44:47], v[158:161], v[206:209], v[44:47]
	v_mfma_f32_16x16x32_bf16 v[80:83], v[132:135], v[214:217], v[80:83]
	v_mfma_f32_16x16x32_bf16 v[72:75], v[158:161], v[214:217], v[72:75]
	v_mfma_f32_16x16x32_bf16 v[96:99], v[132:135], v[222:225], v[96:99]
	v_mfma_f32_16x16x32_bf16 v[88:91], v[158:161], v[222:225], v[88:91]
	v_mfma_f32_16x16x32_bf16 v[32:35], v[162:165], v[178:181], v[32:35]
	v_mfma_f32_16x16x32_bf16 v[16:19], v[170:173], v[178:181], v[16:19]
	v_mfma_f32_16x16x32_bf16 v[64:67], v[162:165], v[202:205], v[64:67]
	v_mfma_f32_16x16x32_bf16 v[48:51], v[170:173], v[202:205], v[48:51]
	v_mfma_f32_16x16x32_bf16 v[28:31], v[162:165], v[210:213], v[28:31]
	v_mfma_f32_16x16x32_bf16 v[4:7], v[170:173], v[210:213], v[4:7]
	v_mfma_f32_16x16x32_bf16 v[68:71], v[162:165], v[218:221], v[68:71]
	v_mfma_f32_16x16x32_bf16 v[52:55], v[170:173], v[218:221], v[52:55]
	v_mfma_f32_16x16x32_bf16 v[32:35], v[166:169], v[182:185], v[32:35]
	v_mfma_f32_16x16x32_bf16 v[16:19], v[174:177], v[182:185], v[16:19]
	v_mfma_f32_16x16x32_bf16 v[64:67], v[166:169], v[206:209], v[64:67]
	v_mfma_f32_16x16x32_bf16 v[48:51], v[174:177], v[206:209], v[48:51]
	v_mfma_f32_16x16x32_bf16 v[28:31], v[166:169], v[214:217], v[28:31]
	v_mfma_f32_16x16x32_bf16 v[4:7], v[174:177], v[214:217], v[4:7]
	v_mfma_f32_16x16x32_bf16 v[68:71], v[166:169], v[222:225], v[68:71]
	v_mfma_f32_16x16x32_bf16 v[52:55], v[174:177], v[222:225], v[52:55]
	s_setprio 0
	s_barrier
	s_add_i32 s61, s56, s29
	v_lshl_add_u64 v[186:187], s[14:15], 0, v[138:139]
	s_mov_b32 m0, s61
	ds_read_b128 v[178:181], v199 offset:16384
	ds_read_b128 v[182:185], v199 offset:17408
	ds_read_b128 v[202:205], v199 offset:18432
	ds_read_b128 v[206:209], v199 offset:19456
	ds_read_b128 v[210:213], v199 offset:20480
	ds_read_b128 v[214:217], v199 offset:21504
	ds_read_b128 v[218:221], v199 offset:22528
	ds_read_b128 v[222:225], v199 offset:23552
	global_load_lds_dwordx4 v[186:187], off
	s_add_i32 m0, s61, 0x2000
	s_add_u32 s62, s14, 0x10000
	v_lshl_add_u64 v[188:189], s[14:15], 0, v[142:143]
	s_addc_u32 s63, s15, 0
	s_add_i32 s61, s57, s29
	global_load_lds_dwordx4 v[188:189], off
	v_lshl_add_u64 v[194:195], s[62:63], 0, v[138:139]
	s_mov_b32 m0, s61
	v_lshl_add_u64 v[226:227], s[16:17], 0, v[140:141]
	global_load_lds_dwordx4 v[194:195], off
	v_lshl_add_u64 v[194:195], s[62:63], 0, v[142:143]
	s_add_i32 m0, s61, 0x2000
	s_nop 0
	global_load_lds_dwordx4 v[194:195], off
	v_lshl_add_u64 v[194:195], s[16:17], 0, v[136:137]
	s_mov_b32 m0, s31
	s_nop 0
	global_load_lds_dwordx4 v[194:195], off
	s_mov_b32 m0, s33
	s_nop 0
	global_load_lds_dwordx4 v[226:227], off
	s_waitcnt vmcnt(8)
	s_waitcnt lgkmcnt(0)
	s_barrier
; #define PG8_STAGE(bufoff, gbase, voff) do { _Pragma("unroll") for (int _i = 0; _i < 2; ++_i) \
;         __builtin_amdgcn_global_load_lds((const unsigned*)((const char*)(gbase) + (voff)[_i]), (LAS unsigned*)(lds + (bufoff) + ldsw + _i * 8192), 16, 0, 0); } while (0)
; #define PG8_LDA(dst, b, h) do { _Pragma("unroll") for (int m = 0; m < 4; ++m) _Pragma("unroll") for (int k = 0; k < 2; ++k) dst[m][k] = *(const LAS bf16x8*)(lds + PG8_SA(b, h) + aoff + m * 2048 + k * 1024); } while (0)
; #define PG8_LDB(dst, b, h) do { _Pragma("unroll") for (int n = 0; n < 2; ++n) _Pragma("unroll") for (int k = 0; k < 2; ++k) dst[n][k] = *(const LAS bf16x8*)(lds + PG8_SB(b, h) + boff + n * 2048 + k * 1024); } while (0)
; #define PG8_MMA(ai, bj, At, Bt) do { __builtin_amdgcn_s_setprio(1); _Pragma("unroll") for (int m = 0; m < 4; ++m) _Pragma("unroll") for (int n = 0; n < 2; ++n) _Pragma("unroll") for (int k = 0; k < 2; ++k) \
;         acc[ai][bj][m][n] = __builtin_amdgcn_mfma_f32_16x16x32_bf16(Bt[n][k], At[m][k], acc[ai][bj][m][n], 0, 0, 0); __builtin_amdgcn_s_setprio(0); } while (0)
; #define PG8_WAIT_V(n) asm volatile("s_waitcnt vmcnt(" #n ")" ::: "memory")
; #define PG8_WAIT_L(n) asm volatile("s_waitcnt lgkmcnt(" #n ")" ::: "memory")
; #define PG8_BAR __builtin_amdgcn_s_barrier()
; #define PG8_SCHED __builtin_amdgcn_sched_barrier(0)
; template <int MODE> DI void gemm_phase(LAS unsigned char* lds, const Gemm g, const StaticOrder& S, const Epi& E) {
;     ...
;             PG8_WAIT_V(8); PG8_WAIT_L(0); PG8_BAR; PG8_MMA(1, 0, At, B0); PG8_MMA(1, 1, At, B1); PG8_BAR; PG8_SCHED;
;             PG8_LDB(B0, 1, 0); PG8_LDB(B1, 1, 1); PG8_SCHED; PG8_LDA(At, 1, 0); PG8_STAGE(PG8_SA(0, 1), a2 + hstepA, voffA);
;             PG8_WAIT_V(8); PG8_WAIT_L(0); PG8_BAR; PG8_MMA(0, 0, At, B0); PG8_MMA(0, 1, At, B1); PG8_BAR; PG8_SCHED;
;             PG8_LDA(At, 1, 1); PG8_STAGE(PG8_SB(1, 0), b3, voffB); PG8_STAGE(PG8_SB(1, 1), b3 + hstepB, voffB); PG8_STAGE(PG8_SA(1, 0), a3, voffA);
;             PG8_WAIT_V(8); PG8_WAIT_L(0); PG8_BAR; PG8_MMA(1, 0, At, B0); PG8_MMA(1, 1, At, B1); PG8_BAR; PG8_SCHED;
	s_setprio 1
	s_waitcnt lgkmcnt(0)
	v_mfma_f32_16x16x32_bf16 v[112:115], v[128:131], v[178:181], v[112:115]
	v_mfma_f32_16x16x32_bf16 v[104:107], v[154:157], v[178:181], v[104:107]
	v_mfma_f32_16x16x32_bf16 v[24:27], v[128:131], v[202:205], v[24:27]
	v_mfma_f32_16x16x32_bf16 v[0:3], v[154:157], v[202:205], v[0:3]
	v_mfma_f32_16x16x32_bf16 v[56:59], v[128:131], v[210:213], v[56:59]
	v_mfma_f32_16x16x32_bf16 v[40:43], v[154:157], v[210:213], v[40:43]
	v_mfma_f32_16x16x32_bf16 v[8:11], v[128:131], v[218:221], v[8:11]
	v_mfma_f32_16x16x32_bf16 v[12:15], v[154:157], v[218:221], v[12:15]
	v_mfma_f32_16x16x32_bf16 v[112:115], v[132:135], v[182:185], v[112:115]
	v_mfma_f32_16x16x32_bf16 v[104:107], v[158:161], v[182:185], v[104:107]
	v_mfma_f32_16x16x32_bf16 v[24:27], v[132:135], v[206:209], v[24:27]
	v_mfma_f32_16x16x32_bf16 v[0:3], v[158:161], v[206:209], v[0:3]
	v_mfma_f32_16x16x32_bf16 v[56:59], v[132:135], v[214:217], v[56:59]
	v_mfma_f32_16x16x32_bf16 v[40:43], v[158:161], v[214:217], v[40:43]
	v_mfma_f32_16x16x32_bf16 v[8:11], v[132:135], v[222:225], v[8:11]
	v_mfma_f32_16x16x32_bf16 v[12:15], v[158:161], v[222:225], v[12:15]
	v_mfma_f32_16x16x32_bf16 v[84:87], v[162:165], v[178:181], v[84:87]
	v_mfma_f32_16x16x32_bf16 v[76:79], v[170:173], v[178:181], v[76:79]
	v_mfma_f32_16x16x32_bf16 v[100:103], v[162:165], v[202:205], v[100:103]
	v_mfma_f32_16x16x32_bf16 v[92:95], v[170:173], v[202:205], v[92:95]
	v_mfma_f32_16x16x32_bf16 v[116:119], v[162:165], v[210:213], v[116:119]
	v_mfma_f32_16x16x32_bf16 v[108:111], v[170:173], v[210:213], v[108:111]
	v_mfma_f32_16x16x32_bf16 v[124:127], v[162:165], v[218:221], v[124:127]
	v_mfma_f32_16x16x32_bf16 v[120:123], v[170:173], v[218:221], v[120:123]
	v_mfma_f32_16x16x32_bf16 v[84:87], v[166:169], v[182:185], v[84:87]
	v_mfma_f32_16x16x32_bf16 v[76:79], v[174:177], v[182:185], v[76:79]
	v_mfma_f32_16x16x32_bf16 v[100:103], v[166:169], v[206:209], v[100:103]
	v_mfma_f32_16x16x32_bf16 v[92:95], v[174:177], v[206:209], v[92:95]
	v_mfma_f32_16x16x32_bf16 v[116:119], v[166:169], v[214:217], v[116:119]
	v_mfma_f32_16x16x32_bf16 v[108:111], v[174:177], v[214:217], v[108:111]
	v_mfma_f32_16x16x32_bf16 v[124:127], v[166:169], v[222:225], v[124:127]
	v_mfma_f32_16x16x32_bf16 v[120:123], v[174:177], v[222:225], v[120:123]
	s_setprio 0
	s_barrier
	s_add_i32 s61, 0, 0x18000
	v_add_u32_e32 v144, s61, v193
	s_add_i32 s62, 0, 0x1c000
	ds_read_b128 v[128:131], v144
	ds_read_b128 v[132:135], v144 offset:1024
	ds_read_b128 v[154:157], v144 offset:2048
	ds_read_b128 v[158:161], v144 offset:3072
	v_add_u32_e32 v144, s62, v193
	ds_read_b128 v[162:165], v144
	ds_read_b128 v[166:169], v144 offset:1024
	ds_read_b128 v[170:173], v144 offset:2048
	ds_read_b128 v[174:177], v144 offset:3072
	s_add_u32 s16, s16, 0x40000
	s_addc_u32 s17, s17, 0
	s_mov_b32 m0, s44
	v_lshl_add_u64 v[228:229], s[16:17], 0, v[136:137]
	ds_read_b128 v[178:181], v199 offset:32768
	ds_read_b128 v[182:185], v199 offset:33792
	ds_read_b128 v[202:205], v199 offset:34816
	ds_read_b128 v[206:209], v199 offset:35840
	ds_read_b128 v[210:213], v199 offset:36864
	ds_read_b128 v[214:217], v199 offset:37888
	ds_read_b128 v[218:221], v199 offset:38912
	ds_read_b128 v[222:225], v199 offset:39936
	global_load_lds_dwordx4 v[228:229], off
	v_lshl_add_u64 v[228:229], s[16:17], 0, v[140:141]
	s_mov_b32 m0, s45
	s_nop 0
	global_load_lds_dwordx4 v[228:229], off
	s_waitcnt vmcnt(8)
	s_waitcnt lgkmcnt(0)
	s_barrier
	s_setprio 1
	s_waitcnt lgkmcnt(0)
	v_mfma_f32_16x16x32_bf16 v[36:39], v[128:131], v[178:181], v[36:39]
	v_mfma_f32_16x16x32_bf16 v[20:23], v[154:157], v[178:181], v[20:23]
	v_mfma_f32_16x16x32_bf16 v[60:63], v[128:131], v[202:205], v[60:63]
	v_mfma_f32_16x16x32_bf16 v[44:47], v[154:157], v[202:205], v[44:47]
	v_mfma_f32_16x16x32_bf16 v[80:83], v[128:131], v[210:213], v[80:83]
	v_mfma_f32_16x16x32_bf16 v[72:75], v[154:157], v[210:213], v[72:75]
	v_mfma_f32_16x16x32_bf16 v[96:99], v[128:131], v[218:221], v[96:99]
	v_mfma_f32_16x16x32_bf16 v[88:91], v[154:157], v[218:221], v[88:91]
	v_mfma_f32_16x16x32_bf16 v[36:39], v[132:135], v[182:185], v[36:39]
	v_mfma_f32_16x16x32_bf16 v[20:23], v[158:161], v[182:185], v[20:23]
	v_mfma_f32_16x16x32_bf16 v[60:63], v[132:135], v[206:209], v[60:63]
	v_mfma_f32_16x16x32_bf16 v[44:47], v[158:161], v[206:209], v[44:47]
	v_mfma_f32_16x16x32_bf16 v[80:83], v[132:135], v[214:217], v[80:83]
	v_mfma_f32_16x16x32_bf16 v[72:75], v[158:161], v[214:217], v[72:75]
	v_mfma_f32_16x16x32_bf16 v[96:99], v[132:135], v[222:225], v[96:99]
	v_mfma_f32_16x16x32_bf16 v[88:91], v[158:161], v[222:225], v[88:91]
	v_mfma_f32_16x16x32_bf16 v[32:35], v[162:165], v[178:181], v[32:35]
	v_mfma_f32_16x16x32_bf16 v[16:19], v[170:173], v[178:181], v[16:19]
	v_mfma_f32_16x16x32_bf16 v[64:67], v[162:165], v[202:205], v[64:67]
	v_mfma_f32_16x16x32_bf16 v[48:51], v[170:173], v[202:205], v[48:51]
	v_mfma_f32_16x16x32_bf16 v[28:31], v[162:165], v[210:213], v[28:31]
	v_mfma_f32_16x16x32_bf16 v[4:7], v[170:173], v[210:213], v[4:7]
	v_mfma_f32_16x16x32_bf16 v[68:71], v[162:165], v[218:221], v[68:71]
	v_mfma_f32_16x16x32_bf16 v[52:55], v[170:173], v[218:221], v[52:55]
	v_mfma_f32_16x16x32_bf16 v[32:35], v[166:169], v[182:185], v[32:35]
	v_mfma_f32_16x16x32_bf16 v[16:19], v[174:177], v[182:185], v[16:19]
	v_mfma_f32_16x16x32_bf16 v[64:67], v[166:169], v[206:209], v[64:67]
	v_mfma_f32_16x16x32_bf16 v[48:51], v[174:177], v[206:209], v[48:51]
	v_mfma_f32_16x16x32_bf16 v[28:31], v[166:169], v[214:217], v[28:31]
	v_mfma_f32_16x16x32_bf16 v[4:7], v[174:177], v[214:217], v[4:7]
	v_mfma_f32_16x16x32_bf16 v[68:71], v[166:169], v[222:225], v[68:71]
	v_mfma_f32_16x16x32_bf16 v[52:55], v[174:177], v[222:225], v[52:55]
	s_setprio 0
	s_barrier
; #define PG8_STAGE(bufoff, gbase, voff) do { _Pragma("unroll") for (int _i = 0; _i < 2; ++_i) \
;         __builtin_amdgcn_global_load_lds((const unsigned*)((const char*)(gbase) + (voff)[_i]), (LAS unsigned*)(lds + (bufoff) + ldsw + _i * 8192), 16, 0, 0); } while (0)
; #define PG8_LDA(dst, b, h) do { _Pragma("unroll") for (int m = 0; m < 4; ++m) _Pragma("unroll") for (int k = 0; k < 2; ++k) dst[m][k] = *(const LAS bf16x8*)(lds + PG8_SA(b, h) + aoff + m * 2048 + k * 1024); } while (0)
; #define PG8_MMA(ai, bj, At, Bt) do { __builtin_amdgcn_s_setprio(1); _Pragma("unroll") for (int m = 0; m < 4; ++m) _Pragma("unroll") for (int n = 0; n < 2; ++n) _Pragma("unroll") for (int k = 0; k < 2; ++k) \
;         acc[ai][bj][m][n] = __builtin_amdgcn_mfma_f32_16x16x32_bf16(Bt[n][k], At[m][k], acc[ai][bj][m][n], 0, 0, 0); __builtin_amdgcn_s_setprio(0); } while (0)
; #define PG8_WAIT_V(n) asm volatile("s_waitcnt vmcnt(" #n ")" ::: "memory")
; #define PG8_WAIT_L(n) asm volatile("s_waitcnt lgkmcnt(" #n ")" ::: "memory")
; #define PG8_BAR __builtin_amdgcn_s_barrier()
; #define PG8_SCHED __builtin_amdgcn_sched_barrier(0)
; template <int MODE> DI void gemm_phase(LAS unsigned char* lds, const Gemm g, const StaticOrder& S, const Epi& E) {
;     ...
;             PG8_LDA(At, 1, 1); PG8_STAGE(PG8_SB(1, 0), b3, voffB); PG8_STAGE(PG8_SB(1, 1), b3 + hstepB, voffB); PG8_STAGE(PG8_SA(1, 0), a3, voffA);
;             PG8_WAIT_V(8); PG8_WAIT_L(0); PG8_BAR; PG8_MMA(1, 0, At, B0); PG8_MMA(1, 1, At, B1); PG8_BAR; PG8_SCHED;
;         }
;         if (wr == 0) PG8_BAR;
	s_add_i32 s16, s61, s29
	v_lshl_add_u64 v[186:187], v[186:187], 0, s[18:19]
	s_mov_b32 m0, s16
	ds_read_b128 v[178:181], v199 offset:49152
	ds_read_b128 v[182:185], v199 offset:50176
	ds_read_b128 v[202:205], v199 offset:51200
	ds_read_b128 v[206:209], v199 offset:52224
	ds_read_b128 v[210:213], v199 offset:53248
	ds_read_b128 v[214:217], v199 offset:54272
	ds_read_b128 v[218:221], v199 offset:55296
	ds_read_b128 v[222:225], v199 offset:56320
	global_load_lds_dwordx4 v[186:187], off
	s_add_i32 m0, s16, 0x2000
	s_add_u32 s14, s14, 0x10080
	v_lshl_add_u64 v[186:187], v[188:189], 0, s[18:19]
	s_addc_u32 s15, s15, 0
	s_add_i32 s16, s62, s29
	global_load_lds_dwordx4 v[186:187], off
	v_lshl_add_u64 v[186:187], s[14:15], 0, v[138:139]
	s_mov_b32 m0, s16
	s_nop 0
	global_load_lds_dwordx4 v[186:187], off
	v_lshl_add_u64 v[186:187], s[14:15], 0, v[142:143]
	s_add_i32 m0, s16, 0x2000
	s_nop 0
	global_load_lds_dwordx4 v[186:187], off
	v_lshl_add_u64 v[186:187], v[194:195], 0, s[18:19]
	s_mov_b32 m0, s53
	s_nop 0
	global_load_lds_dwordx4 v[186:187], off
	v_lshl_add_u64 v[186:187], v[226:227], 0, s[18:19]
	s_mov_b32 m0, s54
	s_nop 0
	global_load_lds_dwordx4 v[186:187], off
	s_waitcnt vmcnt(8)
	s_waitcnt lgkmcnt(0)
	s_barrier
	s_setprio 1
	s_waitcnt lgkmcnt(0)
	v_mfma_f32_16x16x32_bf16 v[112:115], v[128:131], v[178:181], v[112:115]
	v_mfma_f32_16x16x32_bf16 v[104:107], v[154:157], v[178:181], v[104:107]
	v_mfma_f32_16x16x32_bf16 v[24:27], v[128:131], v[202:205], v[24:27]
	v_mfma_f32_16x16x32_bf16 v[0:3], v[154:157], v[202:205], v[0:3]
	v_mfma_f32_16x16x32_bf16 v[56:59], v[128:131], v[210:213], v[56:59]
	v_mfma_f32_16x16x32_bf16 v[40:43], v[154:157], v[210:213], v[40:43]
	v_mfma_f32_16x16x32_bf16 v[8:11], v[128:131], v[218:221], v[8:11]
	v_mfma_f32_16x16x32_bf16 v[12:15], v[154:157], v[218:221], v[12:15]
	v_mfma_f32_16x16x32_bf16 v[112:115], v[132:135], v[182:185], v[112:115]
	v_mfma_f32_16x16x32_bf16 v[104:107], v[158:161], v[182:185], v[104:107]
	v_mfma_f32_16x16x32_bf16 v[24:27], v[132:135], v[206:209], v[24:27]
	v_mfma_f32_16x16x32_bf16 v[0:3], v[158:161], v[206:209], v[0:3]
	v_mfma_f32_16x16x32_bf16 v[56:59], v[132:135], v[214:217], v[56:59]
	v_mfma_f32_16x16x32_bf16 v[40:43], v[158:161], v[214:217], v[40:43]
	v_mfma_f32_16x16x32_bf16 v[8:11], v[132:135], v[222:225], v[8:11]
	v_mfma_f32_16x16x32_bf16 v[12:15], v[158:161], v[222:225], v[12:15]
	v_mfma_f32_16x16x32_bf16 v[84:87], v[162:165], v[178:181], v[84:87]
	v_mfma_f32_16x16x32_bf16 v[76:79], v[170:173], v[178:181], v[76:79]
	v_mfma_f32_16x16x32_bf16 v[100:103], v[162:165], v[202:205], v[100:103]
	v_mfma_f32_16x16x32_bf16 v[92:95], v[170:173], v[202:205], v[92:95]
	v_mfma_f32_16x16x32_bf16 v[116:119], v[162:165], v[210:213], v[116:119]
	v_mfma_f32_16x16x32_bf16 v[108:111], v[170:173], v[210:213], v[108:111]
	v_mfma_f32_16x16x32_bf16 v[124:127], v[162:165], v[218:221], v[124:127]
	v_mfma_f32_16x16x32_bf16 v[120:123], v[170:173], v[218:221], v[120:123]
	v_mfma_f32_16x16x32_bf16 v[84:87], v[166:169], v[182:185], v[84:87]
	v_mfma_f32_16x16x32_bf16 v[76:79], v[174:177], v[182:185], v[76:79]
	v_mfma_f32_16x16x32_bf16 v[100:103], v[166:169], v[206:209], v[100:103]
	v_mfma_f32_16x16x32_bf16 v[92:95], v[174:177], v[206:209], v[92:95]
	v_mfma_f32_16x16x32_bf16 v[116:119], v[166:169], v[214:217], v[116:119]
	v_mfma_f32_16x16x32_bf16 v[108:111], v[174:177], v[214:217], v[108:111]
	v_mfma_f32_16x16x32_bf16 v[124:127], v[166:169], v[222:225], v[124:127]
	v_mfma_f32_16x16x32_bf16 v[120:123], v[174:177], v[222:225], v[120:123]
	s_setprio 0
	s_barrier
	s_add_i32 s60, s60, 2
	s_add_u32 s12, s12, 0x100
	s_addc_u32 s13, s13, 0
	s_add_u32 s42, s42, 0x100
	s_addc_u32 s43, s43, 0
	s_cmp_gt_u32 s60, 13
	s_cbranch_scc0 .LBB0_996
	s_and_b64 vcc, exec, s[20:21]
	s_cbranch_vccz .LBB0_999
	s_barrier

; #define PG8_STAGE(bufoff, gbase, voff) do { _Pragma("unroll") for (int _i = 0; _i < 2; ++_i) \
;         __builtin_amdgcn_global_load_lds((const unsigned*)((const char*)(gbase) + (voff)[_i]), (LAS unsigned*)(lds + (bufoff) + ldsw + _i * 8192), 16, 0, 0); } while (0)
; #define PG8_LDA(dst, b, h) do { _Pragma("unroll") for (int m = 0; m < 4; ++m) _Pragma("unroll") for (int k = 0; k < 2; ++k) dst[m][k] = *(const LAS bf16x8*)(lds + PG8_SA(b, h) + aoff + m * 2048 + k * 1024); } while (0)
; #define PG8_LDB(dst, b, h) do { _Pragma("unroll") for (int n = 0; n < 2; ++n) _Pragma("unroll") for (int k = 0; k < 2; ++k) dst[n][k] = *(const LAS bf16x8*)(lds + PG8_SB(b, h) + boff + n * 2048 + k * 1024); } while (0)
; #define PG8_MMA(ai, bj, At, Bt) do { __builtin_amdgcn_s_setprio(1); _Pragma("unroll") for (int m = 0; m < 4; ++m) _Pragma("unroll") for (int n = 0; n < 2; ++n) _Pragma("unroll") for (int k = 0; k < 2; ++k) \
;         acc[ai][bj][m][n] = __builtin_amdgcn_mfma_f32_16x16x32_bf16(Bt[n][k], At[m][k], acc[ai][bj][m][n], 0, 0, 0); __builtin_amdgcn_s_setprio(0); } while (0)
; #define PG8_WAIT_V(n) asm volatile("s_waitcnt vmcnt(" #n ")" ::: "memory")
; #define PG8_WAIT_L(n) asm volatile("s_waitcnt lgkmcnt(" #n ")" ::: "memory")
; #define PG8_BAR __builtin_amdgcn_s_barrier()
; #define PG8_SCHED __builtin_amdgcn_sched_barrier(0)
; template <int MODE> DI void gemm_phase(LAS unsigned char* lds, const Gemm g, const StaticOrder& S, const Epi& E) {
;     ...
;         for (int t = 0; t < nt; t += 2) {
;             const bool last = (t == nt - 2);
;             const char* a1 = cA + (size_t)(t + 1) * kstep;
;             const char* a2 = last ? nA : cA + (size_t)(t + 2) * kstep; const char* b2 = last ? nB : cB + (size_t)(t + 2) * kstep;
;             const char* a3 = a2 + kstep; const char* b3 = b2 + kstep;
;             PG8_LDB(B0, 0, 0); PG8_LDB(B1, 0, 1); PG8_SCHED; PG8_LDA(At, 0, 0); PG8_STAGE(PG8_SA(1, 1), a1 + hstepA, voffA);
;             PG8_WAIT_V(8); PG8_WAIT_L(0); PG8_BAR; PG8_MMA(0, 0, At, B0); PG8_MMA(0, 1, At, B1); PG8_BAR; PG8_SCHED;
;             PG8_LDA(At, 0, 1); PG8_STAGE(PG8_SB(0, 0), b2, voffB); PG8_STAGE(PG8_SB(0, 1), b2 + hstepB, voffB); PG8_STAGE(PG8_SA(0, 0), a2, voffA);
;             PG8_WAIT_V(8); PG8_WAIT_L(0); PG8_BAR; PG8_MMA(1, 0, At, B0); PG8_MMA(1, 1, At, B1); PG8_BAR; PG8_SCHED;
.LBB0_1087:
	ds_read_b128 v[144:147], v151
	ds_read_b128 v[154:157], v151 offset:1024
	ds_read_b128 v[158:161], v151 offset:2048
	ds_read_b128 v[162:165], v151 offset:3072
	ds_read_b128 v[166:169], v152
	ds_read_b128 v[170:173], v152 offset:1024
	ds_read_b128 v[174:177], v152 offset:2048
	ds_read_b128 v[178:181], v152 offset:3072
	s_add_u32 s22, s20, 0xfffc0080
	s_addc_u32 s23, s21, -1
	s_cmp_eq_u32 s45, 12
	s_cselect_b32 s25, s13, s23
	s_cselect_b32 s24, s41, s22
	s_cselect_b32 s23, s11, s44
	s_cselect_b32 s22, s42, s43
	v_lshl_add_u64 v[214:215], s[20:21], 0, v[136:137]
	s_add_i32 m0, s19, 0xc000
	ds_read_b128 v[182:185], v153
	ds_read_b128 v[186:189], v153 offset:1024
	ds_read_b128 v[190:193], v153 offset:2048
	ds_read_b128 v[194:197], v153 offset:3072
	ds_read_b128 v[198:201], v153 offset:4096
	ds_read_b128 v[202:205], v153 offset:5120
	ds_read_b128 v[206:209], v153 offset:6144
	ds_read_b128 v[210:213], v153 offset:7168
	global_load_lds_dwordx4 v[214:215], off
	v_lshl_add_u64 v[214:215], s[20:21], 0, v[138:139]
	s_add_i32 m0, s19, 0xe000
	s_nop 0
	global_load_lds_dwordx4 v[214:215], off
	s_waitcnt vmcnt(8)
	s_waitcnt lgkmcnt(0)
	s_barrier
	s_setprio 1
	s_waitcnt lgkmcnt(0)
	v_mfma_f32_16x16x32_bf16 v[124:127], v[144:147], v[182:185], v[124:127]
	v_mfma_f32_16x16x32_bf16 v[116:119], v[158:161], v[182:185], v[116:119]
	v_mfma_f32_16x16x32_bf16 v[108:111], v[144:147], v[190:193], v[108:111]
	v_mfma_f32_16x16x32_bf16 v[100:103], v[158:161], v[190:193], v[100:103]
	v_mfma_f32_16x16x32_bf16 v[92:95], v[144:147], v[198:201], v[92:95]
	v_mfma_f32_16x16x32_bf16 v[84:87], v[158:161], v[198:201], v[84:87]
	v_mfma_f32_16x16x32_bf16 v[76:79], v[144:147], v[206:209], v[76:79]
	v_mfma_f32_16x16x32_bf16 v[68:71], v[158:161], v[206:209], v[68:71]
	v_mfma_f32_16x16x32_bf16 v[124:127], v[154:157], v[186:189], v[124:127]
	v_mfma_f32_16x16x32_bf16 v[116:119], v[162:165], v[186:189], v[116:119]
	v_mfma_f32_16x16x32_bf16 v[108:111], v[154:157], v[194:197], v[108:111]
	v_mfma_f32_16x16x32_bf16 v[100:103], v[162:165], v[194:197], v[100:103]
	v_mfma_f32_16x16x32_bf16 v[92:95], v[154:157], v[202:205], v[92:95]
	v_mfma_f32_16x16x32_bf16 v[84:87], v[162:165], v[202:205], v[84:87]
	v_mfma_f32_16x16x32_bf16 v[76:79], v[154:157], v[210:213], v[76:79]
	v_mfma_f32_16x16x32_bf16 v[68:71], v[162:165], v[210:213], v[68:71]
	v_mfma_f32_16x16x32_bf16 v[120:123], v[166:169], v[182:185], v[120:123]
	v_mfma_f32_16x16x32_bf16 v[112:115], v[174:177], v[182:185], v[112:115]
	v_mfma_f32_16x16x32_bf16 v[104:107], v[166:169], v[190:193], v[104:107]
	v_mfma_f32_16x16x32_bf16 v[96:99], v[174:177], v[190:193], v[96:99]
	v_mfma_f32_16x16x32_bf16 v[88:91], v[166:169], v[198:201], v[88:91]
	v_mfma_f32_16x16x32_bf16 v[80:83], v[174:177], v[198:201], v[80:83]
	v_mfma_f32_16x16x32_bf16 v[72:75], v[166:169], v[206:209], v[72:75]
	v_mfma_f32_16x16x32_bf16 v[64:67], v[174:177], v[206:209], v[64:67]
	v_mfma_f32_16x16x32_bf16 v[120:123], v[170:173], v[186:189], v[120:123]
	v_mfma_f32_16x16x32_bf16 v[112:115], v[178:181], v[186:189], v[112:115]
	v_mfma_f32_16x16x32_bf16 v[104:107], v[170:173], v[194:197], v[104:107]
	v_mfma_f32_16x16x32_bf16 v[96:99], v[178:181], v[194:197], v[96:99]
	v_mfma_f32_16x16x32_bf16 v[88:91], v[170:173], v[202:205], v[88:91]
	v_mfma_f32_16x16x32_bf16 v[80:83], v[178:181], v[202:205], v[80:83]
	v_mfma_f32_16x16x32_bf16 v[72:75], v[170:173], v[210:213], v[72:75]
	v_mfma_f32_16x16x32_bf16 v[64:67], v[178:181], v[210:213], v[64:67]
	s_setprio 0
	s_barrier
	s_add_i32 s46, s37, s28
	v_lshl_add_u64 v[214:215], s[22:23], 0, v[132:133]
	s_mov_b32 m0, s46
	ds_read_b128 v[182:185], v153 offset:16384
	ds_read_b128 v[186:189], v153 offset:17408
	ds_read_b128 v[190:193], v153 offset:18432
	ds_read_b128 v[194:197], v153 offset:19456
	ds_read_b128 v[198:201], v153 offset:20480
	ds_read_b128 v[202:205], v153 offset:21504
	ds_read_b128 v[206:209], v153 offset:22528
	ds_read_b128 v[210:213], v153 offset:23552
	global_load_lds_dwordx4 v[214:215], off
	s_add_i32 m0, s46, 0x2000
	s_add_u32 s46, s22, 0x10000
	v_lshl_add_u64 v[216:217], s[22:23], 0, v[128:129]
	s_addc_u32 s47, s23, 0
	s_add_i32 s48, s38, s28
	global_load_lds_dwordx4 v[216:217], off
	v_lshl_add_u64 v[218:219], s[46:47], 0, v[132:133]
	s_mov_b32 m0, s48
	v_lshl_add_u64 v[220:221], s[24:25], 0, v[130:131]
	global_load_lds_dwordx4 v[218:219], off
	v_lshl_add_u64 v[218:219], s[46:47], 0, v[128:129]
	s_add_i32 m0, s48, 0x2000
	s_nop 0
	global_load_lds_dwordx4 v[218:219], off
	v_lshl_add_u64 v[218:219], s[24:25], 0, v[134:135]
	s_mov_b32 m0, s19
	s_nop 0
	global_load_lds_dwordx4 v[218:219], off
	s_mov_b32 m0, s30
	s_nop 0
	global_load_lds_dwordx4 v[220:221], off
	s_waitcnt vmcnt(8)
	s_waitcnt lgkmcnt(0)
	s_barrier
; #define PG8_STAGE(bufoff, gbase, voff) do { _Pragma("unroll") for (int _i = 0; _i < 2; ++_i) \
;         __builtin_amdgcn_global_load_lds((const unsigned*)((const char*)(gbase) + (voff)[_i]), (LAS unsigned*)(lds + (bufoff) + ldsw + _i * 8192), 16, 0, 0); } while (0)
; #define PG8_LDA(dst, b, h) do { _Pragma("unroll") for (int m = 0; m < 4; ++m) _Pragma("unroll") for (int k = 0; k < 2; ++k) dst[m][k] = *(const LAS bf16x8*)(lds + PG8_SA(b, h) + aoff + m * 2048 + k * 1024); } while (0)
; #define PG8_LDB(dst, b, h) do { _Pragma("unroll") for (int n = 0; n < 2; ++n) _Pragma("unroll") for (int k = 0; k < 2; ++k) dst[n][k] = *(const LAS bf16x8*)(lds + PG8_SB(b, h) + boff + n * 2048 + k * 1024); } while (0)
; #define PG8_MMA(ai, bj, At, Bt) do { __builtin_amdgcn_s_setprio(1); _Pragma("unroll") for (int m = 0; m < 4; ++m) _Pragma("unroll") for (int n = 0; n < 2; ++n) _Pragma("unroll") for (int k = 0; k < 2; ++k) \
;         acc[ai][bj][m][n] = __builtin_amdgcn_mfma_f32_16x16x32_bf16(Bt[n][k], At[m][k], acc[ai][bj][m][n], 0, 0, 0); __builtin_amdgcn_s_setprio(0); } while (0)
; #define PG8_WAIT_V(n) asm volatile("s_waitcnt vmcnt(" #n ")" ::: "memory")
; #define PG8_WAIT_L(n) asm volatile("s_waitcnt lgkmcnt(" #n ")" ::: "memory")
; #define PG8_BAR __builtin_amdgcn_s_barrier()
; #define PG8_SCHED __builtin_amdgcn_sched_barrier(0)
; template <int MODE> DI void gemm_phase(LAS unsigned char* lds, const Gemm g, const StaticOrder& S, const Epi& E) {
;     ...
;             PG8_WAIT_V(8); PG8_WAIT_L(0); PG8_BAR; PG8_MMA(1, 0, At, B0); PG8_MMA(1, 1, At, B1); PG8_BAR; PG8_SCHED;
;             PG8_LDB(B0, 1, 0); PG8_LDB(B1, 1, 1); PG8_SCHED; PG8_LDA(At, 1, 0); PG8_STAGE(PG8_SA(0, 1), a2 + hstepA, voffA);
;             PG8_WAIT_V(8); PG8_WAIT_L(0); PG8_BAR; PG8_MMA(0, 0, At, B0); PG8_MMA(0, 1, At, B1); PG8_BAR; PG8_SCHED;
;             PG8_LDA(At, 1, 1); PG8_STAGE(PG8_SB(1, 0), b3, voffB); PG8_STAGE(PG8_SB(1, 1), b3 + hstepB, voffB); PG8_STAGE(PG8_SA(1, 0), a3, voffA);
;             PG8_WAIT_V(8); PG8_WAIT_L(0); PG8_BAR; PG8_MMA(1, 0, At, B0); PG8_MMA(1, 1, At, B1); PG8_BAR; PG8_SCHED;
	s_setprio 1
	s_waitcnt lgkmcnt(0)
	v_mfma_f32_16x16x32_bf16 v[60:63], v[144:147], v[182:185], v[60:63]
	v_mfma_f32_16x16x32_bf16 v[52:55], v[158:161], v[182:185], v[52:55]
	v_mfma_f32_16x16x32_bf16 v[44:47], v[144:147], v[190:193], v[44:47]
	v_mfma_f32_16x16x32_bf16 v[36:39], v[158:161], v[190:193], v[36:39]
	v_mfma_f32_16x16x32_bf16 v[28:31], v[144:147], v[198:201], v[28:31]
	v_mfma_f32_16x16x32_bf16 v[20:23], v[158:161], v[198:201], v[20:23]
	v_mfma_f32_16x16x32_bf16 v[12:15], v[144:147], v[206:209], v[12:15]
	v_mfma_f32_16x16x32_bf16 v[4:7], v[158:161], v[206:209], v[4:7]
	v_mfma_f32_16x16x32_bf16 v[60:63], v[154:157], v[186:189], v[60:63]
	v_mfma_f32_16x16x32_bf16 v[52:55], v[162:165], v[186:189], v[52:55]
	v_mfma_f32_16x16x32_bf16 v[44:47], v[154:157], v[194:197], v[44:47]
	v_mfma_f32_16x16x32_bf16 v[36:39], v[162:165], v[194:197], v[36:39]
	v_mfma_f32_16x16x32_bf16 v[28:31], v[154:157], v[202:205], v[28:31]
	v_mfma_f32_16x16x32_bf16 v[20:23], v[162:165], v[202:205], v[20:23]
	v_mfma_f32_16x16x32_bf16 v[12:15], v[154:157], v[210:213], v[12:15]
	v_mfma_f32_16x16x32_bf16 v[4:7], v[162:165], v[210:213], v[4:7]
	v_mfma_f32_16x16x32_bf16 v[56:59], v[166:169], v[182:185], v[56:59]
	v_mfma_f32_16x16x32_bf16 v[48:51], v[174:177], v[182:185], v[48:51]
	v_mfma_f32_16x16x32_bf16 v[40:43], v[166:169], v[190:193], v[40:43]
	v_mfma_f32_16x16x32_bf16 v[32:35], v[174:177], v[190:193], v[32:35]
	v_mfma_f32_16x16x32_bf16 v[24:27], v[166:169], v[198:201], v[24:27]
	v_mfma_f32_16x16x32_bf16 v[16:19], v[174:177], v[198:201], v[16:19]
	v_mfma_f32_16x16x32_bf16 v[8:11], v[166:169], v[206:209], v[8:11]
	v_mfma_f32_16x16x32_bf16 v[0:3], v[174:177], v[206:209], v[0:3]
	v_mfma_f32_16x16x32_bf16 v[56:59], v[170:173], v[186:189], v[56:59]
	v_mfma_f32_16x16x32_bf16 v[48:51], v[178:181], v[186:189], v[48:51]
	v_mfma_f32_16x16x32_bf16 v[40:43], v[170:173], v[194:197], v[40:43]
	v_mfma_f32_16x16x32_bf16 v[32:35], v[178:181], v[194:197], v[32:35]
	v_mfma_f32_16x16x32_bf16 v[24:27], v[170:173], v[202:205], v[24:27]
	v_mfma_f32_16x16x32_bf16 v[16:19], v[178:181], v[202:205], v[16:19]
	v_mfma_f32_16x16x32_bf16 v[8:11], v[170:173], v[210:213], v[8:11]
	v_mfma_f32_16x16x32_bf16 v[0:3], v[178:181], v[210:213], v[0:3]
	s_setprio 0
	s_barrier
	s_add_i32 s46, 0, 0x18000
	s_add_i32 s47, 0, 0x1c000
	v_add_u32_e32 v162, s46, v149
	v_add_u32_e32 v178, s47, v149
	ds_read_b128 v[144:147], v162
	ds_read_b128 v[154:157], v162 offset:1024
	ds_read_b128 v[158:161], v162 offset:2048
	ds_read_b128 v[162:165], v162 offset:3072
	ds_read_b128 v[166:169], v178
	ds_read_b128 v[170:173], v178 offset:1024
	ds_read_b128 v[174:177], v178 offset:2048
	ds_read_b128 v[178:181], v178 offset:3072
	s_add_u32 s24, s24, 0x40000
	s_addc_u32 s25, s25, 0
	s_mov_b32 m0, s31
	v_lshl_add_u64 v[222:223], s[24:25], 0, v[134:135]
	ds_read_b128 v[182:185], v153 offset:32768
	ds_read_b128 v[186:189], v153 offset:33792
	ds_read_b128 v[190:193], v153 offset:34816
	ds_read_b128 v[194:197], v153 offset:35840
	ds_read_b128 v[198:201], v153 offset:36864
	ds_read_b128 v[202:205], v153 offset:37888
	ds_read_b128 v[206:209], v153 offset:38912
	ds_read_b128 v[210:213], v153 offset:39936
	global_load_lds_dwordx4 v[222:223], off
	v_lshl_add_u64 v[222:223], s[24:25], 0, v[130:131]
	s_mov_b32 m0, s33
	s_nop 0
	global_load_lds_dwordx4 v[222:223], off
	s_waitcnt vmcnt(8)
	s_waitcnt lgkmcnt(0)
	s_barrier
	s_setprio 1
	s_waitcnt lgkmcnt(0)
	v_mfma_f32_16x16x32_bf16 v[124:127], v[144:147], v[182:185], v[124:127]
	v_mfma_f32_16x16x32_bf16 v[116:119], v[158:161], v[182:185], v[116:119]
	v_mfma_f32_16x16x32_bf16 v[108:111], v[144:147], v[190:193], v[108:111]
	v_mfma_f32_16x16x32_bf16 v[100:103], v[158:161], v[190:193], v[100:103]
	v_mfma_f32_16x16x32_bf16 v[92:95], v[144:147], v[198:201], v[92:95]
	v_mfma_f32_16x16x32_bf16 v[84:87], v[158:161], v[198:201], v[84:87]
	v_mfma_f32_16x16x32_bf16 v[76:79], v[144:147], v[206:209], v[76:79]
	v_mfma_f32_16x16x32_bf16 v[68:71], v[158:161], v[206:209], v[68:71]
	v_mfma_f32_16x16x32_bf16 v[124:127], v[154:157], v[186:189], v[124:127]
	v_mfma_f32_16x16x32_bf16 v[116:119], v[162:165], v[186:189], v[116:119]
	v_mfma_f32_16x16x32_bf16 v[108:111], v[154:157], v[194:197], v[108:111]
	v_mfma_f32_16x16x32_bf16 v[100:103], v[162:165], v[194:197], v[100:103]
	v_mfma_f32_16x16x32_bf16 v[92:95], v[154:157], v[202:205], v[92:95]
	v_mfma_f32_16x16x32_bf16 v[84:87], v[162:165], v[202:205], v[84:87]
	v_mfma_f32_16x16x32_bf16 v[76:79], v[154:157], v[210:213], v[76:79]
	v_mfma_f32_16x16x32_bf16 v[68:71], v[162:165], v[210:213], v[68:71]
	v_mfma_f32_16x16x32_bf16 v[120:123], v[166:169], v[182:185], v[120:123]
	v_mfma_f32_16x16x32_bf16 v[112:115], v[174:177], v[182:185], v[112:115]
	v_mfma_f32_16x16x32_bf16 v[104:107], v[166:169], v[190:193], v[104:107]
	v_mfma_f32_16x16x32_bf16 v[96:99], v[174:177], v[190:193], v[96:99]
	v_mfma_f32_16x16x32_bf16 v[88:91], v[166:169], v[198:201], v[88:91]
	v_mfma_f32_16x16x32_bf16 v[80:83], v[174:177], v[198:201], v[80:83]
	v_mfma_f32_16x16x32_bf16 v[72:75], v[166:169], v[206:209], v[72:75]
	v_mfma_f32_16x16x32_bf16 v[64:67], v[174:177], v[206:209], v[64:67]
	v_mfma_f32_16x16x32_bf16 v[120:123], v[170:173], v[186:189], v[120:123]
	v_mfma_f32_16x16x32_bf16 v[112:115], v[178:181], v[186:189], v[112:115]
	v_mfma_f32_16x16x32_bf16 v[104:107], v[170:173], v[194:197], v[104:107]
	v_mfma_f32_16x16x32_bf16 v[96:99], v[178:181], v[194:197], v[96:99]
	v_mfma_f32_16x16x32_bf16 v[88:91], v[170:173], v[202:205], v[88:91]
	v_mfma_f32_16x16x32_bf16 v[80:83], v[178:181], v[202:205], v[80:83]
	v_mfma_f32_16x16x32_bf16 v[72:75], v[170:173], v[210:213], v[72:75]
	v_mfma_f32_16x16x32_bf16 v[64:67], v[178:181], v[210:213], v[64:67]
	s_setprio 0
	s_barrier
; #define PG8_STAGE(bufoff, gbase, voff) do { _Pragma("unroll") for (int _i = 0; _i < 2; ++_i) \
;         __builtin_amdgcn_global_load_lds((const unsigned*)((const char*)(gbase) + (voff)[_i]), (LAS unsigned*)(lds + (bufoff) + ldsw + _i * 8192), 16, 0, 0); } while (0)
; #define PG8_LDA(dst, b, h) do { _Pragma("unroll") for (int m = 0; m < 4; ++m) _Pragma("unroll") for (int k = 0; k < 2; ++k) dst[m][k] = *(const LAS bf16x8*)(lds + PG8_SA(b, h) + aoff + m * 2048 + k * 1024); } while (0)
; #define PG8_MMA(ai, bj, At, Bt) do { __builtin_amdgcn_s_setprio(1); _Pragma("unroll") for (int m = 0; m < 4; ++m) _Pragma("unroll") for (int n = 0; n < 2; ++n) _Pragma("unroll") for (int k = 0; k < 2; ++k) \
;         acc[ai][bj][m][n] = __builtin_amdgcn_mfma_f32_16x16x32_bf16(Bt[n][k], At[m][k], acc[ai][bj][m][n], 0, 0, 0); __builtin_amdgcn_s_setprio(0); } while (0)
; #define PG8_WAIT_V(n) asm volatile("s_waitcnt vmcnt(" #n ")" ::: "memory")
; #define PG8_WAIT_L(n) asm volatile("s_waitcnt lgkmcnt(" #n ")" ::: "memory")
; #define PG8_BAR __builtin_amdgcn_s_barrier()
; #define PG8_SCHED __builtin_amdgcn_sched_barrier(0)
; template <int MODE> DI void gemm_phase(LAS unsigned char* lds, const Gemm g, const StaticOrder& S, const Epi& E) {
;     ...
;             PG8_LDA(At, 1, 1); PG8_STAGE(PG8_SB(1, 0), b3, voffB); PG8_STAGE(PG8_SB(1, 1), b3 + hstepB, voffB); PG8_STAGE(PG8_SA(1, 0), a3, voffA);
;             PG8_WAIT_V(8); PG8_WAIT_L(0); PG8_BAR; PG8_MMA(1, 0, At, B0); PG8_MMA(1, 1, At, B1); PG8_BAR; PG8_SCHED;
;         }
;         if (wr == 0) PG8_BAR;
	s_add_i32 s24, s46, s28
	v_lshl_add_u64 v[214:215], v[214:215], 0, s[6:7]
	s_mov_b32 m0, s24
	ds_read_b128 v[182:185], v153 offset:49152
	ds_read_b128 v[186:189], v153 offset:50176
	ds_read_b128 v[190:193], v153 offset:51200
	ds_read_b128 v[194:197], v153 offset:52224
	ds_read_b128 v[198:201], v153 offset:53248
	ds_read_b128 v[202:205], v153 offset:54272
	ds_read_b128 v[206:209], v153 offset:55296
	ds_read_b128 v[210:213], v153 offset:56320
	global_load_lds_dwordx4 v[214:215], off
	s_add_i32 m0, s24, 0x2000
	s_add_u32 s22, s22, 0x10080
	v_lshl_add_u64 v[214:215], v[216:217], 0, s[6:7]
	s_addc_u32 s23, s23, 0
	s_add_i32 s24, s47, s28
	global_load_lds_dwordx4 v[214:215], off
	v_lshl_add_u64 v[214:215], s[22:23], 0, v[132:133]
	s_mov_b32 m0, s24
	s_nop 0
	global_load_lds_dwordx4 v[214:215], off
	v_lshl_add_u64 v[214:215], s[22:23], 0, v[128:129]
	s_add_i32 m0, s24, 0x2000
	s_nop 0
	global_load_lds_dwordx4 v[214:215], off
	v_lshl_add_u64 v[214:215], v[218:219], 0, s[6:7]
	s_mov_b32 m0, s35
	s_nop 0
	global_load_lds_dwordx4 v[214:215], off
	v_lshl_add_u64 v[214:215], v[220:221], 0, s[6:7]
	s_mov_b32 m0, s36
	s_nop 0
	global_load_lds_dwordx4 v[214:215], off
	s_waitcnt vmcnt(8)
	s_waitcnt lgkmcnt(0)
	s_barrier
	s_setprio 1
	s_waitcnt lgkmcnt(0)
	v_mfma_f32_16x16x32_bf16 v[60:63], v[144:147], v[182:185], v[60:63]
	v_mfma_f32_16x16x32_bf16 v[52:55], v[158:161], v[182:185], v[52:55]
	v_mfma_f32_16x16x32_bf16 v[44:47], v[144:147], v[190:193], v[44:47]
	v_mfma_f32_16x16x32_bf16 v[36:39], v[158:161], v[190:193], v[36:39]
	v_mfma_f32_16x16x32_bf16 v[28:31], v[144:147], v[198:201], v[28:31]
	v_mfma_f32_16x16x32_bf16 v[20:23], v[158:161], v[198:201], v[20:23]
	v_mfma_f32_16x16x32_bf16 v[12:15], v[144:147], v[206:209], v[12:15]
	v_mfma_f32_16x16x32_bf16 v[4:7], v[158:161], v[206:209], v[4:7]
	v_mfma_f32_16x16x32_bf16 v[60:63], v[154:157], v[186:189], v[60:63]
	v_mfma_f32_16x16x32_bf16 v[52:55], v[162:165], v[186:189], v[52:55]
	v_mfma_f32_16x16x32_bf16 v[44:47], v[154:157], v[194:197], v[44:47]
	v_mfma_f32_16x16x32_bf16 v[36:39], v[162:165], v[194:197], v[36:39]
	v_mfma_f32_16x16x32_bf16 v[28:31], v[154:157], v[202:205], v[28:31]
	v_mfma_f32_16x16x32_bf16 v[20:23], v[162:165], v[202:205], v[20:23]
	v_mfma_f32_16x16x32_bf16 v[12:15], v[154:157], v[210:213], v[12:15]
	v_mfma_f32_16x16x32_bf16 v[4:7], v[162:165], v[210:213], v[4:7]
	v_mfma_f32_16x16x32_bf16 v[56:59], v[166:169], v[182:185], v[56:59]
	v_mfma_f32_16x16x32_bf16 v[48:51], v[174:177], v[182:185], v[48:51]
	v_mfma_f32_16x16x32_bf16 v[40:43], v[166:169], v[190:193], v[40:43]
	v_mfma_f32_16x16x32_bf16 v[32:35], v[174:177], v[190:193], v[32:35]
	v_mfma_f32_16x16x32_bf16 v[24:27], v[166:169], v[198:201], v[24:27]
	v_mfma_f32_16x16x32_bf16 v[16:19], v[174:177], v[198:201], v[16:19]
	v_mfma_f32_16x16x32_bf16 v[8:11], v[166:169], v[206:209], v[8:11]
	v_mfma_f32_16x16x32_bf16 v[0:3], v[174:177], v[206:209], v[0:3]
	v_mfma_f32_16x16x32_bf16 v[56:59], v[170:173], v[186:189], v[56:59]
	v_mfma_f32_16x16x32_bf16 v[48:51], v[178:181], v[186:189], v[48:51]
	v_mfma_f32_16x16x32_bf16 v[40:43], v[170:173], v[194:197], v[40:43]
	v_mfma_f32_16x16x32_bf16 v[32:35], v[178:181], v[194:197], v[32:35]
	v_mfma_f32_16x16x32_bf16 v[24:27], v[170:173], v[202:205], v[24:27]
	v_mfma_f32_16x16x32_bf16 v[16:19], v[178:181], v[202:205], v[16:19]
	v_mfma_f32_16x16x32_bf16 v[8:11], v[170:173], v[210:213], v[8:11]
	v_mfma_f32_16x16x32_bf16 v[0:3], v[178:181], v[210:213], v[0:3]
	s_setprio 0
	s_barrier
	s_add_i32 s45, s45, 2
	s_add_u32 s20, s20, 0x100
	s_addc_u32 s21, s21, 0
	s_add_u32 s43, s43, 0x100
	s_addc_u32 s44, s44, 0
	s_cmp_gt_u32 s45, 13
	s_cbranch_scc0 .LBB0_1087
	s_and_b64 vcc, exec, s[8:9]
	s_cbranch_vccz .LBB0_1090
	s_barrier

; #define PG8_STAGE(bufoff, gbase, voff) do { _Pragma("unroll") for (int _i = 0; _i < 2; ++_i) \
;         __builtin_amdgcn_global_load_lds((const unsigned*)((const char*)(gbase) + (voff)[_i]), (LAS unsigned*)(lds + (bufoff) + ldsw + _i * 8192), 16, 0, 0); } while (0)
; #define PG8_LDA(dst, b, h) do { _Pragma("unroll") for (int m = 0; m < 4; ++m) _Pragma("unroll") for (int k = 0; k < 2; ++k) dst[m][k] = *(const LAS bf16x8*)(lds + PG8_SA(b, h) + aoff + m * 2048 + k * 1024); } while (0)
; #define PG8_LDB(dst, b, h) do { _Pragma("unroll") for (int n = 0; n < 2; ++n) _Pragma("unroll") for (int k = 0; k < 2; ++k) dst[n][k] = *(const LAS bf16x8*)(lds + PG8_SB(b, h) + boff + n * 2048 + k * 1024); } while (0)
; #define PG8_MMA(ai, bj, At, Bt) do { __builtin_amdgcn_s_setprio(1); _Pragma("unroll") for (int m = 0; m < 4; ++m) _Pragma("unroll") for (int n = 0; n < 2; ++n) _Pragma("unroll") for (int k = 0; k < 2; ++k) \
;         acc[ai][bj][m][n] = __builtin_amdgcn_mfma_f32_16x16x32_bf16(Bt[n][k], At[m][k], acc[ai][bj][m][n], 0, 0, 0); __builtin_amdgcn_s_setprio(0); } while (0)
; #define PG8_WAIT_V(n) asm volatile("s_waitcnt vmcnt(" #n ")" ::: "memory")
; #define PG8_WAIT_L(n) asm volatile("s_waitcnt lgkmcnt(" #n ")" ::: "memory")
; #define PG8_BAR __builtin_amdgcn_s_barrier()
; #define PG8_SCHED __builtin_amdgcn_sched_barrier(0)
; template <int MODE> DI void gemm_phase(LAS unsigned char* lds, const Gemm g, const StaticOrder& S, const Epi& E) {
;     ...
;         for (int t = 0; t < nt; t += 2) {
;             const bool last = (t == nt - 2);
;             const char* a1 = cA + (size_t)(t + 1) * kstep;
;             const char* a2 = last ? nA : cA + (size_t)(t + 2) * kstep; const char* b2 = last ? nB : cB + (size_t)(t + 2) * kstep;
;             const char* a3 = a2 + kstep; const char* b3 = b2 + kstep;
;             PG8_LDB(B0, 0, 0); PG8_LDB(B1, 0, 1); PG8_SCHED; PG8_LDA(At, 0, 0); PG8_STAGE(PG8_SA(1, 1), a1 + hstepA, voffA);
;             PG8_WAIT_V(8); PG8_WAIT_L(0); PG8_BAR; PG8_MMA(0, 0, At, B0); PG8_MMA(0, 1, At, B1); PG8_BAR; PG8_SCHED;
;             PG8_LDA(At, 0, 1); PG8_STAGE(PG8_SB(0, 0), b2, voffB); PG8_STAGE(PG8_SB(0, 1), b2 + hstepB, voffB); PG8_STAGE(PG8_SA(0, 0), a2, voffA);
;             PG8_WAIT_V(8); PG8_WAIT_L(0); PG8_BAR; PG8_MMA(1, 0, At, B0); PG8_MMA(1, 1, At, B1); PG8_BAR; PG8_SCHED;
.LBB0_1163:
	ds_read_b128 v[80:83], v197
	ds_read_b128 v[88:91], v197 offset:1024
	ds_read_b128 v[136:139], v197 offset:2048
	ds_read_b128 v[140:143], v197 offset:3072
	ds_read_b128 v[162:165], v198
	ds_read_b128 v[166:169], v198 offset:1024
	ds_read_b128 v[170:173], v198 offset:2048
	ds_read_b128 v[174:177], v198 offset:3072
	s_add_u32 s4, s8, 0x100
	s_addc_u32 s5, s9, 0
	s_cmp_eq_u32 s56, 40
	s_cselect_b32 s13, s37, s5
	s_cselect_b32 s12, s36, s4
	s_cselect_b32 s11, s39, s55
	s_cselect_b32 s10, s38, s54
	v_lshl_add_u64 v[218:219], s[8:9], 0, v[154:155]
	s_add_i32 m0, s33, 0xc000
	ds_read_b128 v[178:181], v199
	ds_read_b128 v[182:185], v199 offset:1024
	ds_read_b128 v[186:189], v199 offset:2048
	ds_read_b128 v[190:193], v199 offset:3072
	ds_read_b128 v[202:205], v199 offset:4096
	ds_read_b128 v[206:209], v199 offset:5120
	ds_read_b128 v[210:213], v199 offset:6144
	ds_read_b128 v[214:217], v199 offset:7168
	global_load_lds_dwordx4 v[218:219], off
	v_lshl_add_u64 v[218:219], s[8:9], 0, v[156:157]
	s_add_i32 m0, s33, 0xe000
	s_nop 0
	global_load_lds_dwordx4 v[218:219], off
	s_waitcnt vmcnt(8)
	s_waitcnt lgkmcnt(0)
	s_barrier
	s_setprio 1
	s_waitcnt lgkmcnt(0)
	v_mfma_f32_16x16x32_bf16 v[4:7], v[80:83], v[178:181], v[4:7]
	v_mfma_f32_16x16x32_bf16 v[0:3], v[136:139], v[178:181], v[0:3]
	v_mfma_f32_16x16x32_bf16 v[12:15], v[80:83], v[186:189], v[12:15]
	v_mfma_f32_16x16x32_bf16 v[8:11], v[136:139], v[186:189], v[8:11]
	v_mfma_f32_16x16x32_bf16 v[20:23], v[80:83], v[202:205], v[20:23]
	v_mfma_f32_16x16x32_bf16 v[16:19], v[136:139], v[202:205], v[16:19]
	v_mfma_f32_16x16x32_bf16 v[32:35], v[80:83], v[210:213], v[32:35]
	v_mfma_f32_16x16x32_bf16 v[24:27], v[136:139], v[210:213], v[24:27]
	v_mfma_f32_16x16x32_bf16 v[4:7], v[88:91], v[182:185], v[4:7]
	v_mfma_f32_16x16x32_bf16 v[0:3], v[140:143], v[182:185], v[0:3]
	v_mfma_f32_16x16x32_bf16 v[12:15], v[88:91], v[190:193], v[12:15]
	v_mfma_f32_16x16x32_bf16 v[8:11], v[140:143], v[190:193], v[8:11]
	v_mfma_f32_16x16x32_bf16 v[20:23], v[88:91], v[206:209], v[20:23]
	v_mfma_f32_16x16x32_bf16 v[16:19], v[140:143], v[206:209], v[16:19]
	v_mfma_f32_16x16x32_bf16 v[32:35], v[88:91], v[214:217], v[32:35]
	v_mfma_f32_16x16x32_bf16 v[24:27], v[140:143], v[214:217], v[24:27]
	v_mfma_f32_16x16x32_bf16 v[132:135], v[162:165], v[178:181], v[132:135]
	v_mfma_f32_16x16x32_bf16 v[128:131], v[170:173], v[178:181], v[128:131]
	v_mfma_f32_16x16x32_bf16 v[48:51], v[162:165], v[186:189], v[48:51]
	v_mfma_f32_16x16x32_bf16 v[40:43], v[170:173], v[186:189], v[40:43]
	v_mfma_f32_16x16x32_bf16 v[76:79], v[162:165], v[202:205], v[76:79]
	v_mfma_f32_16x16x32_bf16 v[60:63], v[170:173], v[202:205], v[60:63]
	v_mfma_f32_16x16x32_bf16 v[92:95], v[162:165], v[210:213], v[92:95]
	v_mfma_f32_16x16x32_bf16 v[84:87], v[170:173], v[210:213], v[84:87]
	v_mfma_f32_16x16x32_bf16 v[132:135], v[166:169], v[182:185], v[132:135]
	v_mfma_f32_16x16x32_bf16 v[128:131], v[174:177], v[182:185], v[128:131]
	v_mfma_f32_16x16x32_bf16 v[48:51], v[166:169], v[190:193], v[48:51]
	v_mfma_f32_16x16x32_bf16 v[40:43], v[174:177], v[190:193], v[40:43]
	v_mfma_f32_16x16x32_bf16 v[76:79], v[166:169], v[206:209], v[76:79]
	v_mfma_f32_16x16x32_bf16 v[60:63], v[174:177], v[206:209], v[60:63]
	v_mfma_f32_16x16x32_bf16 v[92:95], v[166:169], v[214:217], v[92:95]
	v_mfma_f32_16x16x32_bf16 v[84:87], v[174:177], v[214:217], v[84:87]
	s_setprio 0
	s_barrier
	s_add_i32 s8, s48, s31
	v_lshl_add_u64 v[218:219], s[10:11], 0, v[146:147]
	s_mov_b32 m0, s8
	ds_read_b128 v[178:181], v199 offset:16384
	ds_read_b128 v[182:185], v199 offset:17408
	ds_read_b128 v[186:189], v199 offset:18432
	ds_read_b128 v[190:193], v199 offset:19456
	ds_read_b128 v[202:205], v199 offset:20480
	ds_read_b128 v[206:209], v199 offset:21504
	ds_read_b128 v[210:213], v199 offset:22528
	ds_read_b128 v[214:217], v199 offset:23552
	global_load_lds_dwordx4 v[218:219], off
	s_add_i32 m0, s8, 0x2000
	s_add_u32 s8, s10, 0x2c000
	v_lshl_add_u64 v[220:221], s[10:11], 0, v[150:151]
	s_addc_u32 s9, s11, 0
	s_add_i32 s57, s49, s31
	global_load_lds_dwordx4 v[220:221], off
	v_lshl_add_u64 v[222:223], s[8:9], 0, v[146:147]
	s_mov_b32 m0, s57
	v_lshl_add_u64 v[224:225], s[12:13], 0, v[148:149]
	global_load_lds_dwordx4 v[222:223], off
	v_lshl_add_u64 v[222:223], s[8:9], 0, v[150:151]
	s_add_i32 m0, s57, 0x2000
	s_nop 0
	global_load_lds_dwordx4 v[222:223], off
	v_lshl_add_u64 v[222:223], s[12:13], 0, v[144:145]
	s_mov_b32 m0, s33
	s_nop 0
	global_load_lds_dwordx4 v[222:223], off
	s_mov_b32 m0, s35
	s_nop 0
	global_load_lds_dwordx4 v[224:225], off
	s_waitcnt vmcnt(8)
	s_waitcnt lgkmcnt(0)
	s_barrier
; #define PG8_STAGE(bufoff, gbase, voff) do { _Pragma("unroll") for (int _i = 0; _i < 2; ++_i) \
;         __builtin_amdgcn_global_load_lds((const unsigned*)((const char*)(gbase) + (voff)[_i]), (LAS unsigned*)(lds + (bufoff) + ldsw + _i * 8192), 16, 0, 0); } while (0)
; #define PG8_LDA(dst, b, h) do { _Pragma("unroll") for (int m = 0; m < 4; ++m) _Pragma("unroll") for (int k = 0; k < 2; ++k) dst[m][k] = *(const LAS bf16x8*)(lds + PG8_SA(b, h) + aoff + m * 2048 + k * 1024); } while (0)
; #define PG8_LDB(dst, b, h) do { _Pragma("unroll") for (int n = 0; n < 2; ++n) _Pragma("unroll") for (int k = 0; k < 2; ++k) dst[n][k] = *(const LAS bf16x8*)(lds + PG8_SB(b, h) + boff + n * 2048 + k * 1024); } while (0)
; #define PG8_MMA(ai, bj, At, Bt) do { __builtin_amdgcn_s_setprio(1); _Pragma("unroll") for (int m = 0; m < 4; ++m) _Pragma("unroll") for (int n = 0; n < 2; ++n) _Pragma("unroll") for (int k = 0; k < 2; ++k) \
;         acc[ai][bj][m][n] = __builtin_amdgcn_mfma_f32_16x16x32_bf16(Bt[n][k], At[m][k], acc[ai][bj][m][n], 0, 0, 0); __builtin_amdgcn_s_setprio(0); } while (0)
; #define PG8_WAIT_V(n) asm volatile("s_waitcnt vmcnt(" #n ")" ::: "memory")
; #define PG8_WAIT_L(n) asm volatile("s_waitcnt lgkmcnt(" #n ")" ::: "memory")
; #define PG8_BAR __builtin_amdgcn_s_barrier()
; #define PG8_SCHED __builtin_amdgcn_sched_barrier(0)
; template <int MODE> DI void gemm_phase(LAS unsigned char* lds, const Gemm g, const StaticOrder& S, const Epi& E) {
;     ...
;             PG8_WAIT_V(8); PG8_WAIT_L(0); PG8_BAR; PG8_MMA(1, 0, At, B0); PG8_MMA(1, 1, At, B1); PG8_BAR; PG8_SCHED;
;             PG8_LDB(B0, 1, 0); PG8_LDB(B1, 1, 1); PG8_SCHED; PG8_LDA(At, 1, 0); PG8_STAGE(PG8_SA(0, 1), a2 + hstepA, voffA);
;             PG8_WAIT_V(8); PG8_WAIT_L(0); PG8_BAR; PG8_MMA(0, 0, At, B0); PG8_MMA(0, 1, At, B1); PG8_BAR; PG8_SCHED;
;             PG8_LDA(At, 1, 1); PG8_STAGE(PG8_SB(1, 0), b3, voffB); PG8_STAGE(PG8_SB(1, 1), b3 + hstepB, voffB); PG8_STAGE(PG8_SA(1, 0), a3, voffA);
;             PG8_WAIT_V(8); PG8_WAIT_L(0); PG8_BAR; PG8_MMA(1, 0, At, B0); PG8_MMA(1, 1, At, B1); PG8_BAR; PG8_SCHED;
	s_setprio 1
	s_waitcnt lgkmcnt(0)
	v_mfma_f32_16x16x32_bf16 v[52:55], v[80:83], v[178:181], v[52:55]
	v_mfma_f32_16x16x32_bf16 v[44:47], v[136:139], v[178:181], v[44:47]
	v_mfma_f32_16x16x32_bf16 v[72:75], v[80:83], v[186:189], v[72:75]
	v_mfma_f32_16x16x32_bf16 v[56:59], v[136:139], v[186:189], v[56:59]
	v_mfma_f32_16x16x32_bf16 v[68:71], v[80:83], v[202:205], v[68:71]
	v_mfma_f32_16x16x32_bf16 v[64:67], v[136:139], v[202:205], v[64:67]
	v_mfma_f32_16x16x32_bf16 v[36:39], v[80:83], v[210:213], v[36:39]
	v_mfma_f32_16x16x32_bf16 v[28:31], v[136:139], v[210:213], v[28:31]
	v_mfma_f32_16x16x32_bf16 v[52:55], v[88:91], v[182:185], v[52:55]
	v_mfma_f32_16x16x32_bf16 v[44:47], v[140:143], v[182:185], v[44:47]
	v_mfma_f32_16x16x32_bf16 v[72:75], v[88:91], v[190:193], v[72:75]
	v_mfma_f32_16x16x32_bf16 v[56:59], v[140:143], v[190:193], v[56:59]
	v_mfma_f32_16x16x32_bf16 v[68:71], v[88:91], v[206:209], v[68:71]
	v_mfma_f32_16x16x32_bf16 v[64:67], v[140:143], v[206:209], v[64:67]
	v_mfma_f32_16x16x32_bf16 v[36:39], v[88:91], v[214:217], v[36:39]
	v_mfma_f32_16x16x32_bf16 v[28:31], v[140:143], v[214:217], v[28:31]
	v_mfma_f32_16x16x32_bf16 v[88:91], v[170:173], v[178:181], v[96:99]
	v_mfma_f32_16x16x32_bf16 v[96:99], v[162:165], v[186:189], v[108:111]
	v_mfma_f32_16x16x32_bf16 v[108:111], v[166:169], v[190:193], v[96:99]
	v_mfma_f32_16x16x32_bf16 v[96:99], v[170:173], v[186:189], v[104:107]
	v_mfma_f32_16x16x32_bf16 v[104:107], v[174:177], v[190:193], v[96:99]
	v_mfma_f32_16x16x32_bf16 v[96:99], v[162:165], v[202:205], v[116:119]
	v_mfma_f32_16x16x32_bf16 v[116:119], v[166:169], v[206:209], v[96:99]
	v_mfma_f32_16x16x32_bf16 v[96:99], v[170:173], v[202:205], v[112:115]
	v_mfma_f32_16x16x32_bf16 v[112:115], v[174:177], v[206:209], v[96:99]
	v_mfma_f32_16x16x32_bf16 v[96:99], v[162:165], v[210:213], v[124:127]
	v_mfma_f32_16x16x32_bf16 v[124:127], v[166:169], v[214:217], v[96:99]
	v_mfma_f32_16x16x32_bf16 v[96:99], v[170:173], v[210:213], v[120:123]
	v_mfma_f32_16x16x32_bf16 v[80:83], v[162:165], v[178:181], v[100:103]
	v_mfma_f32_16x16x32_bf16 v[120:123], v[174:177], v[214:217], v[96:99]
	v_mfma_f32_16x16x32_bf16 v[80:83], v[166:169], v[182:185], v[80:83]
	v_mfma_f32_16x16x32_bf16 v[88:91], v[174:177], v[182:185], v[88:91]
	s_setprio 0
	s_barrier
	s_add_i32 s57, 0, 0x18000
	s_add_i32 s58, 0, 0x1c000
	v_add_u32_e32 v140, s57, v195
	v_add_u32_e32 v152, s58, v195
	ds_read_b128 v[96:99], v140
	ds_read_b128 v[100:103], v140 offset:1024
	ds_read_b128 v[136:139], v140 offset:2048
	ds_read_b128 v[140:143], v140 offset:3072
	ds_read_b128 v[162:165], v152
	ds_read_b128 v[166:169], v152 offset:1024
	ds_read_b128 v[170:173], v152 offset:2048
	ds_read_b128 v[174:177], v152 offset:3072
	s_add_u32 s8, s12, 0xb0000
	s_addc_u32 s9, s13, 0
	s_mov_b32 m0, s40
	v_lshl_add_u64 v[226:227], s[8:9], 0, v[144:145]
	ds_read_b128 v[178:181], v199 offset:32768
	ds_read_b128 v[182:185], v199 offset:33792
	ds_read_b128 v[186:189], v199 offset:34816
	ds_read_b128 v[190:193], v199 offset:35840
	ds_read_b128 v[202:205], v199 offset:36864
	ds_read_b128 v[206:209], v199 offset:37888
	ds_read_b128 v[210:213], v199 offset:38912
	ds_read_b128 v[214:217], v199 offset:39936
	global_load_lds_dwordx4 v[226:227], off
	v_lshl_add_u64 v[226:227], s[8:9], 0, v[148:149]
	s_mov_b32 m0, s41
	s_nop 0
	global_load_lds_dwordx4 v[226:227], off
	s_waitcnt vmcnt(8)
	s_waitcnt lgkmcnt(0)
	s_barrier
	s_setprio 1
	s_waitcnt lgkmcnt(0)
	v_mfma_f32_16x16x32_bf16 v[4:7], v[96:99], v[178:181], v[4:7]
	v_mfma_f32_16x16x32_bf16 v[0:3], v[136:139], v[178:181], v[0:3]
	v_mfma_f32_16x16x32_bf16 v[12:15], v[96:99], v[186:189], v[12:15]
	v_mfma_f32_16x16x32_bf16 v[8:11], v[136:139], v[186:189], v[8:11]
	v_mfma_f32_16x16x32_bf16 v[20:23], v[96:99], v[202:205], v[20:23]
	v_mfma_f32_16x16x32_bf16 v[16:19], v[136:139], v[202:205], v[16:19]
	v_mfma_f32_16x16x32_bf16 v[32:35], v[96:99], v[210:213], v[32:35]
	v_mfma_f32_16x16x32_bf16 v[24:27], v[136:139], v[210:213], v[24:27]
	v_mfma_f32_16x16x32_bf16 v[4:7], v[100:103], v[182:185], v[4:7]
	v_mfma_f32_16x16x32_bf16 v[0:3], v[140:143], v[182:185], v[0:3]
	v_mfma_f32_16x16x32_bf16 v[12:15], v[100:103], v[190:193], v[12:15]
	v_mfma_f32_16x16x32_bf16 v[8:11], v[140:143], v[190:193], v[8:11]
	v_mfma_f32_16x16x32_bf16 v[20:23], v[100:103], v[206:209], v[20:23]
	v_mfma_f32_16x16x32_bf16 v[16:19], v[140:143], v[206:209], v[16:19]
	v_mfma_f32_16x16x32_bf16 v[32:35], v[100:103], v[214:217], v[32:35]
	v_mfma_f32_16x16x32_bf16 v[24:27], v[140:143], v[214:217], v[24:27]
	v_mfma_f32_16x16x32_bf16 v[132:135], v[162:165], v[178:181], v[132:135]
	v_mfma_f32_16x16x32_bf16 v[128:131], v[170:173], v[178:181], v[128:131]
	v_mfma_f32_16x16x32_bf16 v[48:51], v[162:165], v[186:189], v[48:51]
	v_mfma_f32_16x16x32_bf16 v[40:43], v[170:173], v[186:189], v[40:43]
	v_mfma_f32_16x16x32_bf16 v[76:79], v[162:165], v[202:205], v[76:79]
	v_mfma_f32_16x16x32_bf16 v[60:63], v[170:173], v[202:205], v[60:63]
	v_mfma_f32_16x16x32_bf16 v[92:95], v[162:165], v[210:213], v[92:95]
	v_mfma_f32_16x16x32_bf16 v[84:87], v[170:173], v[210:213], v[84:87]
	v_mfma_f32_16x16x32_bf16 v[132:135], v[166:169], v[182:185], v[132:135]
	v_mfma_f32_16x16x32_bf16 v[128:131], v[174:177], v[182:185], v[128:131]
	v_mfma_f32_16x16x32_bf16 v[48:51], v[166:169], v[190:193], v[48:51]
	v_mfma_f32_16x16x32_bf16 v[40:43], v[174:177], v[190:193], v[40:43]
	v_mfma_f32_16x16x32_bf16 v[76:79], v[166:169], v[206:209], v[76:79]
	v_mfma_f32_16x16x32_bf16 v[60:63], v[174:177], v[206:209], v[60:63]
	v_mfma_f32_16x16x32_bf16 v[92:95], v[166:169], v[214:217], v[92:95]
	v_mfma_f32_16x16x32_bf16 v[84:87], v[174:177], v[214:217], v[84:87]
	s_setprio 0
	s_barrier
; #define PG8_STAGE(bufoff, gbase, voff) do { _Pragma("unroll") for (int _i = 0; _i < 2; ++_i) \
;         __builtin_amdgcn_global_load_lds((const unsigned*)((const char*)(gbase) + (voff)[_i]), (LAS unsigned*)(lds + (bufoff) + ldsw + _i * 8192), 16, 0, 0); } while (0)
; #define PG8_LDA(dst, b, h) do { _Pragma("unroll") for (int m = 0; m < 4; ++m) _Pragma("unroll") for (int k = 0; k < 2; ++k) dst[m][k] = *(const LAS bf16x8*)(lds + PG8_SA(b, h) + aoff + m * 2048 + k * 1024); } while (0)
; #define PG8_MMA(ai, bj, At, Bt) do { __builtin_amdgcn_s_setprio(1); _Pragma("unroll") for (int m = 0; m < 4; ++m) _Pragma("unroll") for (int n = 0; n < 2; ++n) _Pragma("unroll") for (int k = 0; k < 2; ++k) \
;         acc[ai][bj][m][n] = __builtin_amdgcn_mfma_f32_16x16x32_bf16(Bt[n][k], At[m][k], acc[ai][bj][m][n], 0, 0, 0); __builtin_amdgcn_s_setprio(0); } while (0)
; #define PG8_WAIT_V(n) asm volatile("s_waitcnt vmcnt(" #n ")" ::: "memory")
; #define PG8_WAIT_L(n) asm volatile("s_waitcnt lgkmcnt(" #n ")" ::: "memory")
; #define PG8_BAR __builtin_amdgcn_s_barrier()
; #define PG8_SCHED __builtin_amdgcn_sched_barrier(0)
; template <int MODE> DI void gemm_phase(LAS unsigned char* lds, const Gemm g, const StaticOrder& S, const Epi& E) {
;     ...
;             PG8_LDA(At, 1, 1); PG8_STAGE(PG8_SB(1, 0), b3, voffB); PG8_STAGE(PG8_SB(1, 1), b3 + hstepB, voffB); PG8_STAGE(PG8_SA(1, 0), a3, voffA);
;             PG8_WAIT_V(8); PG8_WAIT_L(0); PG8_BAR; PG8_MMA(1, 0, At, B0); PG8_MMA(1, 1, At, B1); PG8_BAR; PG8_SCHED;
;         }
;         if (wr == 0) PG8_BAR;
	s_add_i32 s8, s57, s31
	v_lshl_add_u64 v[218:219], v[218:219], 0, s[20:21]
	s_mov_b32 m0, s8
	ds_read_b128 v[178:181], v199 offset:49152
	ds_read_b128 v[182:185], v199 offset:50176
	ds_read_b128 v[186:189], v199 offset:51200
	ds_read_b128 v[190:193], v199 offset:52224
	ds_read_b128 v[202:205], v199 offset:53248
	ds_read_b128 v[206:209], v199 offset:54272
	ds_read_b128 v[210:213], v199 offset:55296
	ds_read_b128 v[214:217], v199 offset:56320
	global_load_lds_dwordx4 v[218:219], off
	s_add_i32 m0, s8, 0x2000
	s_add_u32 s8, s10, 0x2c080
	v_lshl_add_u64 v[218:219], v[220:221], 0, s[20:21]
	s_addc_u32 s9, s11, 0
	s_add_i32 s10, s58, s31
	global_load_lds_dwordx4 v[218:219], off
	v_lshl_add_u64 v[218:219], s[8:9], 0, v[146:147]
	s_mov_b32 m0, s10
	s_nop 0
	global_load_lds_dwordx4 v[218:219], off
	v_lshl_add_u64 v[218:219], s[8:9], 0, v[150:151]
	s_add_i32 m0, s10, 0x2000
	s_nop 0
	global_load_lds_dwordx4 v[218:219], off
	v_lshl_add_u64 v[218:219], v[222:223], 0, s[20:21]
	s_mov_b32 m0, s45
	s_nop 0
	global_load_lds_dwordx4 v[218:219], off
	v_lshl_add_u64 v[218:219], v[224:225], 0, s[20:21]
	s_mov_b32 m0, s46
	s_nop 0
	global_load_lds_dwordx4 v[218:219], off
	s_waitcnt vmcnt(8)
	s_waitcnt lgkmcnt(0)
	s_barrier
	s_setprio 1
	s_waitcnt lgkmcnt(0)
	v_mfma_f32_16x16x32_bf16 v[52:55], v[96:99], v[178:181], v[52:55]
	v_mfma_f32_16x16x32_bf16 v[44:47], v[136:139], v[178:181], v[44:47]
	v_mfma_f32_16x16x32_bf16 v[72:75], v[96:99], v[186:189], v[72:75]
	v_mfma_f32_16x16x32_bf16 v[56:59], v[136:139], v[186:189], v[56:59]
	v_mfma_f32_16x16x32_bf16 v[68:71], v[96:99], v[202:205], v[68:71]
	v_mfma_f32_16x16x32_bf16 v[64:67], v[136:139], v[202:205], v[64:67]
	v_mfma_f32_16x16x32_bf16 v[36:39], v[96:99], v[210:213], v[36:39]
	v_mfma_f32_16x16x32_bf16 v[28:31], v[136:139], v[210:213], v[28:31]
	v_mfma_f32_16x16x32_bf16 v[52:55], v[100:103], v[182:185], v[52:55]
	v_mfma_f32_16x16x32_bf16 v[44:47], v[140:143], v[182:185], v[44:47]
	v_mfma_f32_16x16x32_bf16 v[72:75], v[100:103], v[190:193], v[72:75]
	v_mfma_f32_16x16x32_bf16 v[56:59], v[140:143], v[190:193], v[56:59]
	v_mfma_f32_16x16x32_bf16 v[68:71], v[100:103], v[206:209], v[68:71]
	v_mfma_f32_16x16x32_bf16 v[64:67], v[140:143], v[206:209], v[64:67]
	v_mfma_f32_16x16x32_bf16 v[36:39], v[100:103], v[214:217], v[36:39]
	v_mfma_f32_16x16x32_bf16 v[28:31], v[140:143], v[214:217], v[28:31]
	v_mfma_f32_16x16x32_bf16 v[80:83], v[162:165], v[178:181], v[80:83]
	v_mfma_f32_16x16x32_bf16 v[100:103], v[166:169], v[182:185], v[80:83]
	v_mfma_f32_16x16x32_bf16 v[80:83], v[170:173], v[178:181], v[88:91]
	v_mfma_f32_16x16x32_bf16 v[96:99], v[174:177], v[182:185], v[80:83]
	v_mfma_f32_16x16x32_bf16 v[80:83], v[162:165], v[186:189], v[108:111]
	v_mfma_f32_16x16x32_bf16 v[108:111], v[166:169], v[190:193], v[80:83]
	v_mfma_f32_16x16x32_bf16 v[80:83], v[170:173], v[186:189], v[104:107]
	v_mfma_f32_16x16x32_bf16 v[104:107], v[174:177], v[190:193], v[80:83]
	v_mfma_f32_16x16x32_bf16 v[80:83], v[162:165], v[202:205], v[116:119]
	v_mfma_f32_16x16x32_bf16 v[116:119], v[166:169], v[206:209], v[80:83]
	v_mfma_f32_16x16x32_bf16 v[80:83], v[170:173], v[202:205], v[112:115]
	v_mfma_f32_16x16x32_bf16 v[112:115], v[174:177], v[206:209], v[80:83]
	v_mfma_f32_16x16x32_bf16 v[80:83], v[162:165], v[210:213], v[124:127]
	v_mfma_f32_16x16x32_bf16 v[124:127], v[166:169], v[214:217], v[80:83]
	v_mfma_f32_16x16x32_bf16 v[80:83], v[170:173], v[210:213], v[120:123]
	v_mfma_f32_16x16x32_bf16 v[120:123], v[174:177], v[214:217], v[80:83]
	s_setprio 0
	s_barrier
	s_add_i32 s56, s56, 2
	s_add_u32 s54, s54, 0x100
	s_addc_u32 s55, s55, 0
	s_cmp_gt_u32 s56, 41
	s_mov_b64 s[8:9], s[4:5]
	s_cbranch_scc0 .LBB0_1163
	s_and_b64 vcc, exec, s[22:23]
	s_cbranch_vccz .LBB0_1166
	s_barrier
